# K-loops: vmcnt and lgkmcnt waits merged into one s_waitcnt before each barrier, redundant post-barrier lgkmcnt(0) removed
# baseline (speedup 1.0000x reference)
; #define PG8_STAGE(bufoff, gbase, voff) do { _Pragma("unroll") for (int _i = 0; _i < 2; ++_i) \
;         __builtin_amdgcn_global_load_lds((const unsigned*)((const char*)(gbase) + (voff)[_i]), (LAS unsigned*)(lds + (bufoff) + ldsw + _i * 8192), 16, 0, 0); } while (0)
; #define PG8_LDA(dst, b, h) do { _Pragma("unroll") for (int m = 0; m < 4; ++m) _Pragma("unroll") for (int k = 0; k < 2; ++k) dst[m][k] = *(const LAS bf16x8*)(lds + PG8_SA(b, h) + aoff + m * 2048 + k * 1024); } while (0)
; #define PG8_LDB(dst, b, h) do { _Pragma("unroll") for (int n = 0; n < 2; ++n) _Pragma("unroll") for (int k = 0; k < 2; ++k) dst[n][k] = *(const LAS bf16x8*)(lds + PG8_SB(b, h) + boff + n * 2048 + k * 1024); } while (0)
; #define PG8_MMA(ai, bj, At, Bt) do { __builtin_amdgcn_s_setprio(1); _Pragma("unroll") for (int m = 0; m < 4; ++m) _Pragma("unroll") for (int n = 0; n < 2; ++n) _Pragma("unroll") for (int k = 0; k < 2; ++k) \
;         acc[ai][bj][m][n] = __builtin_amdgcn_mfma_f32_16x16x32_bf16(Bt[n][k], At[m][k], acc[ai][bj][m][n], 0, 0, 0); __builtin_amdgcn_s_setprio(0); } while (0)
; #define PG8_WAIT_V(n) asm volatile("s_waitcnt vmcnt(" #n ")" ::: "memory")
; #define PG8_WAIT_L(n) asm volatile("s_waitcnt lgkmcnt(" #n ")" ::: "memory")
; #define PG8_BAR __builtin_amdgcn_s_barrier()
; #define PG8_SCHED __builtin_amdgcn_sched_barrier(0)
; template <class Epi, bool PERMA = false, bool DUAL = false, bool ALIGN_EPI = true, bool SP2 = true>
; __device__ __forceinline__ void gemm_phase(LAS unsigned char* lds, const Gemm g, const StaticOrder& S, const Epi& E) {
;     ...
;             const bool last = (t == nt - 2);
;             const char* a1 = cA + (size_t)(t + 1) * kstep;
;             const char* a2 = last ? nA : cA + (size_t)(t + 2) * kstep; const char* b2 = last ? nB : cB + (size_t)(t + 2) * kstep;
;             const char* a3 = a2 + kstep; const char* b3 = b2 + kstep;
;             if constexpr (SP2) {
;             PG8_LDB(B0, 0, 0); PG8_LDB(B1, 0, 1); PG8_SCHED; PG8_LDA(At, 0, 0); PG8_STAGE(PG8_SA(1, 1), a1 + hstepA, voffA);
;             PG8_WAIT_V(8); PG8_WAIT_L(0); PG8_BAR; PG8_MMA(0, 0, At, B0); PG8_MMA(0, 1, At, B1); PG8_BAR; PG8_SCHED;
;             PG8_LDA(At, 0, 1); PG8_STAGE(PG8_SB(0, 0), b2, voffB); PG8_STAGE(PG8_SB(0, 1), b2 + hstepB, voffB); PG8_STAGE(PG8_SA(0, 0), a2, voffA);
.LBB0_130:
	s_add_u32 s16, s14, 0xfff80080
	s_addc_u32 s17, s15, -1
	s_add_i32 s38, 0, 0x10000
	s_cmp_eq_u32 s37, 28
	s_cselect_b32 s19, s9, s17
	s_cselect_b32 s18, s33, s16
	s_cselect_b32 s17, s7, s36
	s_cselect_b32 s16, s34, s35
	s_add_i32 s40, 0, 0x14000
	v_add_u32_e32 v156, s38, v141
	v_add_u32_e32 v172, s40, v141
	ds_read_b128 v[144:147], v156
	ds_read_b128 v[148:151], v156 offset:1024
	ds_read_b128 v[152:155], v156 offset:2048
	ds_read_b128 v[156:159], v156 offset:3072
	ds_read_b128 v[160:163], v172
	ds_read_b128 v[164:167], v172 offset:1024
	ds_read_b128 v[168:171], v172 offset:2048
	ds_read_b128 v[172:175], v172 offset:3072
	v_lshl_add_u64 v[222:223], s[14:15], 0, v[136:137]
	s_add_i32 m0, s21, 0xc000
	ds_read_b128 v[176:179], v143
	ds_read_b128 v[180:183], v143 offset:1024
	ds_read_b128 v[184:187], v143 offset:2048
	ds_read_b128 v[188:191], v143 offset:3072
	ds_read_b128 v[206:209], v143 offset:4096
	ds_read_b128 v[210:213], v143 offset:5120
	ds_read_b128 v[214:217], v143 offset:6144
	ds_read_b128 v[218:221], v143 offset:7168
	global_load_lds_dwordx4 v[222:223], off
	v_lshl_add_u64 v[222:223], s[14:15], 0, v[138:139]
	s_add_i32 m0, s21, 0xe000
	s_nop 0
	global_load_lds_dwordx4 v[222:223], off
	s_waitcnt vmcnt(8) lgkmcnt(0)
	s_barrier
	v_mfma_f32_16x16x32_bf16 v[124:127], v[144:147], v[176:179], v[124:127]
	v_mfma_f32_16x16x32_bf16 v[120:123], v[152:155], v[176:179], v[120:123]
	v_mfma_f32_16x16x32_bf16 v[116:119], v[144:147], v[184:187], v[116:119]
	v_mfma_f32_16x16x32_bf16 v[108:111], v[152:155], v[184:187], v[108:111]
	v_mfma_f32_16x16x32_bf16 v[100:103], v[144:147], v[206:209], v[100:103]
	v_mfma_f32_16x16x32_bf16 v[92:95], v[152:155], v[206:209], v[92:95]
	v_mfma_f32_16x16x32_bf16 v[84:87], v[144:147], v[214:217], v[84:87]
	v_mfma_f32_16x16x32_bf16 v[76:79], v[152:155], v[214:217], v[76:79]
	v_mfma_f32_16x16x32_bf16 v[124:127], v[148:151], v[180:183], v[124:127]
	v_mfma_f32_16x16x32_bf16 v[120:123], v[156:159], v[180:183], v[120:123]
	v_mfma_f32_16x16x32_bf16 v[116:119], v[148:151], v[188:191], v[116:119]
	v_mfma_f32_16x16x32_bf16 v[108:111], v[156:159], v[188:191], v[108:111]
	v_mfma_f32_16x16x32_bf16 v[100:103], v[148:151], v[210:213], v[100:103]
	v_mfma_f32_16x16x32_bf16 v[92:95], v[156:159], v[210:213], v[92:95]
	v_mfma_f32_16x16x32_bf16 v[84:87], v[148:151], v[218:221], v[84:87]
	v_mfma_f32_16x16x32_bf16 v[76:79], v[156:159], v[218:221], v[76:79]
	v_mfma_f32_16x16x32_bf16 v[112:115], v[160:163], v[176:179], v[112:115]
	v_mfma_f32_16x16x32_bf16 v[104:107], v[168:171], v[176:179], v[104:107]
	v_mfma_f32_16x16x32_bf16 v[96:99], v[160:163], v[184:187], v[96:99]
	v_mfma_f32_16x16x32_bf16 v[88:91], v[168:171], v[184:187], v[88:91]
	v_mfma_f32_16x16x32_bf16 v[80:83], v[160:163], v[206:209], v[80:83]
	v_mfma_f32_16x16x32_bf16 v[72:75], v[168:171], v[206:209], v[72:75]
	v_mfma_f32_16x16x32_bf16 v[68:71], v[160:163], v[214:217], v[68:71]
	v_mfma_f32_16x16x32_bf16 v[64:67], v[168:171], v[214:217], v[64:67]
	v_mfma_f32_16x16x32_bf16 v[112:115], v[164:167], v[180:183], v[112:115]
	v_mfma_f32_16x16x32_bf16 v[104:107], v[172:175], v[180:183], v[104:107]
	v_mfma_f32_16x16x32_bf16 v[96:99], v[164:167], v[188:191], v[96:99]
	v_mfma_f32_16x16x32_bf16 v[88:91], v[172:175], v[188:191], v[88:91]
	v_mfma_f32_16x16x32_bf16 v[80:83], v[164:167], v[210:213], v[80:83]
	v_mfma_f32_16x16x32_bf16 v[72:75], v[172:175], v[210:213], v[72:75]
	v_mfma_f32_16x16x32_bf16 v[68:71], v[164:167], v[218:221], v[68:71]
	v_mfma_f32_16x16x32_bf16 v[64:67], v[172:175], v[218:221], v[64:67]
	s_barrier
	s_add_i32 s38, s38, s20
	v_lshl_add_u64 v[222:223], s[16:17], 0, v[132:133]
	s_mov_b32 m0, s38
	ds_read_b128 v[176:179], v143 offset:16384
	ds_read_b128 v[180:183], v143 offset:17408
	ds_read_b128 v[184:187], v143 offset:18432
	ds_read_b128 v[188:191], v143 offset:19456
	ds_read_b128 v[206:209], v143 offset:20480
	ds_read_b128 v[210:213], v143 offset:21504
	ds_read_b128 v[214:217], v143 offset:22528
	ds_read_b128 v[218:221], v143 offset:23552
	global_load_lds_dwordx4 v[222:223], off
	s_add_i32 m0, s38, 0x2000
	s_add_u32 s38, s16, 0x80000
	v_lshl_add_u64 v[224:225], s[16:17], 0, v[128:129]
	s_addc_u32 s39, s17, 0
	s_add_i32 s40, s40, s20
	global_load_lds_dwordx4 v[224:225], off
	v_lshl_add_u64 v[226:227], s[38:39], 0, v[132:133]
	s_mov_b32 m0, s40
	v_lshl_add_u64 v[228:229], s[18:19], 0, v[130:131]
	global_load_lds_dwordx4 v[226:227], off
	v_lshl_add_u64 v[226:227], s[38:39], 0, v[128:129]
	s_add_i32 m0, s40, 0x2000
	s_nop 0
	global_load_lds_dwordx4 v[226:227], off
	v_lshl_add_u64 v[226:227], s[18:19], 0, v[134:135]
	s_mov_b32 m0, s21
	s_nop 0
	global_load_lds_dwordx4 v[226:227], off
	s_mov_b32 m0, s22
	s_nop 0
	global_load_lds_dwordx4 v[228:229], off
	s_waitcnt vmcnt(8) lgkmcnt(0)
	s_barrier
; #define PG8_STAGE(bufoff, gbase, voff) do { _Pragma("unroll") for (int _i = 0; _i < 2; ++_i) \
;         __builtin_amdgcn_global_load_lds((const unsigned*)((const char*)(gbase) + (voff)[_i]), (LAS unsigned*)(lds + (bufoff) + ldsw + _i * 8192), 16, 0, 0); } while (0)
; #define PG8_LDA(dst, b, h) do { _Pragma("unroll") for (int m = 0; m < 4; ++m) _Pragma("unroll") for (int k = 0; k < 2; ++k) dst[m][k] = *(const LAS bf16x8*)(lds + PG8_SA(b, h) + aoff + m * 2048 + k * 1024); } while (0)
; #define PG8_LDB(dst, b, h) do { _Pragma("unroll") for (int n = 0; n < 2; ++n) _Pragma("unroll") for (int k = 0; k < 2; ++k) dst[n][k] = *(const LAS bf16x8*)(lds + PG8_SB(b, h) + boff + n * 2048 + k * 1024); } while (0)
; #define PG8_MMA(ai, bj, At, Bt) do { __builtin_amdgcn_s_setprio(1); _Pragma("unroll") for (int m = 0; m < 4; ++m) _Pragma("unroll") for (int n = 0; n < 2; ++n) _Pragma("unroll") for (int k = 0; k < 2; ++k) \
;         acc[ai][bj][m][n] = __builtin_amdgcn_mfma_f32_16x16x32_bf16(Bt[n][k], At[m][k], acc[ai][bj][m][n], 0, 0, 0); __builtin_amdgcn_s_setprio(0); } while (0)
; #define PG8_WAIT_V(n) asm volatile("s_waitcnt vmcnt(" #n ")" ::: "memory")
; #define PG8_WAIT_L(n) asm volatile("s_waitcnt lgkmcnt(" #n ")" ::: "memory")
; #define PG8_BAR __builtin_amdgcn_s_barrier()
; #define PG8_SCHED __builtin_amdgcn_sched_barrier(0)
; template <class Epi, bool PERMA = false, bool DUAL = false, bool ALIGN_EPI = true, bool SP2 = true>
; __device__ __forceinline__ void gemm_phase(LAS unsigned char* lds, const Gemm g, const StaticOrder& S, const Epi& E) {
;     ...
;             PG8_WAIT_V(8); PG8_WAIT_L(0); PG8_BAR; PG8_MMA(1, 0, At, B0); PG8_MMA(1, 1, At, B1); PG8_BAR; PG8_SCHED;
;             PG8_LDB(B0, 1, 0); PG8_LDB(B1, 1, 1); PG8_SCHED; PG8_LDA(At, 1, 0); PG8_STAGE(PG8_SA(0, 1), a2 + hstepA, voffA);
;             PG8_WAIT_V(8); PG8_WAIT_L(0); PG8_BAR; PG8_MMA(0, 0, At, B0); PG8_MMA(0, 1, At, B1); PG8_BAR; PG8_SCHED;
	v_mfma_f32_16x16x32_bf16 v[60:63], v[144:147], v[176:179], v[60:63]
	v_mfma_f32_16x16x32_bf16 v[56:59], v[152:155], v[176:179], v[56:59]
	v_mfma_f32_16x16x32_bf16 v[52:55], v[144:147], v[184:187], v[52:55]
	v_mfma_f32_16x16x32_bf16 v[44:47], v[152:155], v[184:187], v[44:47]
	v_mfma_f32_16x16x32_bf16 v[36:39], v[144:147], v[206:209], v[36:39]
	v_mfma_f32_16x16x32_bf16 v[28:31], v[152:155], v[206:209], v[28:31]
	v_mfma_f32_16x16x32_bf16 v[20:23], v[144:147], v[214:217], v[20:23]
	v_mfma_f32_16x16x32_bf16 v[12:15], v[152:155], v[214:217], v[12:15]
	v_mfma_f32_16x16x32_bf16 v[60:63], v[148:151], v[180:183], v[60:63]
	v_mfma_f32_16x16x32_bf16 v[56:59], v[156:159], v[180:183], v[56:59]
	v_mfma_f32_16x16x32_bf16 v[52:55], v[148:151], v[188:191], v[52:55]
	v_mfma_f32_16x16x32_bf16 v[44:47], v[156:159], v[188:191], v[44:47]
	v_mfma_f32_16x16x32_bf16 v[36:39], v[148:151], v[210:213], v[36:39]
	v_mfma_f32_16x16x32_bf16 v[28:31], v[156:159], v[210:213], v[28:31]
	v_mfma_f32_16x16x32_bf16 v[20:23], v[148:151], v[218:221], v[20:23]
	v_mfma_f32_16x16x32_bf16 v[12:15], v[156:159], v[218:221], v[12:15]
	v_mfma_f32_16x16x32_bf16 v[48:51], v[160:163], v[176:179], v[48:51]
	v_mfma_f32_16x16x32_bf16 v[40:43], v[168:171], v[176:179], v[40:43]
	v_mfma_f32_16x16x32_bf16 v[32:35], v[160:163], v[184:187], v[32:35]
	v_mfma_f32_16x16x32_bf16 v[24:27], v[168:171], v[184:187], v[24:27]
	v_mfma_f32_16x16x32_bf16 v[16:19], v[160:163], v[206:209], v[16:19]
	v_mfma_f32_16x16x32_bf16 v[8:11], v[168:171], v[206:209], v[8:11]
	v_mfma_f32_16x16x32_bf16 v[4:7], v[160:163], v[214:217], v[4:7]
	v_mfma_f32_16x16x32_bf16 v[0:3], v[168:171], v[214:217], v[0:3]
	v_mfma_f32_16x16x32_bf16 v[48:51], v[164:167], v[180:183], v[48:51]
	v_mfma_f32_16x16x32_bf16 v[40:43], v[172:175], v[180:183], v[40:43]
	v_mfma_f32_16x16x32_bf16 v[32:35], v[164:167], v[188:191], v[32:35]
	v_mfma_f32_16x16x32_bf16 v[24:27], v[172:175], v[188:191], v[24:27]
	v_mfma_f32_16x16x32_bf16 v[16:19], v[164:167], v[210:213], v[16:19]
	v_mfma_f32_16x16x32_bf16 v[8:11], v[172:175], v[210:213], v[8:11]
	v_mfma_f32_16x16x32_bf16 v[4:7], v[164:167], v[218:221], v[4:7]
	v_mfma_f32_16x16x32_bf16 v[0:3], v[172:175], v[218:221], v[0:3]
	s_barrier
	s_add_i32 s38, 0, 0x18000
	s_add_i32 s39, 0, 0x1c000
	v_add_u32_e32 v156, s38, v141
	v_add_u32_e32 v172, s39, v141
	ds_read_b128 v[144:147], v156
	ds_read_b128 v[148:151], v156 offset:1024
	ds_read_b128 v[152:155], v156 offset:2048
	ds_read_b128 v[156:159], v156 offset:3072
	ds_read_b128 v[160:163], v172
	ds_read_b128 v[164:167], v172 offset:1024
	ds_read_b128 v[168:171], v172 offset:2048
	ds_read_b128 v[172:175], v172 offset:3072
	s_add_u32 s18, s18, 0x80000
	s_addc_u32 s19, s19, 0
	s_mov_b32 m0, s23
	v_lshl_add_u64 v[238:239], s[18:19], 0, v[134:135]
	ds_read_b128 v[176:179], v143 offset:32768
	ds_read_b128 v[180:183], v143 offset:33792
	ds_read_b128 v[184:187], v143 offset:34816
	ds_read_b128 v[188:191], v143 offset:35840
	ds_read_b128 v[206:209], v143 offset:36864
	ds_read_b128 v[210:213], v143 offset:37888
	ds_read_b128 v[214:217], v143 offset:38912
	ds_read_b128 v[218:221], v143 offset:39936
	global_load_lds_dwordx4 v[238:239], off
	v_lshl_add_u64 v[238:239], s[18:19], 0, v[130:131]
	s_mov_b32 m0, s24
	s_nop 0
	global_load_lds_dwordx4 v[238:239], off
	s_waitcnt vmcnt(8) lgkmcnt(0)
	s_barrier
	v_mfma_f32_16x16x32_bf16 v[124:127], v[144:147], v[176:179], v[124:127]
	v_mfma_f32_16x16x32_bf16 v[120:123], v[152:155], v[176:179], v[120:123]
	v_mfma_f32_16x16x32_bf16 v[116:119], v[144:147], v[184:187], v[116:119]
	v_mfma_f32_16x16x32_bf16 v[108:111], v[152:155], v[184:187], v[108:111]
	v_mfma_f32_16x16x32_bf16 v[100:103], v[144:147], v[206:209], v[100:103]
	v_mfma_f32_16x16x32_bf16 v[92:95], v[152:155], v[206:209], v[92:95]
	v_mfma_f32_16x16x32_bf16 v[84:87], v[144:147], v[214:217], v[84:87]
	v_mfma_f32_16x16x32_bf16 v[76:79], v[152:155], v[214:217], v[76:79]
	v_mfma_f32_16x16x32_bf16 v[124:127], v[148:151], v[180:183], v[124:127]
	v_mfma_f32_16x16x32_bf16 v[120:123], v[156:159], v[180:183], v[120:123]
	v_mfma_f32_16x16x32_bf16 v[116:119], v[148:151], v[188:191], v[116:119]
	v_mfma_f32_16x16x32_bf16 v[108:111], v[156:159], v[188:191], v[108:111]
	v_mfma_f32_16x16x32_bf16 v[100:103], v[148:151], v[210:213], v[100:103]
	v_mfma_f32_16x16x32_bf16 v[92:95], v[156:159], v[210:213], v[92:95]
	v_mfma_f32_16x16x32_bf16 v[84:87], v[148:151], v[218:221], v[84:87]
	v_mfma_f32_16x16x32_bf16 v[76:79], v[156:159], v[218:221], v[76:79]
	v_mfma_f32_16x16x32_bf16 v[112:115], v[160:163], v[176:179], v[112:115]
	v_mfma_f32_16x16x32_bf16 v[104:107], v[168:171], v[176:179], v[104:107]
	v_mfma_f32_16x16x32_bf16 v[96:99], v[160:163], v[184:187], v[96:99]
	v_mfma_f32_16x16x32_bf16 v[88:91], v[168:171], v[184:187], v[88:91]
	v_mfma_f32_16x16x32_bf16 v[80:83], v[160:163], v[206:209], v[80:83]
	v_mfma_f32_16x16x32_bf16 v[72:75], v[168:171], v[206:209], v[72:75]
	v_mfma_f32_16x16x32_bf16 v[68:71], v[160:163], v[214:217], v[68:71]
	v_mfma_f32_16x16x32_bf16 v[64:67], v[168:171], v[214:217], v[64:67]
	v_mfma_f32_16x16x32_bf16 v[112:115], v[164:167], v[180:183], v[112:115]
	v_mfma_f32_16x16x32_bf16 v[104:107], v[172:175], v[180:183], v[104:107]
	v_mfma_f32_16x16x32_bf16 v[96:99], v[164:167], v[188:191], v[96:99]
	v_mfma_f32_16x16x32_bf16 v[88:91], v[172:175], v[188:191], v[88:91]
	v_mfma_f32_16x16x32_bf16 v[80:83], v[164:167], v[210:213], v[80:83]
	v_mfma_f32_16x16x32_bf16 v[72:75], v[172:175], v[210:213], v[72:75]
	v_mfma_f32_16x16x32_bf16 v[68:71], v[164:167], v[218:221], v[68:71]
	v_mfma_f32_16x16x32_bf16 v[64:67], v[172:175], v[218:221], v[64:67]
	s_barrier
; #define PG8_STAGE(bufoff, gbase, voff) do { _Pragma("unroll") for (int _i = 0; _i < 2; ++_i) \
;         __builtin_amdgcn_global_load_lds((const unsigned*)((const char*)(gbase) + (voff)[_i]), (LAS unsigned*)(lds + (bufoff) + ldsw + _i * 8192), 16, 0, 0); } while (0)
; #define PG8_LDA(dst, b, h) do { _Pragma("unroll") for (int m = 0; m < 4; ++m) _Pragma("unroll") for (int k = 0; k < 2; ++k) dst[m][k] = *(const LAS bf16x8*)(lds + PG8_SA(b, h) + aoff + m * 2048 + k * 1024); } while (0)
; #define PG8_MMA(ai, bj, At, Bt) do { __builtin_amdgcn_s_setprio(1); _Pragma("unroll") for (int m = 0; m < 4; ++m) _Pragma("unroll") for (int n = 0; n < 2; ++n) _Pragma("unroll") for (int k = 0; k < 2; ++k) \
;         acc[ai][bj][m][n] = __builtin_amdgcn_mfma_f32_16x16x32_bf16(Bt[n][k], At[m][k], acc[ai][bj][m][n], 0, 0, 0); __builtin_amdgcn_s_setprio(0); } while (0)
; #define PG8_WAIT_V(n) asm volatile("s_waitcnt vmcnt(" #n ")" ::: "memory")
; #define PG8_WAIT_L(n) asm volatile("s_waitcnt lgkmcnt(" #n ")" ::: "memory")
; #define PG8_BAR __builtin_amdgcn_s_barrier()
; #define PG8_SCHED __builtin_amdgcn_sched_barrier(0)
; template <class Epi, bool PERMA = false, bool DUAL = false, bool ALIGN_EPI = true, bool SP2 = true>
; __device__ __forceinline__ void gemm_phase(LAS unsigned char* lds, const Gemm g, const StaticOrder& S, const Epi& E) {
;     ...
;             PG8_LDA(At, 1, 1); PG8_STAGE(PG8_SB(1, 0), b3, voffB); PG8_STAGE(PG8_SB(1, 1), b3 + hstepB, voffB); PG8_STAGE(PG8_SA(1, 0), a3, voffA);
;             PG8_WAIT_V(8); PG8_WAIT_L(0); PG8_BAR; PG8_MMA(1, 0, At, B0); PG8_MMA(1, 1, At, B1); PG8_BAR; PG8_SCHED;
;     ...
;         if constexpr (ALIGN_EPI) { if (wr == 0) PG8_BAR; }
	s_add_i32 s18, s38, s20
	v_lshl_add_u64 v[222:223], v[222:223], 0, s[46:47]
	s_mov_b32 m0, s18
	ds_read_b128 v[176:179], v143 offset:49152
	ds_read_b128 v[180:183], v143 offset:50176
	ds_read_b128 v[184:187], v143 offset:51200
	ds_read_b128 v[188:191], v143 offset:52224
	ds_read_b128 v[206:209], v143 offset:53248
	ds_read_b128 v[210:213], v143 offset:54272
	ds_read_b128 v[214:217], v143 offset:55296
	ds_read_b128 v[218:221], v143 offset:56320
	global_load_lds_dwordx4 v[222:223], off
	s_add_i32 m0, s18, 0x2000
	s_add_u32 s16, s16, 0x80080
	v_lshl_add_u64 v[222:223], v[224:225], 0, s[46:47]
	s_addc_u32 s17, s17, 0
	s_add_i32 s18, s39, s20
	global_load_lds_dwordx4 v[222:223], off
	v_lshl_add_u64 v[222:223], s[16:17], 0, v[132:133]
	s_mov_b32 m0, s18
	s_nop 0
	global_load_lds_dwordx4 v[222:223], off
	v_lshl_add_u64 v[222:223], s[16:17], 0, v[128:129]
	s_add_i32 m0, s18, 0x2000
	s_nop 0
	global_load_lds_dwordx4 v[222:223], off
	v_lshl_add_u64 v[222:223], v[226:227], 0, s[46:47]
	s_mov_b32 m0, s25
	s_nop 0
	global_load_lds_dwordx4 v[222:223], off
	v_lshl_add_u64 v[222:223], v[228:229], 0, s[46:47]
	s_mov_b32 m0, s26
	s_nop 0
	global_load_lds_dwordx4 v[222:223], off
	s_waitcnt vmcnt(8) lgkmcnt(0)
	s_barrier
	v_mfma_f32_16x16x32_bf16 v[60:63], v[144:147], v[176:179], v[60:63]
	v_mfma_f32_16x16x32_bf16 v[56:59], v[152:155], v[176:179], v[56:59]
	v_mfma_f32_16x16x32_bf16 v[52:55], v[144:147], v[184:187], v[52:55]
	v_mfma_f32_16x16x32_bf16 v[44:47], v[152:155], v[184:187], v[44:47]
	v_mfma_f32_16x16x32_bf16 v[36:39], v[144:147], v[206:209], v[36:39]
	v_mfma_f32_16x16x32_bf16 v[28:31], v[152:155], v[206:209], v[28:31]
	v_mfma_f32_16x16x32_bf16 v[20:23], v[144:147], v[214:217], v[20:23]
	v_mfma_f32_16x16x32_bf16 v[12:15], v[152:155], v[214:217], v[12:15]
	v_mfma_f32_16x16x32_bf16 v[60:63], v[148:151], v[180:183], v[60:63]
	v_mfma_f32_16x16x32_bf16 v[56:59], v[156:159], v[180:183], v[56:59]
	v_mfma_f32_16x16x32_bf16 v[52:55], v[148:151], v[188:191], v[52:55]
	v_mfma_f32_16x16x32_bf16 v[44:47], v[156:159], v[188:191], v[44:47]
	v_mfma_f32_16x16x32_bf16 v[36:39], v[148:151], v[210:213], v[36:39]
	v_mfma_f32_16x16x32_bf16 v[28:31], v[156:159], v[210:213], v[28:31]
	v_mfma_f32_16x16x32_bf16 v[20:23], v[148:151], v[218:221], v[20:23]
	v_mfma_f32_16x16x32_bf16 v[12:15], v[156:159], v[218:221], v[12:15]
	v_mfma_f32_16x16x32_bf16 v[48:51], v[160:163], v[176:179], v[48:51]
	v_mfma_f32_16x16x32_bf16 v[40:43], v[168:171], v[176:179], v[40:43]
	v_mfma_f32_16x16x32_bf16 v[32:35], v[160:163], v[184:187], v[32:35]
	v_mfma_f32_16x16x32_bf16 v[24:27], v[168:171], v[184:187], v[24:27]
	v_mfma_f32_16x16x32_bf16 v[16:19], v[160:163], v[206:209], v[16:19]
	v_mfma_f32_16x16x32_bf16 v[8:11], v[168:171], v[206:209], v[8:11]
	v_mfma_f32_16x16x32_bf16 v[4:7], v[160:163], v[214:217], v[4:7]
	v_mfma_f32_16x16x32_bf16 v[0:3], v[168:171], v[214:217], v[0:3]
	v_mfma_f32_16x16x32_bf16 v[48:51], v[164:167], v[180:183], v[48:51]
	v_mfma_f32_16x16x32_bf16 v[40:43], v[172:175], v[180:183], v[40:43]
	v_mfma_f32_16x16x32_bf16 v[32:35], v[164:167], v[188:191], v[32:35]
	v_mfma_f32_16x16x32_bf16 v[24:27], v[172:175], v[188:191], v[24:27]
	v_mfma_f32_16x16x32_bf16 v[16:19], v[164:167], v[210:213], v[16:19]
	v_mfma_f32_16x16x32_bf16 v[8:11], v[172:175], v[210:213], v[8:11]
	v_mfma_f32_16x16x32_bf16 v[4:7], v[164:167], v[218:221], v[4:7]
	v_mfma_f32_16x16x32_bf16 v[0:3], v[172:175], v[218:221], v[0:3]
	s_barrier
	s_add_i32 s37, s37, 2
	s_add_u32 s14, s14, 0x100
	s_addc_u32 s15, s15, 0
	s_add_u32 s35, s35, 0x100
	s_addc_u32 s36, s36, 0
	s_cmp_gt_u32 s37, 29
	s_cbranch_scc0 .LBB0_130
	s_and_b64 vcc, exec, s[4:5]
	s_cbranch_vccz .LBB0_133
	s_barrier

; #define PG8_STAGE(bufoff, gbase, voff) do { _Pragma("unroll") for (int _i = 0; _i < 2; ++_i) \
;         __builtin_amdgcn_global_load_lds((const unsigned*)((const char*)(gbase) + (voff)[_i]), (LAS unsigned*)(lds + (bufoff) + ldsw + _i * 8192), 16, 0, 0); } while (0)
; #define PG8_LDA(dst, b, h) do { _Pragma("unroll") for (int m = 0; m < 4; ++m) _Pragma("unroll") for (int k = 0; k < 2; ++k) dst[m][k] = *(const LAS bf16x8*)(lds + PG8_SA(b, h) + aoff + m * 2048 + k * 1024); } while (0)
; #define PG8_LDB(dst, b, h) do { _Pragma("unroll") for (int n = 0; n < 2; ++n) _Pragma("unroll") for (int k = 0; k < 2; ++k) dst[n][k] = *(const LAS bf16x8*)(lds + PG8_SB(b, h) + boff + n * 2048 + k * 1024); } while (0)
; #define PG8_MMA(ai, bj, At, Bt) do { __builtin_amdgcn_s_setprio(1); _Pragma("unroll") for (int m = 0; m < 4; ++m) _Pragma("unroll") for (int n = 0; n < 2; ++n) _Pragma("unroll") for (int k = 0; k < 2; ++k) \
;         acc[ai][bj][m][n] = __builtin_amdgcn_mfma_f32_16x16x32_bf16(Bt[n][k], At[m][k], acc[ai][bj][m][n], 0, 0, 0); __builtin_amdgcn_s_setprio(0); } while (0)
; #define PG8_WAIT_V(n) asm volatile("s_waitcnt vmcnt(" #n ")" ::: "memory")
; #define PG8_WAIT_L(n) asm volatile("s_waitcnt lgkmcnt(" #n ")" ::: "memory")
; #define PG8_BAR __builtin_amdgcn_s_barrier()
; #define PG8_SCHED __builtin_amdgcn_sched_barrier(0)
; template <class Epi, bool PERMA = false, bool DUAL = false, bool ALIGN_EPI = true, bool SP2 = true>
; __device__ __forceinline__ void gemm_phase(LAS unsigned char* lds, const Gemm g, const StaticOrder& S, const Epi& E) {
;     ...
;             const bool last = (t == nt - 2);
;             const char* a1 = cA + (size_t)(t + 1) * kstep;
;             const char* a2 = last ? nA : cA + (size_t)(t + 2) * kstep; const char* b2 = last ? nB : cB + (size_t)(t + 2) * kstep;
;             const char* a3 = a2 + kstep; const char* b3 = b2 + kstep;
;             if constexpr (SP2) {
;             PG8_LDB(B0, 0, 0); PG8_LDB(B1, 0, 1); PG8_SCHED; PG8_LDA(At, 0, 0); PG8_STAGE(PG8_SA(1, 1), a1 + hstepA, voffA);
;             PG8_WAIT_V(8); PG8_WAIT_L(0); PG8_BAR; PG8_MMA(0, 0, At, B0); PG8_MMA(0, 1, At, B1); PG8_BAR; PG8_SCHED;
;             PG8_LDA(At, 0, 1); PG8_STAGE(PG8_SB(0, 0), b2, voffB); PG8_STAGE(PG8_SB(0, 1), b2 + hstepB, voffB); PG8_STAGE(PG8_SA(0, 0), a2, voffA);
.LBB0_329:
	s_add_u32 s0, s12, 0x100
	s_addc_u32 s1, s13, 0
	s_add_i32 s38, 0, 0x10000
	s_cmp_eq_u32 s37, 4
	s_cselect_b32 s17, s9, s1
	s_cselect_b32 s16, s8, s0
	s_cselect_b32 s15, s7, s36
	s_cselect_b32 s14, s34, s35
	s_add_i32 s39, 0, 0x14000
	v_add_u32_e32 v140, s38, v193
	v_add_u32_e32 v156, s39, v193
	ds_read_b128 v[128:131], v140
	ds_read_b128 v[132:135], v140 offset:1024
	ds_read_b128 v[136:139], v140 offset:2048
	ds_read_b128 v[140:143], v140 offset:3072
	ds_read_b128 v[144:147], v156
	ds_read_b128 v[148:151], v156 offset:1024
	ds_read_b128 v[152:155], v156 offset:2048
	ds_read_b128 v[156:159], v156 offset:3072
	v_lshl_add_u64 v[220:221], s[12:13], 0, v[216:217]
	s_add_i32 m0, s19, 0xc000
	ds_read_b128 v[160:163], v238
	ds_read_b128 v[164:167], v238 offset:1024
	ds_read_b128 v[168:171], v238 offset:2048
	ds_read_b128 v[172:175], v238 offset:3072
	ds_read_b128 v[176:179], v238 offset:4096
	ds_read_b128 v[180:183], v238 offset:5120
	ds_read_b128 v[184:187], v238 offset:6144
	ds_read_b128 v[188:191], v238 offset:7168
	global_load_lds_dwordx4 v[220:221], off
	v_lshl_add_u64 v[220:221], s[12:13], 0, v[218:219]
	s_add_i32 m0, s19, 0xe000
	s_nop 0
	global_load_lds_dwordx4 v[220:221], off
	s_waitcnt vmcnt(8) lgkmcnt(0)
	s_barrier
	v_mfma_f32_16x16x32_bf16 v[124:127], v[128:131], v[160:163], v[124:127]
	v_mfma_f32_16x16x32_bf16 v[120:123], v[136:139], v[160:163], v[120:123]
	v_mfma_f32_16x16x32_bf16 v[108:111], v[128:131], v[168:171], v[108:111]
	v_mfma_f32_16x16x32_bf16 v[104:107], v[136:139], v[168:171], v[104:107]
	v_mfma_f32_16x16x32_bf16 v[92:95], v[128:131], v[176:179], v[92:95]
	v_mfma_f32_16x16x32_bf16 v[88:91], v[136:139], v[176:179], v[88:91]
	v_mfma_f32_16x16x32_bf16 v[76:79], v[128:131], v[184:187], v[76:79]
	v_mfma_f32_16x16x32_bf16 v[72:75], v[136:139], v[184:187], v[72:75]
	v_mfma_f32_16x16x32_bf16 v[124:127], v[132:135], v[164:167], v[124:127]
	v_mfma_f32_16x16x32_bf16 v[120:123], v[140:143], v[164:167], v[120:123]
	v_mfma_f32_16x16x32_bf16 v[108:111], v[132:135], v[172:175], v[108:111]
	v_mfma_f32_16x16x32_bf16 v[104:107], v[140:143], v[172:175], v[104:107]
	v_mfma_f32_16x16x32_bf16 v[92:95], v[132:135], v[180:183], v[92:95]
	v_mfma_f32_16x16x32_bf16 v[88:91], v[140:143], v[180:183], v[88:91]
	v_mfma_f32_16x16x32_bf16 v[76:79], v[132:135], v[188:191], v[76:79]
	v_mfma_f32_16x16x32_bf16 v[72:75], v[140:143], v[188:191], v[72:75]
	v_mfma_f32_16x16x32_bf16 v[116:119], v[144:147], v[160:163], v[116:119]
	v_mfma_f32_16x16x32_bf16 v[112:115], v[152:155], v[160:163], v[112:115]
	v_mfma_f32_16x16x32_bf16 v[100:103], v[144:147], v[168:171], v[100:103]
	v_mfma_f32_16x16x32_bf16 v[96:99], v[152:155], v[168:171], v[96:99]
	v_mfma_f32_16x16x32_bf16 v[84:87], v[144:147], v[176:179], v[84:87]
	v_mfma_f32_16x16x32_bf16 v[80:83], v[152:155], v[176:179], v[80:83]
	v_mfma_f32_16x16x32_bf16 v[68:71], v[144:147], v[184:187], v[68:71]
	v_mfma_f32_16x16x32_bf16 v[64:67], v[152:155], v[184:187], v[64:67]
	v_mfma_f32_16x16x32_bf16 v[116:119], v[148:151], v[164:167], v[116:119]
	v_mfma_f32_16x16x32_bf16 v[112:115], v[156:159], v[164:167], v[112:115]
	v_mfma_f32_16x16x32_bf16 v[100:103], v[148:151], v[172:175], v[100:103]
	v_mfma_f32_16x16x32_bf16 v[96:99], v[156:159], v[172:175], v[96:99]
	v_mfma_f32_16x16x32_bf16 v[84:87], v[148:151], v[180:183], v[84:87]
	v_mfma_f32_16x16x32_bf16 v[80:83], v[156:159], v[180:183], v[80:83]
	v_mfma_f32_16x16x32_bf16 v[68:71], v[148:151], v[188:191], v[68:71]
	v_mfma_f32_16x16x32_bf16 v[64:67], v[156:159], v[188:191], v[64:67]
	s_barrier
	s_add_i32 s12, s38, s18
	v_lshl_add_u64 v[220:221], s[14:15], 0, v[210:211]
	s_mov_b32 m0, s12
	ds_read_b128 v[160:163], v238 offset:16384
	ds_read_b128 v[164:167], v238 offset:17408
	ds_read_b128 v[168:171], v238 offset:18432
	ds_read_b128 v[172:175], v238 offset:19456
	ds_read_b128 v[176:179], v238 offset:20480
	ds_read_b128 v[180:183], v238 offset:21504
	ds_read_b128 v[184:187], v238 offset:22528
	ds_read_b128 v[188:191], v238 offset:23552
	global_load_lds_dwordx4 v[220:221], off
	s_add_i32 m0, s12, 0x2000
	s_add_u32 s12, s14, 0x20000
	v_lshl_add_u64 v[222:223], s[14:15], 0, v[206:207]
	s_addc_u32 s13, s15, 0
	s_add_i32 s38, s39, s18
	global_load_lds_dwordx4 v[222:223], off
	v_lshl_add_u64 v[224:225], s[12:13], 0, v[210:211]
	s_mov_b32 m0, s38
	v_lshl_add_u64 v[226:227], s[16:17], 0, v[208:209]
	global_load_lds_dwordx4 v[224:225], off
	v_lshl_add_u64 v[224:225], s[12:13], 0, v[206:207]
	s_add_i32 m0, s38, 0x2000
	s_nop 0
	global_load_lds_dwordx4 v[224:225], off
	v_lshl_add_u64 v[224:225], s[16:17], 0, v[212:213]
	s_mov_b32 m0, s19
	s_nop 0
	global_load_lds_dwordx4 v[224:225], off
	s_mov_b32 m0, s20
	s_nop 0
	global_load_lds_dwordx4 v[226:227], off
	s_waitcnt vmcnt(8) lgkmcnt(0)
	s_barrier
; #define PG8_STAGE(bufoff, gbase, voff) do { _Pragma("unroll") for (int _i = 0; _i < 2; ++_i) \
;         __builtin_amdgcn_global_load_lds((const unsigned*)((const char*)(gbase) + (voff)[_i]), (LAS unsigned*)(lds + (bufoff) + ldsw + _i * 8192), 16, 0, 0); } while (0)
; #define PG8_LDA(dst, b, h) do { _Pragma("unroll") for (int m = 0; m < 4; ++m) _Pragma("unroll") for (int k = 0; k < 2; ++k) dst[m][k] = *(const LAS bf16x8*)(lds + PG8_SA(b, h) + aoff + m * 2048 + k * 1024); } while (0)
; #define PG8_LDB(dst, b, h) do { _Pragma("unroll") for (int n = 0; n < 2; ++n) _Pragma("unroll") for (int k = 0; k < 2; ++k) dst[n][k] = *(const LAS bf16x8*)(lds + PG8_SB(b, h) + boff + n * 2048 + k * 1024); } while (0)
; #define PG8_MMA(ai, bj, At, Bt) do { __builtin_amdgcn_s_setprio(1); _Pragma("unroll") for (int m = 0; m < 4; ++m) _Pragma("unroll") for (int n = 0; n < 2; ++n) _Pragma("unroll") for (int k = 0; k < 2; ++k) \
;         acc[ai][bj][m][n] = __builtin_amdgcn_mfma_f32_16x16x32_bf16(Bt[n][k], At[m][k], acc[ai][bj][m][n], 0, 0, 0); __builtin_amdgcn_s_setprio(0); } while (0)
; #define PG8_WAIT_V(n) asm volatile("s_waitcnt vmcnt(" #n ")" ::: "memory")
; #define PG8_WAIT_L(n) asm volatile("s_waitcnt lgkmcnt(" #n ")" ::: "memory")
; #define PG8_BAR __builtin_amdgcn_s_barrier()
; #define PG8_SCHED __builtin_amdgcn_sched_barrier(0)
; template <class Epi, bool PERMA = false, bool DUAL = false, bool ALIGN_EPI = true, bool SP2 = true>
; __device__ __forceinline__ void gemm_phase(LAS unsigned char* lds, const Gemm g, const StaticOrder& S, const Epi& E) {
;     ...
;             PG8_WAIT_V(8); PG8_WAIT_L(0); PG8_BAR; PG8_MMA(1, 0, At, B0); PG8_MMA(1, 1, At, B1); PG8_BAR; PG8_SCHED;
;             PG8_LDB(B0, 1, 0); PG8_LDB(B1, 1, 1); PG8_SCHED; PG8_LDA(At, 1, 0); PG8_STAGE(PG8_SA(0, 1), a2 + hstepA, voffA);
;             PG8_WAIT_V(8); PG8_WAIT_L(0); PG8_BAR; PG8_MMA(0, 0, At, B0); PG8_MMA(0, 1, At, B1); PG8_BAR; PG8_SCHED;
	v_mfma_f32_16x16x32_bf16 v[60:63], v[128:131], v[160:163], v[60:63]
	v_mfma_f32_16x16x32_bf16 v[56:59], v[136:139], v[160:163], v[56:59]
	v_mfma_f32_16x16x32_bf16 v[44:47], v[128:131], v[168:171], v[44:47]
	v_mfma_f32_16x16x32_bf16 v[40:43], v[136:139], v[168:171], v[40:43]
	v_mfma_f32_16x16x32_bf16 v[28:31], v[128:131], v[176:179], v[28:31]
	v_mfma_f32_16x16x32_bf16 v[24:27], v[136:139], v[176:179], v[24:27]
	v_mfma_f32_16x16x32_bf16 v[12:15], v[128:131], v[184:187], v[12:15]
	v_mfma_f32_16x16x32_bf16 v[8:11], v[136:139], v[184:187], v[8:11]
	v_mfma_f32_16x16x32_bf16 v[60:63], v[132:135], v[164:167], v[60:63]
	v_mfma_f32_16x16x32_bf16 v[56:59], v[140:143], v[164:167], v[56:59]
	v_mfma_f32_16x16x32_bf16 v[44:47], v[132:135], v[172:175], v[44:47]
	v_mfma_f32_16x16x32_bf16 v[40:43], v[140:143], v[172:175], v[40:43]
	v_mfma_f32_16x16x32_bf16 v[28:31], v[132:135], v[180:183], v[28:31]
	v_mfma_f32_16x16x32_bf16 v[24:27], v[140:143], v[180:183], v[24:27]
	v_mfma_f32_16x16x32_bf16 v[12:15], v[132:135], v[188:191], v[12:15]
	v_mfma_f32_16x16x32_bf16 v[8:11], v[140:143], v[188:191], v[8:11]
	v_mfma_f32_16x16x32_bf16 v[52:55], v[144:147], v[160:163], v[52:55]
	v_mfma_f32_16x16x32_bf16 v[48:51], v[152:155], v[160:163], v[48:51]
	v_mfma_f32_16x16x32_bf16 v[36:39], v[144:147], v[168:171], v[36:39]
	v_mfma_f32_16x16x32_bf16 v[32:35], v[152:155], v[168:171], v[32:35]
	v_mfma_f32_16x16x32_bf16 v[20:23], v[144:147], v[176:179], v[20:23]
	v_mfma_f32_16x16x32_bf16 v[16:19], v[152:155], v[176:179], v[16:19]
	v_mfma_f32_16x16x32_bf16 v[4:7], v[144:147], v[184:187], v[4:7]
	v_mfma_f32_16x16x32_bf16 v[0:3], v[152:155], v[184:187], v[0:3]
	v_mfma_f32_16x16x32_bf16 v[52:55], v[148:151], v[164:167], v[52:55]
	v_mfma_f32_16x16x32_bf16 v[48:51], v[156:159], v[164:167], v[48:51]
	v_mfma_f32_16x16x32_bf16 v[36:39], v[148:151], v[172:175], v[36:39]
	v_mfma_f32_16x16x32_bf16 v[32:35], v[156:159], v[172:175], v[32:35]
	v_mfma_f32_16x16x32_bf16 v[20:23], v[148:151], v[180:183], v[20:23]
	v_mfma_f32_16x16x32_bf16 v[16:19], v[156:159], v[180:183], v[16:19]
	v_mfma_f32_16x16x32_bf16 v[4:7], v[148:151], v[188:191], v[4:7]
	v_mfma_f32_16x16x32_bf16 v[0:3], v[156:159], v[188:191], v[0:3]
	s_barrier
	s_add_i32 s38, 0, 0x18000
	s_add_i32 s39, 0, 0x1c000
	v_add_u32_e32 v140, s38, v193
	v_add_u32_e32 v156, s39, v193
	ds_read_b128 v[128:131], v140
	ds_read_b128 v[132:135], v140 offset:1024
	ds_read_b128 v[136:139], v140 offset:2048
	ds_read_b128 v[140:143], v140 offset:3072
	ds_read_b128 v[144:147], v156
	ds_read_b128 v[148:151], v156 offset:1024
	ds_read_b128 v[152:155], v156 offset:2048
	ds_read_b128 v[156:159], v156 offset:3072
	s_add_u32 s12, s16, 0x180000
	s_addc_u32 s13, s17, 0
	s_mov_b32 m0, s21
	v_lshl_add_u64 v[228:229], s[12:13], 0, v[212:213]
	ds_read_b128 v[160:163], v238 offset:32768
	ds_read_b128 v[164:167], v238 offset:33792
	ds_read_b128 v[168:171], v238 offset:34816
	ds_read_b128 v[172:175], v238 offset:35840
	ds_read_b128 v[176:179], v238 offset:36864
	ds_read_b128 v[180:183], v238 offset:37888
	ds_read_b128 v[184:187], v238 offset:38912
	ds_read_b128 v[188:191], v238 offset:39936
	global_load_lds_dwordx4 v[228:229], off
	v_lshl_add_u64 v[228:229], s[12:13], 0, v[208:209]
	s_mov_b32 m0, s22
	s_nop 0
	global_load_lds_dwordx4 v[228:229], off
	s_waitcnt vmcnt(8) lgkmcnt(0)
	s_barrier
	v_mfma_f32_16x16x32_bf16 v[124:127], v[128:131], v[160:163], v[124:127]
	v_mfma_f32_16x16x32_bf16 v[120:123], v[136:139], v[160:163], v[120:123]
	v_mfma_f32_16x16x32_bf16 v[108:111], v[128:131], v[168:171], v[108:111]
	v_mfma_f32_16x16x32_bf16 v[104:107], v[136:139], v[168:171], v[104:107]
	v_mfma_f32_16x16x32_bf16 v[92:95], v[128:131], v[176:179], v[92:95]
	v_mfma_f32_16x16x32_bf16 v[88:91], v[136:139], v[176:179], v[88:91]
	v_mfma_f32_16x16x32_bf16 v[76:79], v[128:131], v[184:187], v[76:79]
	v_mfma_f32_16x16x32_bf16 v[72:75], v[136:139], v[184:187], v[72:75]
	v_mfma_f32_16x16x32_bf16 v[124:127], v[132:135], v[164:167], v[124:127]
	v_mfma_f32_16x16x32_bf16 v[120:123], v[140:143], v[164:167], v[120:123]
	v_mfma_f32_16x16x32_bf16 v[108:111], v[132:135], v[172:175], v[108:111]
	v_mfma_f32_16x16x32_bf16 v[104:107], v[140:143], v[172:175], v[104:107]
	v_mfma_f32_16x16x32_bf16 v[92:95], v[132:135], v[180:183], v[92:95]
	v_mfma_f32_16x16x32_bf16 v[88:91], v[140:143], v[180:183], v[88:91]
	v_mfma_f32_16x16x32_bf16 v[76:79], v[132:135], v[188:191], v[76:79]
	v_mfma_f32_16x16x32_bf16 v[72:75], v[140:143], v[188:191], v[72:75]
	v_mfma_f32_16x16x32_bf16 v[116:119], v[144:147], v[160:163], v[116:119]
	v_mfma_f32_16x16x32_bf16 v[112:115], v[152:155], v[160:163], v[112:115]
	v_mfma_f32_16x16x32_bf16 v[100:103], v[144:147], v[168:171], v[100:103]
	v_mfma_f32_16x16x32_bf16 v[96:99], v[152:155], v[168:171], v[96:99]
	v_mfma_f32_16x16x32_bf16 v[84:87], v[144:147], v[176:179], v[84:87]
	v_mfma_f32_16x16x32_bf16 v[80:83], v[152:155], v[176:179], v[80:83]
	v_mfma_f32_16x16x32_bf16 v[68:71], v[144:147], v[184:187], v[68:71]
	v_mfma_f32_16x16x32_bf16 v[64:67], v[152:155], v[184:187], v[64:67]
	v_mfma_f32_16x16x32_bf16 v[116:119], v[148:151], v[164:167], v[116:119]
	v_mfma_f32_16x16x32_bf16 v[112:115], v[156:159], v[164:167], v[112:115]
	v_mfma_f32_16x16x32_bf16 v[100:103], v[148:151], v[172:175], v[100:103]
	v_mfma_f32_16x16x32_bf16 v[96:99], v[156:159], v[172:175], v[96:99]
	v_mfma_f32_16x16x32_bf16 v[84:87], v[148:151], v[180:183], v[84:87]
	v_mfma_f32_16x16x32_bf16 v[80:83], v[156:159], v[180:183], v[80:83]
	v_mfma_f32_16x16x32_bf16 v[68:71], v[148:151], v[188:191], v[68:71]
	v_mfma_f32_16x16x32_bf16 v[64:67], v[156:159], v[188:191], v[64:67]
	s_barrier
; #define PG8_STAGE(bufoff, gbase, voff) do { _Pragma("unroll") for (int _i = 0; _i < 2; ++_i) \
;         __builtin_amdgcn_global_load_lds((const unsigned*)((const char*)(gbase) + (voff)[_i]), (LAS unsigned*)(lds + (bufoff) + ldsw + _i * 8192), 16, 0, 0); } while (0)
; #define PG8_LDA(dst, b, h) do { _Pragma("unroll") for (int m = 0; m < 4; ++m) _Pragma("unroll") for (int k = 0; k < 2; ++k) dst[m][k] = *(const LAS bf16x8*)(lds + PG8_SA(b, h) + aoff + m * 2048 + k * 1024); } while (0)
; #define PG8_MMA(ai, bj, At, Bt) do { __builtin_amdgcn_s_setprio(1); _Pragma("unroll") for (int m = 0; m < 4; ++m) _Pragma("unroll") for (int n = 0; n < 2; ++n) _Pragma("unroll") for (int k = 0; k < 2; ++k) \
;         acc[ai][bj][m][n] = __builtin_amdgcn_mfma_f32_16x16x32_bf16(Bt[n][k], At[m][k], acc[ai][bj][m][n], 0, 0, 0); __builtin_amdgcn_s_setprio(0); } while (0)
; #define PG8_WAIT_V(n) asm volatile("s_waitcnt vmcnt(" #n ")" ::: "memory")
; #define PG8_WAIT_L(n) asm volatile("s_waitcnt lgkmcnt(" #n ")" ::: "memory")
; #define PG8_BAR __builtin_amdgcn_s_barrier()
; #define PG8_SCHED __builtin_amdgcn_sched_barrier(0)
; template <class Epi, bool PERMA = false, bool DUAL = false, bool ALIGN_EPI = true, bool SP2 = true>
; __device__ __forceinline__ void gemm_phase(LAS unsigned char* lds, const Gemm g, const StaticOrder& S, const Epi& E) {
;     ...
;             PG8_LDA(At, 1, 1); PG8_STAGE(PG8_SB(1, 0), b3, voffB); PG8_STAGE(PG8_SB(1, 1), b3 + hstepB, voffB); PG8_STAGE(PG8_SA(1, 0), a3, voffA);
;             PG8_WAIT_V(8); PG8_WAIT_L(0); PG8_BAR; PG8_MMA(1, 0, At, B0); PG8_MMA(1, 1, At, B1); PG8_BAR; PG8_SCHED;
;     ...
;         if constexpr (ALIGN_EPI) { if (wr == 0) PG8_BAR; }
	s_add_i32 s12, s38, s18
	v_lshl_add_u64 v[220:221], v[220:221], 0, s[46:47]
	s_mov_b32 m0, s12
	ds_read_b128 v[160:163], v238 offset:49152
	ds_read_b128 v[164:167], v238 offset:50176
	ds_read_b128 v[168:171], v238 offset:51200
	ds_read_b128 v[172:175], v238 offset:52224
	ds_read_b128 v[176:179], v238 offset:53248
	ds_read_b128 v[180:183], v238 offset:54272
	ds_read_b128 v[184:187], v238 offset:55296
	ds_read_b128 v[188:191], v238 offset:56320
	global_load_lds_dwordx4 v[220:221], off
	s_add_i32 m0, s12, 0x2000
	s_add_u32 s12, s14, 0x20080
	v_lshl_add_u64 v[220:221], v[222:223], 0, s[46:47]
	s_addc_u32 s13, s15, 0
	s_add_i32 s14, s39, s18
	global_load_lds_dwordx4 v[220:221], off
	v_lshl_add_u64 v[220:221], s[12:13], 0, v[210:211]
	s_mov_b32 m0, s14
	s_nop 0
	global_load_lds_dwordx4 v[220:221], off
	v_lshl_add_u64 v[220:221], s[12:13], 0, v[206:207]
	s_add_i32 m0, s14, 0x2000
	s_nop 0
	global_load_lds_dwordx4 v[220:221], off
	v_lshl_add_u64 v[220:221], v[224:225], 0, s[46:47]
	s_mov_b32 m0, s25
	s_nop 0
	global_load_lds_dwordx4 v[220:221], off
	v_lshl_add_u64 v[220:221], v[226:227], 0, s[46:47]
	s_mov_b32 m0, s26
	s_nop 0
	global_load_lds_dwordx4 v[220:221], off
	s_waitcnt vmcnt(8) lgkmcnt(0)
	s_barrier
	v_mfma_f32_16x16x32_bf16 v[60:63], v[128:131], v[160:163], v[60:63]
	v_mfma_f32_16x16x32_bf16 v[56:59], v[136:139], v[160:163], v[56:59]
	v_mfma_f32_16x16x32_bf16 v[44:47], v[128:131], v[168:171], v[44:47]
	v_mfma_f32_16x16x32_bf16 v[40:43], v[136:139], v[168:171], v[40:43]
	v_mfma_f32_16x16x32_bf16 v[28:31], v[128:131], v[176:179], v[28:31]
	v_mfma_f32_16x16x32_bf16 v[24:27], v[136:139], v[176:179], v[24:27]
	v_mfma_f32_16x16x32_bf16 v[12:15], v[128:131], v[184:187], v[12:15]
	v_mfma_f32_16x16x32_bf16 v[8:11], v[136:139], v[184:187], v[8:11]
	v_mfma_f32_16x16x32_bf16 v[60:63], v[132:135], v[164:167], v[60:63]
	v_mfma_f32_16x16x32_bf16 v[56:59], v[140:143], v[164:167], v[56:59]
	v_mfma_f32_16x16x32_bf16 v[44:47], v[132:135], v[172:175], v[44:47]
	v_mfma_f32_16x16x32_bf16 v[40:43], v[140:143], v[172:175], v[40:43]
	v_mfma_f32_16x16x32_bf16 v[28:31], v[132:135], v[180:183], v[28:31]
	v_mfma_f32_16x16x32_bf16 v[24:27], v[140:143], v[180:183], v[24:27]
	v_mfma_f32_16x16x32_bf16 v[12:15], v[132:135], v[188:191], v[12:15]
	v_mfma_f32_16x16x32_bf16 v[8:11], v[140:143], v[188:191], v[8:11]
	v_mfma_f32_16x16x32_bf16 v[52:55], v[144:147], v[160:163], v[52:55]
	v_mfma_f32_16x16x32_bf16 v[48:51], v[152:155], v[160:163], v[48:51]
	v_mfma_f32_16x16x32_bf16 v[36:39], v[144:147], v[168:171], v[36:39]
	v_mfma_f32_16x16x32_bf16 v[32:35], v[152:155], v[168:171], v[32:35]
	v_mfma_f32_16x16x32_bf16 v[20:23], v[144:147], v[176:179], v[20:23]
	v_mfma_f32_16x16x32_bf16 v[16:19], v[152:155], v[176:179], v[16:19]
	v_mfma_f32_16x16x32_bf16 v[4:7], v[144:147], v[184:187], v[4:7]
	v_mfma_f32_16x16x32_bf16 v[0:3], v[152:155], v[184:187], v[0:3]
	v_mfma_f32_16x16x32_bf16 v[52:55], v[148:151], v[164:167], v[52:55]
	v_mfma_f32_16x16x32_bf16 v[48:51], v[156:159], v[164:167], v[48:51]
	v_mfma_f32_16x16x32_bf16 v[36:39], v[148:151], v[172:175], v[36:39]
	v_mfma_f32_16x16x32_bf16 v[32:35], v[156:159], v[172:175], v[32:35]
	v_mfma_f32_16x16x32_bf16 v[20:23], v[148:151], v[180:183], v[20:23]
	v_mfma_f32_16x16x32_bf16 v[16:19], v[156:159], v[180:183], v[16:19]
	v_mfma_f32_16x16x32_bf16 v[4:7], v[148:151], v[188:191], v[4:7]
	v_mfma_f32_16x16x32_bf16 v[0:3], v[156:159], v[188:191], v[0:3]
	s_barrier
	s_add_i32 s37, s37, 2
	s_add_u32 s35, s35, 0x100
	s_addc_u32 s36, s36, 0
	s_cmp_gt_u32 s37, 5
	s_mov_b64 s[12:13], s[0:1]
	s_cbranch_scc0 .LBB0_329
	s_and_b64 vcc, exec, s[4:5]
	s_cbranch_vccz .LBB0_332
	s_barrier

; #define PG8_STAGE(bufoff, gbase, voff) do { _Pragma("unroll") for (int _i = 0; _i < 2; ++_i) \
;         __builtin_amdgcn_global_load_lds((const unsigned*)((const char*)(gbase) + (voff)[_i]), (LAS unsigned*)(lds + (bufoff) + ldsw + _i * 8192), 16, 0, 0); } while (0)
; #define PG8_LDA(dst, b, h) do { _Pragma("unroll") for (int m = 0; m < 4; ++m) _Pragma("unroll") for (int k = 0; k < 2; ++k) dst[m][k] = *(const LAS bf16x8*)(lds + PG8_SA(b, h) + aoff + m * 2048 + k * 1024); } while (0)
; #define PG8_LDB(dst, b, h) do { _Pragma("unroll") for (int n = 0; n < 2; ++n) _Pragma("unroll") for (int k = 0; k < 2; ++k) dst[n][k] = *(const LAS bf16x8*)(lds + PG8_SB(b, h) + boff + n * 2048 + k * 1024); } while (0)
; #define PG8_MMA(ai, bj, At, Bt) do { __builtin_amdgcn_s_setprio(1); _Pragma("unroll") for (int m = 0; m < 4; ++m) _Pragma("unroll") for (int n = 0; n < 2; ++n) _Pragma("unroll") for (int k = 0; k < 2; ++k) \
;         acc[ai][bj][m][n] = __builtin_amdgcn_mfma_f32_16x16x32_bf16(Bt[n][k], At[m][k], acc[ai][bj][m][n], 0, 0, 0); __builtin_amdgcn_s_setprio(0); } while (0)
; #define PG8_WAIT_V(n) asm volatile("s_waitcnt vmcnt(" #n ")" ::: "memory")
; #define PG8_WAIT_L(n) asm volatile("s_waitcnt lgkmcnt(" #n ")" ::: "memory")
; #define PG8_BAR __builtin_amdgcn_s_barrier()
; #define PG8_SCHED __builtin_amdgcn_sched_barrier(0)
; template <class Epi, bool PERMA = false, bool DUAL = false, bool ALIGN_EPI = true, bool SP2 = true>
; __device__ __forceinline__ void gemm_phase(LAS unsigned char* lds, const Gemm g, const StaticOrder& S, const Epi& E) {
;     ...
;             const bool last = (t == nt - 2);
;             const char* a1 = cA + (size_t)(t + 1) * kstep;
;             const char* a2 = last ? nA : cA + (size_t)(t + 2) * kstep; const char* b2 = last ? nB : cB + (size_t)(t + 2) * kstep;
;             const char* a3 = a2 + kstep; const char* b3 = b2 + kstep;
;             if constexpr (SP2) {
;             PG8_LDB(B0, 0, 0); PG8_LDB(B1, 0, 1); PG8_SCHED; PG8_LDA(At, 0, 0); PG8_STAGE(PG8_SA(1, 1), a1 + hstepA, voffA);
;             PG8_WAIT_V(8); PG8_WAIT_L(0); PG8_BAR; PG8_MMA(0, 0, At, B0); PG8_MMA(0, 1, At, B1); PG8_BAR; PG8_SCHED;
;             PG8_LDA(At, 0, 1); PG8_STAGE(PG8_SB(0, 0), b2, voffB); PG8_STAGE(PG8_SB(0, 1), b2 + hstepB, voffB); PG8_STAGE(PG8_SA(0, 0), a2, voffA);
.LBB0_405:
	s_add_u32 s16, s14, 0xfff00080
	s_addc_u32 s17, s15, -1
	s_add_i32 s38, 0, 0x10000
	s_cmp_eq_u32 s37, 28
	s_cselect_b32 s19, s9, s17
	s_cselect_b32 s18, s33, s16
	v_add_u32_e32 v142, s38, v144
	s_cselect_b32 s17, s7, s36
	s_cselect_b32 s16, s34, s35
	s_add_i32 s40, 0, 0x14000
	ds_read_b128 v[146:149], v142
	ds_read_b128 v[150:153], v142 offset:1024
	ds_read_b128 v[154:157], v142 offset:2048
	ds_read_b128 v[158:161], v142 offset:3072
	v_add_u32_e32 v142, s40, v144
	ds_read_b128 v[162:165], v142
	ds_read_b128 v[166:169], v142 offset:1024
	ds_read_b128 v[170:173], v142 offset:2048
	ds_read_b128 v[174:177], v142 offset:3072
	v_lshl_add_u64 v[142:143], s[14:15], 0, v[138:139]
	s_add_i32 m0, s21, 0xc000
	ds_read_b128 v[178:181], v145
	ds_read_b128 v[182:185], v145 offset:1024
	ds_read_b128 v[186:189], v145 offset:2048
	ds_read_b128 v[206:209], v145 offset:3072
	ds_read_b128 v[210:213], v145 offset:4096
	ds_read_b128 v[214:217], v145 offset:5120
	ds_read_b128 v[218:221], v145 offset:6144
	ds_read_b128 v[222:225], v145 offset:7168
	global_load_lds_dwordx4 v[142:143], off
	v_lshl_add_u64 v[142:143], s[14:15], 0, v[140:141]
	s_add_i32 m0, s21, 0xe000
	s_nop 0
	global_load_lds_dwordx4 v[142:143], off
	s_waitcnt vmcnt(8) lgkmcnt(0)
	s_barrier
	v_mfma_f32_16x16x32_bf16 v[124:127], v[146:149], v[178:181], v[124:127]
	v_mfma_f32_16x16x32_bf16 v[120:123], v[154:157], v[178:181], v[120:123]
	v_mfma_f32_16x16x32_bf16 v[116:119], v[146:149], v[186:189], v[116:119]
	v_mfma_f32_16x16x32_bf16 v[108:111], v[154:157], v[186:189], v[108:111]
	v_mfma_f32_16x16x32_bf16 v[100:103], v[146:149], v[210:213], v[100:103]
	v_mfma_f32_16x16x32_bf16 v[92:95], v[154:157], v[210:213], v[92:95]
	v_mfma_f32_16x16x32_bf16 v[84:87], v[146:149], v[218:221], v[84:87]
	v_mfma_f32_16x16x32_bf16 v[76:79], v[154:157], v[218:221], v[76:79]
	v_mfma_f32_16x16x32_bf16 v[124:127], v[150:153], v[182:185], v[124:127]
	v_mfma_f32_16x16x32_bf16 v[120:123], v[158:161], v[182:185], v[120:123]
	v_mfma_f32_16x16x32_bf16 v[116:119], v[150:153], v[206:209], v[116:119]
	v_mfma_f32_16x16x32_bf16 v[108:111], v[158:161], v[206:209], v[108:111]
	v_mfma_f32_16x16x32_bf16 v[100:103], v[150:153], v[214:217], v[100:103]
	v_mfma_f32_16x16x32_bf16 v[92:95], v[158:161], v[214:217], v[92:95]
	v_mfma_f32_16x16x32_bf16 v[84:87], v[150:153], v[222:225], v[84:87]
	v_mfma_f32_16x16x32_bf16 v[76:79], v[158:161], v[222:225], v[76:79]
	v_mfma_f32_16x16x32_bf16 v[112:115], v[162:165], v[178:181], v[112:115]
	v_mfma_f32_16x16x32_bf16 v[104:107], v[170:173], v[178:181], v[104:107]
	v_mfma_f32_16x16x32_bf16 v[96:99], v[162:165], v[186:189], v[96:99]
	v_mfma_f32_16x16x32_bf16 v[88:91], v[170:173], v[186:189], v[88:91]
	v_mfma_f32_16x16x32_bf16 v[80:83], v[162:165], v[210:213], v[80:83]
	v_mfma_f32_16x16x32_bf16 v[72:75], v[170:173], v[210:213], v[72:75]
	v_mfma_f32_16x16x32_bf16 v[68:71], v[162:165], v[218:221], v[68:71]
	v_mfma_f32_16x16x32_bf16 v[64:67], v[170:173], v[218:221], v[64:67]
	v_mfma_f32_16x16x32_bf16 v[112:115], v[166:169], v[182:185], v[112:115]
	v_mfma_f32_16x16x32_bf16 v[104:107], v[174:177], v[182:185], v[104:107]
	v_mfma_f32_16x16x32_bf16 v[96:99], v[166:169], v[206:209], v[96:99]
	v_mfma_f32_16x16x32_bf16 v[88:91], v[174:177], v[206:209], v[88:91]
	v_mfma_f32_16x16x32_bf16 v[80:83], v[166:169], v[214:217], v[80:83]
	v_mfma_f32_16x16x32_bf16 v[72:75], v[174:177], v[214:217], v[72:75]
	v_mfma_f32_16x16x32_bf16 v[68:71], v[166:169], v[222:225], v[68:71]
	v_mfma_f32_16x16x32_bf16 v[64:67], v[174:177], v[222:225], v[64:67]
	s_barrier
	s_add_i32 s38, s38, s20
	v_lshl_add_u64 v[142:143], s[16:17], 0, v[132:133]
	s_mov_b32 m0, s38
	ds_read_b128 v[178:181], v145 offset:16384
	ds_read_b128 v[182:185], v145 offset:17408
	ds_read_b128 v[186:189], v145 offset:18432
	ds_read_b128 v[206:209], v145 offset:19456
	ds_read_b128 v[210:213], v145 offset:20480
	ds_read_b128 v[214:217], v145 offset:21504
	ds_read_b128 v[218:221], v145 offset:22528
	ds_read_b128 v[222:225], v145 offset:23552
	global_load_lds_dwordx4 v[142:143], off
	s_add_i32 m0, s38, 0x2000
	s_add_u32 s38, s16, 0x80000
	v_lshl_add_u64 v[190:191], s[16:17], 0, v[128:129]
	s_addc_u32 s39, s17, 0
	s_add_i32 s40, s40, s20
	global_load_lds_dwordx4 v[190:191], off
	v_lshl_add_u64 v[226:227], s[38:39], 0, v[132:133]
	s_mov_b32 m0, s40
	v_lshl_add_u64 v[228:229], s[18:19], 0, v[130:131]
	global_load_lds_dwordx4 v[226:227], off
	v_lshl_add_u64 v[226:227], s[38:39], 0, v[128:129]
	s_add_i32 m0, s40, 0x2000
	s_nop 0
	global_load_lds_dwordx4 v[226:227], off
	v_lshl_add_u64 v[226:227], s[18:19], 0, v[134:135]
	s_mov_b32 m0, s21
	s_nop 0
	global_load_lds_dwordx4 v[226:227], off
	s_mov_b32 m0, s22
	s_nop 0
	global_load_lds_dwordx4 v[228:229], off
	s_waitcnt vmcnt(8) lgkmcnt(0)
	s_barrier
; #define PG8_STAGE(bufoff, gbase, voff) do { _Pragma("unroll") for (int _i = 0; _i < 2; ++_i) \
;         __builtin_amdgcn_global_load_lds((const unsigned*)((const char*)(gbase) + (voff)[_i]), (LAS unsigned*)(lds + (bufoff) + ldsw + _i * 8192), 16, 0, 0); } while (0)
; #define PG8_LDA(dst, b, h) do { _Pragma("unroll") for (int m = 0; m < 4; ++m) _Pragma("unroll") for (int k = 0; k < 2; ++k) dst[m][k] = *(const LAS bf16x8*)(lds + PG8_SA(b, h) + aoff + m * 2048 + k * 1024); } while (0)
; #define PG8_LDB(dst, b, h) do { _Pragma("unroll") for (int n = 0; n < 2; ++n) _Pragma("unroll") for (int k = 0; k < 2; ++k) dst[n][k] = *(const LAS bf16x8*)(lds + PG8_SB(b, h) + boff + n * 2048 + k * 1024); } while (0)
; #define PG8_MMA(ai, bj, At, Bt) do { __builtin_amdgcn_s_setprio(1); _Pragma("unroll") for (int m = 0; m < 4; ++m) _Pragma("unroll") for (int n = 0; n < 2; ++n) _Pragma("unroll") for (int k = 0; k < 2; ++k) \
;         acc[ai][bj][m][n] = __builtin_amdgcn_mfma_f32_16x16x32_bf16(Bt[n][k], At[m][k], acc[ai][bj][m][n], 0, 0, 0); __builtin_amdgcn_s_setprio(0); } while (0)
; #define PG8_WAIT_V(n) asm volatile("s_waitcnt vmcnt(" #n ")" ::: "memory")
; #define PG8_WAIT_L(n) asm volatile("s_waitcnt lgkmcnt(" #n ")" ::: "memory")
; #define PG8_BAR __builtin_amdgcn_s_barrier()
; #define PG8_SCHED __builtin_amdgcn_sched_barrier(0)
; template <class Epi, bool PERMA = false, bool DUAL = false, bool ALIGN_EPI = true, bool SP2 = true>
; __device__ __forceinline__ void gemm_phase(LAS unsigned char* lds, const Gemm g, const StaticOrder& S, const Epi& E) {
;     ...
;             PG8_WAIT_V(8); PG8_WAIT_L(0); PG8_BAR; PG8_MMA(1, 0, At, B0); PG8_MMA(1, 1, At, B1); PG8_BAR; PG8_SCHED;
;             PG8_LDB(B0, 1, 0); PG8_LDB(B1, 1, 1); PG8_SCHED; PG8_LDA(At, 1, 0); PG8_STAGE(PG8_SA(0, 1), a2 + hstepA, voffA);
;             PG8_WAIT_V(8); PG8_WAIT_L(0); PG8_BAR; PG8_MMA(0, 0, At, B0); PG8_MMA(0, 1, At, B1); PG8_BAR; PG8_SCHED;
	v_mfma_f32_16x16x32_bf16 v[60:63], v[146:149], v[178:181], v[60:63]
	v_mfma_f32_16x16x32_bf16 v[56:59], v[154:157], v[178:181], v[56:59]
	v_mfma_f32_16x16x32_bf16 v[52:55], v[146:149], v[186:189], v[52:55]
	v_mfma_f32_16x16x32_bf16 v[44:47], v[154:157], v[186:189], v[44:47]
	v_mfma_f32_16x16x32_bf16 v[36:39], v[146:149], v[210:213], v[36:39]
	v_mfma_f32_16x16x32_bf16 v[28:31], v[154:157], v[210:213], v[28:31]
	v_mfma_f32_16x16x32_bf16 v[20:23], v[146:149], v[218:221], v[20:23]
	v_mfma_f32_16x16x32_bf16 v[12:15], v[154:157], v[218:221], v[12:15]
	v_mfma_f32_16x16x32_bf16 v[60:63], v[150:153], v[182:185], v[60:63]
	v_mfma_f32_16x16x32_bf16 v[56:59], v[158:161], v[182:185], v[56:59]
	v_mfma_f32_16x16x32_bf16 v[52:55], v[150:153], v[206:209], v[52:55]
	v_mfma_f32_16x16x32_bf16 v[44:47], v[158:161], v[206:209], v[44:47]
	v_mfma_f32_16x16x32_bf16 v[36:39], v[150:153], v[214:217], v[36:39]
	v_mfma_f32_16x16x32_bf16 v[28:31], v[158:161], v[214:217], v[28:31]
	v_mfma_f32_16x16x32_bf16 v[20:23], v[150:153], v[222:225], v[20:23]
	v_mfma_f32_16x16x32_bf16 v[12:15], v[158:161], v[222:225], v[12:15]
	v_mfma_f32_16x16x32_bf16 v[48:51], v[162:165], v[178:181], v[48:51]
	v_mfma_f32_16x16x32_bf16 v[40:43], v[170:173], v[178:181], v[40:43]
	v_mfma_f32_16x16x32_bf16 v[32:35], v[162:165], v[186:189], v[32:35]
	v_mfma_f32_16x16x32_bf16 v[24:27], v[170:173], v[186:189], v[24:27]
	v_mfma_f32_16x16x32_bf16 v[16:19], v[162:165], v[210:213], v[16:19]
	v_mfma_f32_16x16x32_bf16 v[8:11], v[170:173], v[210:213], v[8:11]
	v_mfma_f32_16x16x32_bf16 v[4:7], v[162:165], v[218:221], v[4:7]
	v_mfma_f32_16x16x32_bf16 v[0:3], v[170:173], v[218:221], v[0:3]
	v_mfma_f32_16x16x32_bf16 v[48:51], v[166:169], v[182:185], v[48:51]
	v_mfma_f32_16x16x32_bf16 v[40:43], v[174:177], v[182:185], v[40:43]
	v_mfma_f32_16x16x32_bf16 v[32:35], v[166:169], v[206:209], v[32:35]
	v_mfma_f32_16x16x32_bf16 v[24:27], v[174:177], v[206:209], v[24:27]
	v_mfma_f32_16x16x32_bf16 v[16:19], v[166:169], v[214:217], v[16:19]
	v_mfma_f32_16x16x32_bf16 v[8:11], v[174:177], v[214:217], v[8:11]
	v_mfma_f32_16x16x32_bf16 v[4:7], v[166:169], v[222:225], v[4:7]
	v_mfma_f32_16x16x32_bf16 v[0:3], v[174:177], v[222:225], v[0:3]
	s_barrier
	s_add_i32 s38, 0, 0x18000
	s_add_i32 s39, 0, 0x1c000
	v_add_u32_e32 v158, s38, v144
	v_add_u32_e32 v174, s39, v144
	ds_read_b128 v[146:149], v158
	ds_read_b128 v[150:153], v158 offset:1024
	ds_read_b128 v[154:157], v158 offset:2048
	ds_read_b128 v[158:161], v158 offset:3072
	ds_read_b128 v[162:165], v174
	ds_read_b128 v[166:169], v174 offset:1024
	ds_read_b128 v[170:173], v174 offset:2048
	ds_read_b128 v[174:177], v174 offset:3072
	s_add_u32 s18, s18, 0x100000
	s_addc_u32 s19, s19, 0
	s_mov_b32 m0, s23
	v_lshl_add_u64 v[238:239], s[18:19], 0, v[134:135]
	ds_read_b128 v[178:181], v145 offset:32768
	ds_read_b128 v[182:185], v145 offset:33792
	ds_read_b128 v[186:189], v145 offset:34816
	ds_read_b128 v[206:209], v145 offset:35840
	ds_read_b128 v[210:213], v145 offset:36864
	ds_read_b128 v[214:217], v145 offset:37888
	ds_read_b128 v[218:221], v145 offset:38912
	ds_read_b128 v[222:225], v145 offset:39936
	global_load_lds_dwordx4 v[238:239], off
	v_lshl_add_u64 v[238:239], s[18:19], 0, v[130:131]
	s_mov_b32 m0, s24
	s_nop 0
	global_load_lds_dwordx4 v[238:239], off
	s_waitcnt vmcnt(8) lgkmcnt(0)
	s_barrier
	v_mfma_f32_16x16x32_bf16 v[124:127], v[146:149], v[178:181], v[124:127]
	v_mfma_f32_16x16x32_bf16 v[120:123], v[154:157], v[178:181], v[120:123]
	v_mfma_f32_16x16x32_bf16 v[116:119], v[146:149], v[186:189], v[116:119]
	v_mfma_f32_16x16x32_bf16 v[108:111], v[154:157], v[186:189], v[108:111]
	v_mfma_f32_16x16x32_bf16 v[100:103], v[146:149], v[210:213], v[100:103]
	v_mfma_f32_16x16x32_bf16 v[92:95], v[154:157], v[210:213], v[92:95]
	v_mfma_f32_16x16x32_bf16 v[84:87], v[146:149], v[218:221], v[84:87]
	v_mfma_f32_16x16x32_bf16 v[76:79], v[154:157], v[218:221], v[76:79]
	v_mfma_f32_16x16x32_bf16 v[124:127], v[150:153], v[182:185], v[124:127]
	v_mfma_f32_16x16x32_bf16 v[120:123], v[158:161], v[182:185], v[120:123]
	v_mfma_f32_16x16x32_bf16 v[116:119], v[150:153], v[206:209], v[116:119]
	v_mfma_f32_16x16x32_bf16 v[108:111], v[158:161], v[206:209], v[108:111]
	v_mfma_f32_16x16x32_bf16 v[100:103], v[150:153], v[214:217], v[100:103]
	v_mfma_f32_16x16x32_bf16 v[92:95], v[158:161], v[214:217], v[92:95]
	v_mfma_f32_16x16x32_bf16 v[84:87], v[150:153], v[222:225], v[84:87]
	v_mfma_f32_16x16x32_bf16 v[76:79], v[158:161], v[222:225], v[76:79]
	v_mfma_f32_16x16x32_bf16 v[112:115], v[162:165], v[178:181], v[112:115]
	v_mfma_f32_16x16x32_bf16 v[104:107], v[170:173], v[178:181], v[104:107]
	v_mfma_f32_16x16x32_bf16 v[96:99], v[162:165], v[186:189], v[96:99]
	v_mfma_f32_16x16x32_bf16 v[88:91], v[170:173], v[186:189], v[88:91]
	v_mfma_f32_16x16x32_bf16 v[80:83], v[162:165], v[210:213], v[80:83]
	v_mfma_f32_16x16x32_bf16 v[72:75], v[170:173], v[210:213], v[72:75]
	v_mfma_f32_16x16x32_bf16 v[68:71], v[162:165], v[218:221], v[68:71]
	v_mfma_f32_16x16x32_bf16 v[64:67], v[170:173], v[218:221], v[64:67]
	v_mfma_f32_16x16x32_bf16 v[112:115], v[166:169], v[182:185], v[112:115]
	v_mfma_f32_16x16x32_bf16 v[104:107], v[174:177], v[182:185], v[104:107]
	v_mfma_f32_16x16x32_bf16 v[96:99], v[166:169], v[206:209], v[96:99]
	v_mfma_f32_16x16x32_bf16 v[88:91], v[174:177], v[206:209], v[88:91]
	v_mfma_f32_16x16x32_bf16 v[80:83], v[166:169], v[214:217], v[80:83]
	v_mfma_f32_16x16x32_bf16 v[72:75], v[174:177], v[214:217], v[72:75]
	v_mfma_f32_16x16x32_bf16 v[68:71], v[166:169], v[222:225], v[68:71]
	v_mfma_f32_16x16x32_bf16 v[64:67], v[174:177], v[222:225], v[64:67]
	s_barrier
; #define PG8_STAGE(bufoff, gbase, voff) do { _Pragma("unroll") for (int _i = 0; _i < 2; ++_i) \
;         __builtin_amdgcn_global_load_lds((const unsigned*)((const char*)(gbase) + (voff)[_i]), (LAS unsigned*)(lds + (bufoff) + ldsw + _i * 8192), 16, 0, 0); } while (0)
; #define PG8_LDA(dst, b, h) do { _Pragma("unroll") for (int m = 0; m < 4; ++m) _Pragma("unroll") for (int k = 0; k < 2; ++k) dst[m][k] = *(const LAS bf16x8*)(lds + PG8_SA(b, h) + aoff + m * 2048 + k * 1024); } while (0)
; #define PG8_MMA(ai, bj, At, Bt) do { __builtin_amdgcn_s_setprio(1); _Pragma("unroll") for (int m = 0; m < 4; ++m) _Pragma("unroll") for (int n = 0; n < 2; ++n) _Pragma("unroll") for (int k = 0; k < 2; ++k) \
;         acc[ai][bj][m][n] = __builtin_amdgcn_mfma_f32_16x16x32_bf16(Bt[n][k], At[m][k], acc[ai][bj][m][n], 0, 0, 0); __builtin_amdgcn_s_setprio(0); } while (0)
; #define PG8_WAIT_V(n) asm volatile("s_waitcnt vmcnt(" #n ")" ::: "memory")
; #define PG8_WAIT_L(n) asm volatile("s_waitcnt lgkmcnt(" #n ")" ::: "memory")
; #define PG8_BAR __builtin_amdgcn_s_barrier()
; #define PG8_SCHED __builtin_amdgcn_sched_barrier(0)
; template <class Epi, bool PERMA = false, bool DUAL = false, bool ALIGN_EPI = true, bool SP2 = true>
; __device__ __forceinline__ void gemm_phase(LAS unsigned char* lds, const Gemm g, const StaticOrder& S, const Epi& E) {
;     ...
;             PG8_LDA(At, 1, 1); PG8_STAGE(PG8_SB(1, 0), b3, voffB); PG8_STAGE(PG8_SB(1, 1), b3 + hstepB, voffB); PG8_STAGE(PG8_SA(1, 0), a3, voffA);
;             PG8_WAIT_V(8); PG8_WAIT_L(0); PG8_BAR; PG8_MMA(1, 0, At, B0); PG8_MMA(1, 1, At, B1); PG8_BAR; PG8_SCHED;
;     ...
;         if constexpr (ALIGN_EPI) { if (wr == 0) PG8_BAR; }
	s_add_i32 s18, s38, s20
	v_lshl_add_u64 v[142:143], v[142:143], 0, s[46:47]
	s_mov_b32 m0, s18
	ds_read_b128 v[178:181], v145 offset:49152
	ds_read_b128 v[182:185], v145 offset:50176
	ds_read_b128 v[186:189], v145 offset:51200
	ds_read_b128 v[206:209], v145 offset:52224
	ds_read_b128 v[210:213], v145 offset:53248
	ds_read_b128 v[214:217], v145 offset:54272
	ds_read_b128 v[218:221], v145 offset:55296
	ds_read_b128 v[222:225], v145 offset:56320
	global_load_lds_dwordx4 v[142:143], off
	s_add_i32 m0, s18, 0x2000
	s_add_u32 s16, s16, 0x80080
	v_lshl_add_u64 v[142:143], v[190:191], 0, s[46:47]
	s_addc_u32 s17, s17, 0
	s_add_i32 s18, s39, s20
	global_load_lds_dwordx4 v[142:143], off
	v_lshl_add_u64 v[142:143], s[16:17], 0, v[132:133]
	s_mov_b32 m0, s18
	s_nop 0
	global_load_lds_dwordx4 v[142:143], off
	v_lshl_add_u64 v[142:143], s[16:17], 0, v[128:129]
	s_add_i32 m0, s18, 0x2000
	s_nop 0
	global_load_lds_dwordx4 v[142:143], off
	v_lshl_add_u64 v[142:143], v[226:227], 0, s[46:47]
	s_mov_b32 m0, s27
	s_nop 0
	global_load_lds_dwordx4 v[142:143], off
	v_lshl_add_u64 v[142:143], v[228:229], 0, s[46:47]
	s_mov_b32 m0, s28
	s_nop 0
	global_load_lds_dwordx4 v[142:143], off
	s_waitcnt vmcnt(8) lgkmcnt(0)
	s_barrier
	v_mfma_f32_16x16x32_bf16 v[60:63], v[146:149], v[178:181], v[60:63]
	v_mfma_f32_16x16x32_bf16 v[56:59], v[154:157], v[178:181], v[56:59]
	v_mfma_f32_16x16x32_bf16 v[52:55], v[146:149], v[186:189], v[52:55]
	v_mfma_f32_16x16x32_bf16 v[44:47], v[154:157], v[186:189], v[44:47]
	v_mfma_f32_16x16x32_bf16 v[36:39], v[146:149], v[210:213], v[36:39]
	v_mfma_f32_16x16x32_bf16 v[28:31], v[154:157], v[210:213], v[28:31]
	v_mfma_f32_16x16x32_bf16 v[20:23], v[146:149], v[218:221], v[20:23]
	v_mfma_f32_16x16x32_bf16 v[12:15], v[154:157], v[218:221], v[12:15]
	v_mfma_f32_16x16x32_bf16 v[60:63], v[150:153], v[182:185], v[60:63]
	v_mfma_f32_16x16x32_bf16 v[56:59], v[158:161], v[182:185], v[56:59]
	v_mfma_f32_16x16x32_bf16 v[52:55], v[150:153], v[206:209], v[52:55]
	v_mfma_f32_16x16x32_bf16 v[44:47], v[158:161], v[206:209], v[44:47]
	v_mfma_f32_16x16x32_bf16 v[36:39], v[150:153], v[214:217], v[36:39]
	v_mfma_f32_16x16x32_bf16 v[28:31], v[158:161], v[214:217], v[28:31]
	v_mfma_f32_16x16x32_bf16 v[20:23], v[150:153], v[222:225], v[20:23]
	v_mfma_f32_16x16x32_bf16 v[12:15], v[158:161], v[222:225], v[12:15]
	v_mfma_f32_16x16x32_bf16 v[48:51], v[162:165], v[178:181], v[48:51]
	v_mfma_f32_16x16x32_bf16 v[40:43], v[170:173], v[178:181], v[40:43]
	v_mfma_f32_16x16x32_bf16 v[32:35], v[162:165], v[186:189], v[32:35]
	v_mfma_f32_16x16x32_bf16 v[24:27], v[170:173], v[186:189], v[24:27]
	v_mfma_f32_16x16x32_bf16 v[16:19], v[162:165], v[210:213], v[16:19]
	v_mfma_f32_16x16x32_bf16 v[8:11], v[170:173], v[210:213], v[8:11]
	v_mfma_f32_16x16x32_bf16 v[4:7], v[162:165], v[218:221], v[4:7]
	v_mfma_f32_16x16x32_bf16 v[0:3], v[170:173], v[218:221], v[0:3]
	v_mfma_f32_16x16x32_bf16 v[48:51], v[166:169], v[182:185], v[48:51]
	v_mfma_f32_16x16x32_bf16 v[40:43], v[174:177], v[182:185], v[40:43]
	v_mfma_f32_16x16x32_bf16 v[32:35], v[166:169], v[206:209], v[32:35]
	v_mfma_f32_16x16x32_bf16 v[24:27], v[174:177], v[206:209], v[24:27]
	v_mfma_f32_16x16x32_bf16 v[16:19], v[166:169], v[214:217], v[16:19]
	v_mfma_f32_16x16x32_bf16 v[8:11], v[174:177], v[214:217], v[8:11]
	v_mfma_f32_16x16x32_bf16 v[4:7], v[166:169], v[222:225], v[4:7]
	v_mfma_f32_16x16x32_bf16 v[0:3], v[174:177], v[222:225], v[0:3]
	s_barrier
	s_add_i32 s37, s37, 2
	s_add_u32 s14, s14, 0x100
	s_addc_u32 s15, s15, 0
	s_add_u32 s35, s35, 0x100
	s_addc_u32 s36, s36, 0
	s_cmp_gt_u32 s37, 29
	s_cbranch_scc0 .LBB0_405
	s_and_b64 vcc, exec, s[4:5]
	s_cbranch_vccz .LBB0_408
	s_barrier

; #define PG8_STAGE(bufoff, gbase, voff) do { _Pragma("unroll") for (int _i = 0; _i < 2; ++_i) \
;         __builtin_amdgcn_global_load_lds((const unsigned*)((const char*)(gbase) + (voff)[_i]), (LAS unsigned*)(lds + (bufoff) + ldsw + _i * 8192), 16, 0, 0); } while (0)
; #define PG8_LDA(dst, b, h) do { _Pragma("unroll") for (int m = 0; m < 4; ++m) _Pragma("unroll") for (int k = 0; k < 2; ++k) dst[m][k] = *(const LAS bf16x8*)(lds + PG8_SA(b, h) + aoff + m * 2048 + k * 1024); } while (0)
; #define PG8_LDB(dst, b, h) do { _Pragma("unroll") for (int n = 0; n < 2; ++n) _Pragma("unroll") for (int k = 0; k < 2; ++k) dst[n][k] = *(const LAS bf16x8*)(lds + PG8_SB(b, h) + boff + n * 2048 + k * 1024); } while (0)
; #define PG8_MMA(ai, bj, At, Bt) do { __builtin_amdgcn_s_setprio(1); _Pragma("unroll") for (int m = 0; m < 4; ++m) _Pragma("unroll") for (int n = 0; n < 2; ++n) _Pragma("unroll") for (int k = 0; k < 2; ++k) \
;         acc[ai][bj][m][n] = __builtin_amdgcn_mfma_f32_16x16x32_bf16(Bt[n][k], At[m][k], acc[ai][bj][m][n], 0, 0, 0); __builtin_amdgcn_s_setprio(0); } while (0)
; #define PG8_WAIT_V(n) asm volatile("s_waitcnt vmcnt(" #n ")" ::: "memory")
; #define PG8_WAIT_L(n) asm volatile("s_waitcnt lgkmcnt(" #n ")" ::: "memory")
; #define PG8_BAR __builtin_amdgcn_s_barrier()
; #define PG8_SCHED __builtin_amdgcn_sched_barrier(0)
; template <class Epi, bool PERMA = false, bool DUAL = false, bool ALIGN_EPI = true, bool SP2 = true>
; __device__ __forceinline__ void gemm_phase(LAS unsigned char* lds, const Gemm g, const StaticOrder& S, const Epi& E) {
;     ...
;             const bool last = (t == nt - 2);
;             const char* a1 = cA + (size_t)(t + 1) * kstep;
;             const char* a2 = last ? nA : cA + (size_t)(t + 2) * kstep; const char* b2 = last ? nB : cB + (size_t)(t + 2) * kstep;
;             const char* a3 = a2 + kstep; const char* b3 = b2 + kstep;
;             if constexpr (SP2) {
;             PG8_LDB(B0, 0, 0); PG8_LDB(B1, 0, 1); PG8_SCHED; PG8_LDA(At, 0, 0); PG8_STAGE(PG8_SA(1, 1), a1 + hstepA, voffA);
;             PG8_WAIT_V(8); PG8_WAIT_L(0); PG8_BAR; PG8_MMA(0, 0, At, B0); PG8_MMA(0, 1, At, B1); PG8_BAR; PG8_SCHED;
;             PG8_LDA(At, 0, 1); PG8_STAGE(PG8_SB(0, 0), b2, voffB); PG8_STAGE(PG8_SB(0, 1), b2 + hstepB, voffB); PG8_STAGE(PG8_SA(0, 0), a2, voffA);
.LBB0_528:
	s_add_u32 s22, s20, 0x100
	s_addc_u32 s23, s21, 0
	s_add_i32 s52, 0, 0x10000
	s_cmp_eq_u32 s51, 28
	s_cselect_b32 s27, s15, s23
	s_cselect_b32 s26, s39, s22
	s_cselect_b32 s25, s13, s50
	s_cselect_b32 s24, s48, s49
	s_add_i32 s53, 0, 0x14000
	v_add_u32_e32 v108, s52, v193
	v_add_u32_e32 v124, s53, v193
	ds_read_b128 v[96:99], v108
	ds_read_b128 v[100:103], v108 offset:1024
	ds_read_b128 v[104:107], v108 offset:2048
	ds_read_b128 v[108:111], v108 offset:3072
	ds_read_b128 v[112:115], v124
	ds_read_b128 v[116:119], v124 offset:1024
	ds_read_b128 v[120:123], v124 offset:2048
	ds_read_b128 v[124:127], v124 offset:3072
	v_lshl_add_u64 v[220:221], s[20:21], 0, v[216:217]
	s_add_i32 m0, s29, 0xc000
	ds_read_b128 v[128:131], v224
	ds_read_b128 v[132:135], v224 offset:1024
	ds_read_b128 v[136:139], v224 offset:2048
	ds_read_b128 v[144:147], v224 offset:3072
	ds_read_b128 v[152:155], v224 offset:4096
	ds_read_b128 v[160:163], v224 offset:5120
	ds_read_b128 v[168:171], v224 offset:6144
	ds_read_b128 v[188:191], v224 offset:7168
	global_load_lds_dwordx4 v[220:221], off
	v_lshl_add_u64 v[220:221], s[20:21], 0, v[218:219]
	s_add_i32 m0, s29, 0xe000
	s_nop 0
	global_load_lds_dwordx4 v[220:221], off
	s_waitcnt vmcnt(8) lgkmcnt(0)
	s_barrier
	v_mfma_f32_16x16x32_bf16 v[184:187], v[96:99], v[128:131], v[184:187]
	v_mfma_f32_16x16x32_bf16 v[92:95], v[104:107], v[128:131], v[92:95]
	v_mfma_f32_16x16x32_bf16 v[180:183], v[96:99], v[136:139], v[180:183]
	v_mfma_f32_16x16x32_bf16 v[88:91], v[104:107], v[136:139], v[88:91]
	v_mfma_f32_16x16x32_bf16 v[176:179], v[96:99], v[152:155], v[176:179]
	v_mfma_f32_16x16x32_bf16 v[84:87], v[104:107], v[152:155], v[84:87]
	v_mfma_f32_16x16x32_bf16 v[172:175], v[96:99], v[168:171], v[172:175]
	v_mfma_f32_16x16x32_bf16 v[80:83], v[104:107], v[168:171], v[80:83]
	v_mfma_f32_16x16x32_bf16 v[184:187], v[100:103], v[132:135], v[184:187]
	v_mfma_f32_16x16x32_bf16 v[92:95], v[108:111], v[132:135], v[92:95]
	v_mfma_f32_16x16x32_bf16 v[180:183], v[100:103], v[144:147], v[180:183]
	v_mfma_f32_16x16x32_bf16 v[88:91], v[108:111], v[144:147], v[88:91]
	v_mfma_f32_16x16x32_bf16 v[176:179], v[100:103], v[160:163], v[176:179]
	v_mfma_f32_16x16x32_bf16 v[84:87], v[108:111], v[160:163], v[84:87]
	v_mfma_f32_16x16x32_bf16 v[172:175], v[100:103], v[188:191], v[172:175]
	v_mfma_f32_16x16x32_bf16 v[80:83], v[108:111], v[188:191], v[80:83]
	v_mfma_f32_16x16x32_bf16 v[164:167], v[112:115], v[128:131], v[164:167]
	v_mfma_f32_16x16x32_bf16 v[76:79], v[120:123], v[128:131], v[76:79]
	v_mfma_f32_16x16x32_bf16 v[72:75], v[120:123], v[136:139], v[72:75]
	v_mfma_f32_16x16x32_bf16 v[68:71], v[120:123], v[152:155], v[68:71]
	v_mfma_f32_16x16x32_bf16 v[64:67], v[120:123], v[168:171], v[64:67]
	v_mfma_f32_16x16x32_bf16 v[164:167], v[116:119], v[132:135], v[164:167]
	v_mfma_f32_16x16x32_bf16 v[76:79], v[124:127], v[132:135], v[76:79]
	v_mfma_f32_16x16x32_bf16 v[128:131], v[112:115], v[136:139], v[156:159]
	v_mfma_f32_16x16x32_bf16 v[72:75], v[124:127], v[144:147], v[72:75]
	v_mfma_f32_16x16x32_bf16 v[132:135], v[112:115], v[152:155], v[148:151]
	v_mfma_f32_16x16x32_bf16 v[68:71], v[124:127], v[160:163], v[68:71]
	v_mfma_f32_16x16x32_bf16 v[136:139], v[112:115], v[168:171], v[140:143]
	v_mfma_f32_16x16x32_bf16 v[64:67], v[124:127], v[188:191], v[64:67]
	v_mfma_f32_16x16x32_bf16 v[128:131], v[116:119], v[144:147], v[128:131]
	v_mfma_f32_16x16x32_bf16 v[132:135], v[116:119], v[160:163], v[132:135]
	v_mfma_f32_16x16x32_bf16 v[136:139], v[116:119], v[188:191], v[136:139]
	s_barrier
	s_add_i32 s20, s52, s28
	v_lshl_add_u64 v[220:221], s[24:25], 0, v[210:211]
	s_mov_b32 m0, s20
	ds_read_b128 v[140:143], v224 offset:16384
	ds_read_b128 v[144:147], v224 offset:17408
	ds_read_b128 v[148:151], v224 offset:18432
	ds_read_b128 v[152:155], v224 offset:19456
	ds_read_b128 v[156:159], v224 offset:20480
	ds_read_b128 v[160:163], v224 offset:21504
	ds_read_b128 v[168:171], v224 offset:22528
	ds_read_b128 v[188:191], v224 offset:23552
	global_load_lds_dwordx4 v[220:221], off
	s_add_i32 m0, s20, 0x2000
	s_add_u32 s20, s24, 0x80000
	v_lshl_add_u64 v[238:239], s[24:25], 0, v[206:207]
	s_addc_u32 s21, s25, 0
	s_add_i32 s52, s53, s28
	global_load_lds_dwordx4 v[238:239], off
	v_lshl_add_u64 v[226:227], s[20:21], 0, v[210:211]
	s_mov_b32 m0, s52
	v_lshl_add_u64 v[240:241], s[26:27], 0, v[212:213]
	global_load_lds_dwordx4 v[226:227], off
	v_lshl_add_u64 v[226:227], s[20:21], 0, v[206:207]
	s_add_i32 m0, s52, 0x2000
	v_lshl_add_u64 v[242:243], s[26:27], 0, v[208:209]
	global_load_lds_dwordx4 v[226:227], off
	s_mov_b32 m0, s29
	s_nop 0
	global_load_lds_dwordx4 v[240:241], off
	s_mov_b32 m0, s30
	s_nop 0
	global_load_lds_dwordx4 v[242:243], off
	s_waitcnt vmcnt(8) lgkmcnt(0)
	s_barrier
; #define PG8_STAGE(bufoff, gbase, voff) do { _Pragma("unroll") for (int _i = 0; _i < 2; ++_i) \
;         __builtin_amdgcn_global_load_lds((const unsigned*)((const char*)(gbase) + (voff)[_i]), (LAS unsigned*)(lds + (bufoff) + ldsw + _i * 8192), 16, 0, 0); } while (0)
; #define PG8_LDA(dst, b, h) do { _Pragma("unroll") for (int m = 0; m < 4; ++m) _Pragma("unroll") for (int k = 0; k < 2; ++k) dst[m][k] = *(const LAS bf16x8*)(lds + PG8_SA(b, h) + aoff + m * 2048 + k * 1024); } while (0)
; #define PG8_LDB(dst, b, h) do { _Pragma("unroll") for (int n = 0; n < 2; ++n) _Pragma("unroll") for (int k = 0; k < 2; ++k) dst[n][k] = *(const LAS bf16x8*)(lds + PG8_SB(b, h) + boff + n * 2048 + k * 1024); } while (0)
; #define PG8_MMA(ai, bj, At, Bt) do { __builtin_amdgcn_s_setprio(1); _Pragma("unroll") for (int m = 0; m < 4; ++m) _Pragma("unroll") for (int n = 0; n < 2; ++n) _Pragma("unroll") for (int k = 0; k < 2; ++k) \
;         acc[ai][bj][m][n] = __builtin_amdgcn_mfma_f32_16x16x32_bf16(Bt[n][k], At[m][k], acc[ai][bj][m][n], 0, 0, 0); __builtin_amdgcn_s_setprio(0); } while (0)
; #define PG8_WAIT_V(n) asm volatile("s_waitcnt vmcnt(" #n ")" ::: "memory")
; #define PG8_WAIT_L(n) asm volatile("s_waitcnt lgkmcnt(" #n ")" ::: "memory")
; #define PG8_BAR __builtin_amdgcn_s_barrier()
; #define PG8_SCHED __builtin_amdgcn_sched_barrier(0)
; template <class Epi, bool PERMA = false, bool DUAL = false, bool ALIGN_EPI = true, bool SP2 = true>
; __device__ __forceinline__ void gemm_phase(LAS unsigned char* lds, const Gemm g, const StaticOrder& S, const Epi& E) {
;     ...
;             PG8_WAIT_V(8); PG8_WAIT_L(0); PG8_BAR; PG8_MMA(1, 0, At, B0); PG8_MMA(1, 1, At, B1); PG8_BAR; PG8_SCHED;
;             PG8_LDB(B0, 1, 0); PG8_LDB(B1, 1, 1); PG8_SCHED; PG8_LDA(At, 1, 0); PG8_STAGE(PG8_SA(0, 1), a2 + hstepA, voffA);
;             PG8_WAIT_V(8); PG8_WAIT_L(0); PG8_BAR; PG8_MMA(0, 0, At, B0); PG8_MMA(0, 1, At, B1); PG8_BAR; PG8_SCHED;
	v_mfma_f32_16x16x32_bf16 v[60:63], v[96:99], v[140:143], v[60:63]
	v_mfma_f32_16x16x32_bf16 v[28:31], v[104:107], v[140:143], v[28:31]
	v_mfma_f32_16x16x32_bf16 v[56:59], v[96:99], v[148:151], v[56:59]
	v_mfma_f32_16x16x32_bf16 v[24:27], v[104:107], v[148:151], v[24:27]
	v_mfma_f32_16x16x32_bf16 v[52:55], v[96:99], v[156:159], v[52:55]
	v_mfma_f32_16x16x32_bf16 v[20:23], v[104:107], v[156:159], v[20:23]
	v_mfma_f32_16x16x32_bf16 v[48:51], v[96:99], v[168:171], v[48:51]
	v_mfma_f32_16x16x32_bf16 v[16:19], v[104:107], v[168:171], v[16:19]
	v_mfma_f32_16x16x32_bf16 v[60:63], v[100:103], v[144:147], v[60:63]
	v_mfma_f32_16x16x32_bf16 v[28:31], v[108:111], v[144:147], v[28:31]
	v_mfma_f32_16x16x32_bf16 v[56:59], v[100:103], v[152:155], v[56:59]
	v_mfma_f32_16x16x32_bf16 v[24:27], v[108:111], v[152:155], v[24:27]
	v_mfma_f32_16x16x32_bf16 v[52:55], v[100:103], v[160:163], v[52:55]
	v_mfma_f32_16x16x32_bf16 v[20:23], v[108:111], v[160:163], v[20:23]
	v_mfma_f32_16x16x32_bf16 v[48:51], v[100:103], v[188:191], v[48:51]
	v_mfma_f32_16x16x32_bf16 v[16:19], v[108:111], v[188:191], v[16:19]
	v_mfma_f32_16x16x32_bf16 v[44:47], v[112:115], v[140:143], v[44:47]
	v_mfma_f32_16x16x32_bf16 v[12:15], v[120:123], v[140:143], v[12:15]
	v_mfma_f32_16x16x32_bf16 v[40:43], v[112:115], v[148:151], v[40:43]
	v_mfma_f32_16x16x32_bf16 v[8:11], v[120:123], v[148:151], v[8:11]
	v_mfma_f32_16x16x32_bf16 v[36:39], v[112:115], v[156:159], v[36:39]
	v_mfma_f32_16x16x32_bf16 v[4:7], v[120:123], v[156:159], v[4:7]
	v_mfma_f32_16x16x32_bf16 v[32:35], v[112:115], v[168:171], v[32:35]
	v_mfma_f32_16x16x32_bf16 v[0:3], v[120:123], v[168:171], v[0:3]
	v_mfma_f32_16x16x32_bf16 v[44:47], v[116:119], v[144:147], v[44:47]
	v_mfma_f32_16x16x32_bf16 v[12:15], v[124:127], v[144:147], v[12:15]
	v_mfma_f32_16x16x32_bf16 v[40:43], v[116:119], v[152:155], v[40:43]
	v_mfma_f32_16x16x32_bf16 v[8:11], v[124:127], v[152:155], v[8:11]
	v_mfma_f32_16x16x32_bf16 v[36:39], v[116:119], v[160:163], v[36:39]
	v_mfma_f32_16x16x32_bf16 v[4:7], v[124:127], v[160:163], v[4:7]
	v_mfma_f32_16x16x32_bf16 v[32:35], v[116:119], v[188:191], v[32:35]
	v_mfma_f32_16x16x32_bf16 v[0:3], v[124:127], v[188:191], v[0:3]
	s_barrier
	s_add_i32 s52, 0, 0x18000
	s_add_i32 s53, 0, 0x1c000
	v_add_u32_e32 v108, s52, v193
	v_add_u32_e32 v124, s53, v193
	ds_read_b128 v[96:99], v108
	ds_read_b128 v[100:103], v108 offset:1024
	ds_read_b128 v[104:107], v108 offset:2048
	ds_read_b128 v[108:111], v108 offset:3072
	ds_read_b128 v[112:115], v124
	ds_read_b128 v[116:119], v124 offset:1024
	ds_read_b128 v[120:123], v124 offset:2048
	ds_read_b128 v[124:127], v124 offset:3072
	s_add_u32 s20, s26, 0x80000
	s_addc_u32 s21, s27, 0
	s_mov_b32 m0, s31
	v_lshl_add_u64 v[156:157], s[20:21], 0, v[212:213]
	ds_read_b128 v[140:143], v224 offset:32768
	ds_read_b128 v[144:147], v224 offset:33792
	ds_read_b128 v[148:151], v224 offset:34816
	ds_read_b128 v[152:155], v224 offset:35840
	ds_read_b128 v[160:163], v224 offset:36864
	ds_read_b128 v[168:171], v224 offset:37888
	ds_read_b128 v[188:191], v224 offset:38912
	ds_read_b128 v[226:229], v224 offset:39936
	global_load_lds_dwordx4 v[156:157], off
	v_lshl_add_u64 v[156:157], s[20:21], 0, v[208:209]
	s_mov_b32 m0, s34
	s_nop 0
	global_load_lds_dwordx4 v[156:157], off
	s_waitcnt vmcnt(8) lgkmcnt(0)
	s_barrier
	v_mfma_f32_16x16x32_bf16 v[156:159], v[96:99], v[140:143], v[184:187]
	v_mfma_f32_16x16x32_bf16 v[184:187], v[100:103], v[144:147], v[156:159]
	v_mfma_f32_16x16x32_bf16 v[156:159], v[96:99], v[148:151], v[180:183]
	v_mfma_f32_16x16x32_bf16 v[180:183], v[100:103], v[152:155], v[156:159]
	v_mfma_f32_16x16x32_bf16 v[156:159], v[96:99], v[160:163], v[176:179]
	v_mfma_f32_16x16x32_bf16 v[92:95], v[104:107], v[140:143], v[92:95]
	v_mfma_f32_16x16x32_bf16 v[88:91], v[104:107], v[148:151], v[88:91]
	v_mfma_f32_16x16x32_bf16 v[176:179], v[100:103], v[168:171], v[156:159]
	v_mfma_f32_16x16x32_bf16 v[84:87], v[104:107], v[160:163], v[84:87]
	v_mfma_f32_16x16x32_bf16 v[156:159], v[96:99], v[188:191], v[172:175]
	v_mfma_f32_16x16x32_bf16 v[80:83], v[104:107], v[188:191], v[80:83]
	v_mfma_f32_16x16x32_bf16 v[92:95], v[108:111], v[144:147], v[92:95]
	v_mfma_f32_16x16x32_bf16 v[88:91], v[108:111], v[152:155], v[88:91]
	v_mfma_f32_16x16x32_bf16 v[84:87], v[108:111], v[168:171], v[84:87]
	v_mfma_f32_16x16x32_bf16 v[172:175], v[100:103], v[226:229], v[156:159]
	v_mfma_f32_16x16x32_bf16 v[80:83], v[108:111], v[226:229], v[80:83]
	v_mfma_f32_16x16x32_bf16 v[156:159], v[112:115], v[140:143], v[164:167]
	v_mfma_f32_16x16x32_bf16 v[128:131], v[112:115], v[148:151], v[128:131]
	v_mfma_f32_16x16x32_bf16 v[164:167], v[116:119], v[144:147], v[156:159]
	v_mfma_f32_16x16x32_bf16 v[156:159], v[116:119], v[152:155], v[128:131]
	v_mfma_f32_16x16x32_bf16 v[128:131], v[112:115], v[160:163], v[132:135]
	v_mfma_f32_16x16x32_bf16 v[76:79], v[120:123], v[140:143], v[76:79]
	v_mfma_f32_16x16x32_bf16 v[72:75], v[120:123], v[148:151], v[72:75]
	v_mfma_f32_16x16x32_bf16 v[148:151], v[116:119], v[168:171], v[128:131]
	v_mfma_f32_16x16x32_bf16 v[68:71], v[120:123], v[160:163], v[68:71]
	v_mfma_f32_16x16x32_bf16 v[128:131], v[112:115], v[188:191], v[136:139]
	v_mfma_f32_16x16x32_bf16 v[64:67], v[120:123], v[188:191], v[64:67]
	v_mfma_f32_16x16x32_bf16 v[76:79], v[124:127], v[144:147], v[76:79]
	v_mfma_f32_16x16x32_bf16 v[72:75], v[124:127], v[152:155], v[72:75]
	v_mfma_f32_16x16x32_bf16 v[68:71], v[124:127], v[168:171], v[68:71]
	v_mfma_f32_16x16x32_bf16 v[140:143], v[116:119], v[226:229], v[128:131]
	v_mfma_f32_16x16x32_bf16 v[64:67], v[124:127], v[226:229], v[64:67]
	s_barrier
; #define PG8_STAGE(bufoff, gbase, voff) do { _Pragma("unroll") for (int _i = 0; _i < 2; ++_i) \
;         __builtin_amdgcn_global_load_lds((const unsigned*)((const char*)(gbase) + (voff)[_i]), (LAS unsigned*)(lds + (bufoff) + ldsw + _i * 8192), 16, 0, 0); } while (0)
; #define PG8_LDA(dst, b, h) do { _Pragma("unroll") for (int m = 0; m < 4; ++m) _Pragma("unroll") for (int k = 0; k < 2; ++k) dst[m][k] = *(const LAS bf16x8*)(lds + PG8_SA(b, h) + aoff + m * 2048 + k * 1024); } while (0)
; #define PG8_MMA(ai, bj, At, Bt) do { __builtin_amdgcn_s_setprio(1); _Pragma("unroll") for (int m = 0; m < 4; ++m) _Pragma("unroll") for (int n = 0; n < 2; ++n) _Pragma("unroll") for (int k = 0; k < 2; ++k) \
;         acc[ai][bj][m][n] = __builtin_amdgcn_mfma_f32_16x16x32_bf16(Bt[n][k], At[m][k], acc[ai][bj][m][n], 0, 0, 0); __builtin_amdgcn_s_setprio(0); } while (0)
; #define PG8_WAIT_V(n) asm volatile("s_waitcnt vmcnt(" #n ")" ::: "memory")
; #define PG8_WAIT_L(n) asm volatile("s_waitcnt lgkmcnt(" #n ")" ::: "memory")
; #define PG8_BAR __builtin_amdgcn_s_barrier()
; #define PG8_SCHED __builtin_amdgcn_sched_barrier(0)
; template <class Epi, bool PERMA = false, bool DUAL = false, bool ALIGN_EPI = true, bool SP2 = true>
; __device__ __forceinline__ void gemm_phase(LAS unsigned char* lds, const Gemm g, const StaticOrder& S, const Epi& E) {
;     ...
;             PG8_LDA(At, 1, 1); PG8_STAGE(PG8_SB(1, 0), b3, voffB); PG8_STAGE(PG8_SB(1, 1), b3 + hstepB, voffB); PG8_STAGE(PG8_SA(1, 0), a3, voffA);
;             PG8_WAIT_V(8); PG8_WAIT_L(0); PG8_BAR; PG8_MMA(1, 0, At, B0); PG8_MMA(1, 1, At, B1); PG8_BAR; PG8_SCHED;
;     __device__ __forceinline__ void operator()(const f32x4 (&acc)[2][2][4][2], const Unit& u, int wr, int wc, int fr, int fq) const {
;     ...
;         for (int n = 0; n < 2; ++n) { const float* wp = cw + ch0 + 4 * n;
;             wgt[n][0] = *(const f32x4*)wp; wgt[n][1] = *(const f32x4*)(wp + 2 * DFF); wgt[n][2] = *(const f32x4*)(wp + 4 * DFF); wgt[n][3] = *(const f32x4*)(cb + ch0 + 4 * n);
;             wgt[n][4] = *(const f32x4*)(wp + DFF); wgt[n][5] = *(const f32x4*)(wp + 3 * DFF); wgt[n][6] = *(const f32x4*)(wp + 5 * DFF); wgt[n][7] = *(const f32x4*)(cb + DFF + ch0 + 4 * n); }
	s_add_i32 s20, s52, s28
	v_lshl_add_u64 v[220:221], v[220:221], 0, s[56:57]
	s_mov_b32 m0, s20
	ds_read_b128 v[128:131], v224 offset:49152
	ds_read_b128 v[132:135], v224 offset:50176
	ds_read_b128 v[136:139], v224 offset:51200
	ds_read_b128 v[144:147], v224 offset:52224
	ds_read_b128 v[152:155], v224 offset:53248
	ds_read_b128 v[160:163], v224 offset:54272
	ds_read_b128 v[168:171], v224 offset:55296
	ds_read_b128 v[188:191], v224 offset:56320
	global_load_lds_dwordx4 v[220:221], off
	s_add_i32 m0, s20, 0x2000
	s_add_u32 s20, s24, 0x80080
	v_lshl_add_u64 v[220:221], v[238:239], 0, s[56:57]
	s_addc_u32 s21, s25, 0
	s_add_i32 s24, s53, s28
	global_load_lds_dwordx4 v[220:221], off
	v_lshl_add_u64 v[220:221], s[20:21], 0, v[210:211]
	s_mov_b32 m0, s24
	s_nop 0
	global_load_lds_dwordx4 v[220:221], off
	v_lshl_add_u64 v[220:221], s[20:21], 0, v[206:207]
	s_add_i32 m0, s24, 0x2000
	s_nop 0
	global_load_lds_dwordx4 v[220:221], off
	v_lshl_add_u64 v[220:221], v[240:241], 0, s[56:57]
	s_mov_b32 m0, s35
	s_nop 0
	global_load_lds_dwordx4 v[220:221], off
	v_lshl_add_u64 v[220:221], v[242:243], 0, s[56:57]
	s_mov_b32 m0, s36
	s_nop 0
	global_load_lds_dwordx4 v[220:221], off
	s_waitcnt vmcnt(8) lgkmcnt(0)
	s_barrier
	v_mfma_f32_16x16x32_bf16 v[60:63], v[96:99], v[128:131], v[60:63]
	v_mfma_f32_16x16x32_bf16 v[28:31], v[104:107], v[128:131], v[28:31]
	v_mfma_f32_16x16x32_bf16 v[56:59], v[96:99], v[136:139], v[56:59]
	v_mfma_f32_16x16x32_bf16 v[24:27], v[104:107], v[136:139], v[24:27]
	v_mfma_f32_16x16x32_bf16 v[52:55], v[96:99], v[152:155], v[52:55]
	v_mfma_f32_16x16x32_bf16 v[20:23], v[104:107], v[152:155], v[20:23]
	v_mfma_f32_16x16x32_bf16 v[48:51], v[96:99], v[168:171], v[48:51]
	v_mfma_f32_16x16x32_bf16 v[16:19], v[104:107], v[168:171], v[16:19]
	v_mfma_f32_16x16x32_bf16 v[60:63], v[100:103], v[132:135], v[60:63]
	v_mfma_f32_16x16x32_bf16 v[28:31], v[108:111], v[132:135], v[28:31]
	v_mfma_f32_16x16x32_bf16 v[56:59], v[100:103], v[144:147], v[56:59]
	v_mfma_f32_16x16x32_bf16 v[24:27], v[108:111], v[144:147], v[24:27]
	v_mfma_f32_16x16x32_bf16 v[52:55], v[100:103], v[160:163], v[52:55]
	v_mfma_f32_16x16x32_bf16 v[20:23], v[108:111], v[160:163], v[20:23]
	v_mfma_f32_16x16x32_bf16 v[48:51], v[100:103], v[188:191], v[48:51]
	v_mfma_f32_16x16x32_bf16 v[16:19], v[108:111], v[188:191], v[16:19]
	v_mfma_f32_16x16x32_bf16 v[44:47], v[112:115], v[128:131], v[44:47]
	v_mfma_f32_16x16x32_bf16 v[12:15], v[120:123], v[128:131], v[12:15]
	v_mfma_f32_16x16x32_bf16 v[40:43], v[112:115], v[136:139], v[40:43]
	v_mfma_f32_16x16x32_bf16 v[8:11], v[120:123], v[136:139], v[8:11]
	v_mfma_f32_16x16x32_bf16 v[36:39], v[112:115], v[152:155], v[36:39]
	v_mfma_f32_16x16x32_bf16 v[4:7], v[120:123], v[152:155], v[4:7]
	v_mfma_f32_16x16x32_bf16 v[32:35], v[112:115], v[168:171], v[32:35]
	v_mfma_f32_16x16x32_bf16 v[0:3], v[120:123], v[168:171], v[0:3]
	v_mfma_f32_16x16x32_bf16 v[44:47], v[116:119], v[132:135], v[44:47]
	v_mfma_f32_16x16x32_bf16 v[12:15], v[124:127], v[132:135], v[12:15]
	v_mfma_f32_16x16x32_bf16 v[40:43], v[116:119], v[144:147], v[40:43]
	v_mfma_f32_16x16x32_bf16 v[8:11], v[124:127], v[144:147], v[8:11]
	v_mfma_f32_16x16x32_bf16 v[36:39], v[116:119], v[160:163], v[36:39]
	v_mfma_f32_16x16x32_bf16 v[4:7], v[124:127], v[160:163], v[4:7]
	v_mfma_f32_16x16x32_bf16 v[32:35], v[116:119], v[188:191], v[32:35]
	v_mfma_f32_16x16x32_bf16 v[0:3], v[124:127], v[188:191], v[0:3]
	s_barrier
	s_add_i32 s51, s51, 2
	s_add_u32 s49, s49, 0x100
	s_addc_u32 s50, s50, 0
	s_cmp_gt_u32 s51, 29
	s_mov_b64 s[20:21], s[22:23]
	s_cbranch_scc0 .LBB0_528
	v_lshl_or_b32 v220, s38, 7, v214
	v_ashrrev_i32_e32 v221, 31, v220
	v_lshlrev_b64 v[96:97], 2, v[220:221]
	v_lshl_add_u64 v[112:113], s[2:3], 0, v[96:97]
	v_add_co_u32_e32 v102, vcc, s72, v112
	s_mov_b64 s[20:21], 0xb000
	s_nop 0
	v_addc_co_u32_e32 v103, vcc, 0, v113, vcc
	s_mov_b32 s13, 0x16000
	v_lshl_add_u64 v[100:101], v[112:113], 0, s[20:21]
	s_mov_b64 s[20:21], 0x16000
	v_add_co_u32_e32 v106, vcc, s13, v112
	s_nop 0
	v_lshl_add_u64 v[104:105], v[112:113], 0, s[20:21]
	v_addc_co_u32_e32 v107, vcc, 0, v113, vcc
	v_lshl_add_u64 v[114:115], s[6:7], 0, v[96:97]
	v_lshl_add_u64 v[188:189], s[10:11], 0, v[96:97]
	global_load_dwordx4 v[96:99], v[112:113], off offset:16
	global_load_dwordx4 v[128:131], v[112:113], off
	global_load_dwordx4 v[132:135], v[102:103], off
	s_nop 0
	global_load_dwordx4 v[100:103], v[100:101], off offset:16
	s_nop 0
	global_load_dwordx4 v[136:139], v[106:107], off
	s_nop 0
	global_load_dwordx4 v[104:107], v[104:105], off offset:16
	s_nop 0
	global_load_dwordx4 v[108:111], v[114:115], off offset:16
	global_load_dwordx4 v[144:147], v[114:115], off
	s_movk_i32 s13, 0x5000
	v_add_co_u32_e32 v116, vcc, s13, v112
	s_mov_b64 s[20:21], 0x5800
	s_nop 0
	v_addc_co_u32_e32 v117, vcc, 0, v113, vcc
	s_mov_b32 s13, 0x10000
	v_lshl_add_u64 v[114:115], v[112:113], 0, s[20:21]
	s_mov_b64 s[20:21], 0x10800
	v_add_co_u32_e32 v120, vcc, s13, v112
	global_load_dwordx4 v[160:163], v[116:117], off offset:2048
	s_nop 0
	global_load_dwordx4 v[116:119], v[114:115], off offset:16
	v_lshl_add_u64 v[114:115], v[112:113], 0, s[20:21]
	v_addc_co_u32_e32 v121, vcc, 0, v113, vcc
	s_mov_b64 s[20:21], 0x1b800
	s_mov_b32 s13, 0x1b000
	global_load_dwordx4 v[168:171], v[120:121], off offset:2048
	s_nop 0
	global_load_dwordx4 v[120:123], v[114:115], off offset:16
	v_lshl_add_u64 v[114:115], v[112:113], 0, s[20:21]
	v_add_co_u32_e32 v112, vcc, s13, v112
	s_nop 0
	v_addc_co_u32_e32 v113, vcc, 0, v113, vcc
	global_load_dwordx4 v[152:155], v[112:113], off offset:2048
	s_nop 0
	global_load_dwordx4 v[112:115], v[114:115], off offset:16
	s_nop 0
	global_load_dwordx4 v[124:127], v[188:189], off offset:16
	s_nop 0
	global_load_dwordx4 v[188:191], v[188:189], off
	s_and_b64 vcc, exec, s[4:5]
	s_cbranch_vccz .LBB0_531
	s_barrier

; #define PG8_STAGE(bufoff, gbase, voff) do { _Pragma("unroll") for (int _i = 0; _i < 2; ++_i) \
;         __builtin_amdgcn_global_load_lds((const unsigned*)((const char*)(gbase) + (voff)[_i]), (LAS unsigned*)(lds + (bufoff) + ldsw + _i * 8192), 16, 0, 0); } while (0)
; #define PG8_LDA(dst, b, h) do { _Pragma("unroll") for (int m = 0; m < 4; ++m) _Pragma("unroll") for (int k = 0; k < 2; ++k) dst[m][k] = *(const LAS bf16x8*)(lds + PG8_SA(b, h) + aoff + m * 2048 + k * 1024); } while (0)
; #define PG8_LDB(dst, b, h) do { _Pragma("unroll") for (int n = 0; n < 2; ++n) _Pragma("unroll") for (int k = 0; k < 2; ++k) dst[n][k] = *(const LAS bf16x8*)(lds + PG8_SB(b, h) + boff + n * 2048 + k * 1024); } while (0)
; #define PG8_MMA(ai, bj, At, Bt) do { __builtin_amdgcn_s_setprio(1); _Pragma("unroll") for (int m = 0; m < 4; ++m) _Pragma("unroll") for (int n = 0; n < 2; ++n) _Pragma("unroll") for (int k = 0; k < 2; ++k) \
;         acc[ai][bj][m][n] = __builtin_amdgcn_mfma_f32_16x16x32_bf16(Bt[n][k], At[m][k], acc[ai][bj][m][n], 0, 0, 0); __builtin_amdgcn_s_setprio(0); } while (0)
; #define PG8_WAIT_V(n) asm volatile("s_waitcnt vmcnt(" #n ")" ::: "memory")
; #define PG8_WAIT_L(n) asm volatile("s_waitcnt lgkmcnt(" #n ")" ::: "memory")
; #define PG8_BAR __builtin_amdgcn_s_barrier()
; #define PG8_SCHED __builtin_amdgcn_sched_barrier(0)
; template <class Epi, bool PERMA = false, bool DUAL = false, bool ALIGN_EPI = true, bool SP2 = true>
; __device__ __forceinline__ void gemm_phase(LAS unsigned char* lds, const Gemm g, const StaticOrder& S, const Epi& E) {
;     ...
;             const bool last = (t == nt - 2);
;             const char* a1 = cA + (size_t)(t + 1) * kstep;
;             const char* a2 = last ? nA : cA + (size_t)(t + 2) * kstep; const char* b2 = last ? nB : cB + (size_t)(t + 2) * kstep;
;             const char* a3 = a2 + kstep; const char* b3 = b2 + kstep;
;             if constexpr (SP2) {
;             PG8_LDB(B0, 0, 0); PG8_LDB(B1, 0, 1); PG8_SCHED; PG8_LDA(At, 0, 0); PG8_STAGE(PG8_SA(1, 1), a1 + hstepA, voffA);
;             PG8_WAIT_V(8); PG8_WAIT_L(0); PG8_BAR; PG8_MMA(0, 0, At, B0); PG8_MMA(0, 1, At, B1); PG8_BAR; PG8_SCHED;
;             PG8_LDA(At, 0, 1); PG8_STAGE(PG8_SB(0, 0), b2, voffB); PG8_STAGE(PG8_SB(0, 1), b2 + hstepB, voffB); PG8_STAGE(PG8_SA(0, 0), a2, voffA);
.LBB0_675:
	s_add_u32 s14, s12, 0x100
	s_addc_u32 s15, s13, 0
	s_add_i32 s36, 0, 0x10000
	s_cmpk_eq_i32 s33, 0x54
	s_cselect_b32 s19, s1, s15
	s_cselect_b32 s18, s0, s14
	s_cselect_b32 s17, s7, s11
	s_cselect_b32 s16, s6, s9
	s_add_i32 s37, 0, 0x14000
	v_add_u32_e32 v116, s36, v193
	v_add_u32_e32 v156, s37, v193
	ds_read_b128 v[104:107], v116
	ds_read_b128 v[108:111], v116 offset:1024
	ds_read_b128 v[112:115], v116 offset:2048
	ds_read_b128 v[116:119], v116 offset:3072
	ds_read_b128 v[144:147], v156
	ds_read_b128 v[148:151], v156 offset:1024
	ds_read_b128 v[152:155], v156 offset:2048
	ds_read_b128 v[156:159], v156 offset:3072
	v_lshl_add_u64 v[206:207], s[12:13], 0, v[180:181]
	s_add_i32 m0, s21, 0xc000
	ds_read_b128 v[184:187], v212
	ds_read_b128 v[188:191], v212 offset:1024
	ds_read_b128 v[214:217], v212 offset:2048
	ds_read_b128 v[218:221], v212 offset:3072
	ds_read_b128 v[222:225], v212 offset:4096
	ds_read_b128 v[226:229], v212 offset:5120
	ds_read_b128 v[238:241], v212 offset:6144
	ds_read_b128 v[242:245], v212 offset:7168
	global_load_lds_dwordx4 v[206:207], off
	v_lshl_add_u64 v[206:207], s[12:13], 0, v[182:183]
	s_add_i32 m0, s21, 0xe000
	s_nop 0
	global_load_lds_dwordx4 v[206:207], off
	s_waitcnt vmcnt(8) lgkmcnt(0)
	s_barrier
	v_mfma_f32_16x16x32_bf16 v[140:143], v[104:107], v[184:187], v[140:143]
	v_mfma_f32_16x16x32_bf16 v[136:139], v[112:115], v[184:187], v[136:139]
	v_mfma_f32_16x16x32_bf16 v[124:127], v[104:107], v[214:217], v[124:127]
	v_mfma_f32_16x16x32_bf16 v[120:123], v[112:115], v[214:217], v[120:123]
	v_mfma_f32_16x16x32_bf16 v[92:95], v[104:107], v[222:225], v[92:95]
	v_mfma_f32_16x16x32_bf16 v[88:91], v[112:115], v[222:225], v[88:91]
	v_mfma_f32_16x16x32_bf16 v[76:79], v[104:107], v[238:241], v[76:79]
	v_mfma_f32_16x16x32_bf16 v[72:75], v[112:115], v[238:241], v[72:75]
	v_mfma_f32_16x16x32_bf16 v[140:143], v[108:111], v[188:191], v[140:143]
	v_mfma_f32_16x16x32_bf16 v[136:139], v[116:119], v[188:191], v[136:139]
	v_mfma_f32_16x16x32_bf16 v[124:127], v[108:111], v[218:221], v[124:127]
	v_mfma_f32_16x16x32_bf16 v[120:123], v[116:119], v[218:221], v[120:123]
	v_mfma_f32_16x16x32_bf16 v[92:95], v[108:111], v[226:229], v[92:95]
	v_mfma_f32_16x16x32_bf16 v[88:91], v[116:119], v[226:229], v[88:91]
	v_mfma_f32_16x16x32_bf16 v[76:79], v[108:111], v[242:245], v[76:79]
	v_mfma_f32_16x16x32_bf16 v[72:75], v[116:119], v[242:245], v[72:75]
	v_mfma_f32_16x16x32_bf16 v[132:135], v[144:147], v[184:187], v[132:135]
	v_mfma_f32_16x16x32_bf16 v[128:131], v[152:155], v[184:187], v[128:131]
	v_mfma_f32_16x16x32_bf16 v[100:103], v[144:147], v[214:217], v[100:103]
	v_mfma_f32_16x16x32_bf16 v[96:99], v[152:155], v[214:217], v[96:99]
	v_mfma_f32_16x16x32_bf16 v[84:87], v[144:147], v[222:225], v[84:87]
	v_mfma_f32_16x16x32_bf16 v[80:83], v[152:155], v[222:225], v[80:83]
	v_mfma_f32_16x16x32_bf16 v[68:71], v[144:147], v[238:241], v[68:71]
	v_mfma_f32_16x16x32_bf16 v[64:67], v[152:155], v[238:241], v[64:67]
	v_mfma_f32_16x16x32_bf16 v[132:135], v[148:151], v[188:191], v[132:135]
	v_mfma_f32_16x16x32_bf16 v[128:131], v[156:159], v[188:191], v[128:131]
	v_mfma_f32_16x16x32_bf16 v[100:103], v[148:151], v[218:221], v[100:103]
	v_mfma_f32_16x16x32_bf16 v[96:99], v[156:159], v[218:221], v[96:99]
	v_mfma_f32_16x16x32_bf16 v[84:87], v[148:151], v[226:229], v[84:87]
	v_mfma_f32_16x16x32_bf16 v[80:83], v[156:159], v[226:229], v[80:83]
	v_mfma_f32_16x16x32_bf16 v[68:71], v[148:151], v[242:245], v[68:71]
	v_mfma_f32_16x16x32_bf16 v[64:67], v[156:159], v[242:245], v[64:67]
	s_barrier
	s_add_i32 s12, s36, s20
	v_lshl_add_u64 v[206:207], s[16:17], 0, v[164:165]
	s_mov_b32 m0, s12
	ds_read_b128 v[184:187], v212 offset:16384
	ds_read_b128 v[188:191], v212 offset:17408
	ds_read_b128 v[214:217], v212 offset:18432
	ds_read_b128 v[218:221], v212 offset:19456
	ds_read_b128 v[222:225], v212 offset:20480
	ds_read_b128 v[226:229], v212 offset:21504
	ds_read_b128 v[238:241], v212 offset:22528
	ds_read_b128 v[242:245], v212 offset:23552
	global_load_lds_dwordx4 v[206:207], off
	s_add_i32 m0, s12, 0x2000
	s_add_u32 s12, s16, 0x160000
	v_lshl_add_u64 v[246:247], s[16:17], 0, v[160:161]
	s_addc_u32 s13, s17, 0
	s_add_i32 s36, s37, s20
	global_load_lds_dwordx4 v[246:247], off
	v_lshl_add_u64 v[248:249], s[12:13], 0, v[164:165]
	s_mov_b32 m0, s36
	v_lshl_add_u64 v[194:195], s[18:19], 0, v[162:163]
	global_load_lds_dwordx4 v[248:249], off
	v_lshl_add_u64 v[248:249], s[12:13], 0, v[160:161]
	s_add_i32 m0, s36, 0x2000
	s_nop 0
	global_load_lds_dwordx4 v[248:249], off
	v_lshl_add_u64 v[248:249], s[18:19], 0, v[166:167]
	s_mov_b32 m0, s21
	s_nop 0
	global_load_lds_dwordx4 v[248:249], off
	s_mov_b32 m0, s22
	s_nop 0
	global_load_lds_dwordx4 v[194:195], off
	s_waitcnt vmcnt(8) lgkmcnt(0)
	s_barrier
; #define PG8_STAGE(bufoff, gbase, voff) do { _Pragma("unroll") for (int _i = 0; _i < 2; ++_i) \
;         __builtin_amdgcn_global_load_lds((const unsigned*)((const char*)(gbase) + (voff)[_i]), (LAS unsigned*)(lds + (bufoff) + ldsw + _i * 8192), 16, 0, 0); } while (0)
; #define PG8_LDA(dst, b, h) do { _Pragma("unroll") for (int m = 0; m < 4; ++m) _Pragma("unroll") for (int k = 0; k < 2; ++k) dst[m][k] = *(const LAS bf16x8*)(lds + PG8_SA(b, h) + aoff + m * 2048 + k * 1024); } while (0)
; #define PG8_LDB(dst, b, h) do { _Pragma("unroll") for (int n = 0; n < 2; ++n) _Pragma("unroll") for (int k = 0; k < 2; ++k) dst[n][k] = *(const LAS bf16x8*)(lds + PG8_SB(b, h) + boff + n * 2048 + k * 1024); } while (0)
; #define PG8_MMA(ai, bj, At, Bt) do { __builtin_amdgcn_s_setprio(1); _Pragma("unroll") for (int m = 0; m < 4; ++m) _Pragma("unroll") for (int n = 0; n < 2; ++n) _Pragma("unroll") for (int k = 0; k < 2; ++k) \
;         acc[ai][bj][m][n] = __builtin_amdgcn_mfma_f32_16x16x32_bf16(Bt[n][k], At[m][k], acc[ai][bj][m][n], 0, 0, 0); __builtin_amdgcn_s_setprio(0); } while (0)
; #define PG8_WAIT_V(n) asm volatile("s_waitcnt vmcnt(" #n ")" ::: "memory")
; #define PG8_WAIT_L(n) asm volatile("s_waitcnt lgkmcnt(" #n ")" ::: "memory")
; #define PG8_BAR __builtin_amdgcn_s_barrier()
; #define PG8_SCHED __builtin_amdgcn_sched_barrier(0)
; template <class Epi, bool PERMA = false, bool DUAL = false, bool ALIGN_EPI = true, bool SP2 = true>
; __device__ __forceinline__ void gemm_phase(LAS unsigned char* lds, const Gemm g, const StaticOrder& S, const Epi& E) {
;     ...
;             PG8_WAIT_V(8); PG8_WAIT_L(0); PG8_BAR; PG8_MMA(1, 0, At, B0); PG8_MMA(1, 1, At, B1); PG8_BAR; PG8_SCHED;
;             PG8_LDB(B0, 1, 0); PG8_LDB(B1, 1, 1); PG8_SCHED; PG8_LDA(At, 1, 0); PG8_STAGE(PG8_SA(0, 1), a2 + hstepA, voffA);
;             PG8_WAIT_V(8); PG8_WAIT_L(0); PG8_BAR; PG8_MMA(0, 0, At, B0); PG8_MMA(0, 1, At, B1); PG8_BAR; PG8_SCHED;
	v_mfma_f32_16x16x32_bf16 v[60:63], v[104:107], v[184:187], v[60:63]
	v_mfma_f32_16x16x32_bf16 v[56:59], v[112:115], v[184:187], v[56:59]
	v_mfma_f32_16x16x32_bf16 v[44:47], v[104:107], v[214:217], v[44:47]
	v_mfma_f32_16x16x32_bf16 v[40:43], v[112:115], v[214:217], v[40:43]
	v_mfma_f32_16x16x32_bf16 v[28:31], v[104:107], v[222:225], v[28:31]
	v_mfma_f32_16x16x32_bf16 v[24:27], v[112:115], v[222:225], v[24:27]
	v_mfma_f32_16x16x32_bf16 v[12:15], v[104:107], v[238:241], v[12:15]
	v_mfma_f32_16x16x32_bf16 v[8:11], v[112:115], v[238:241], v[8:11]
	v_mfma_f32_16x16x32_bf16 v[60:63], v[108:111], v[188:191], v[60:63]
	v_mfma_f32_16x16x32_bf16 v[56:59], v[116:119], v[188:191], v[56:59]
	v_mfma_f32_16x16x32_bf16 v[44:47], v[108:111], v[218:221], v[44:47]
	v_mfma_f32_16x16x32_bf16 v[40:43], v[116:119], v[218:221], v[40:43]
	v_mfma_f32_16x16x32_bf16 v[28:31], v[108:111], v[226:229], v[28:31]
	v_mfma_f32_16x16x32_bf16 v[24:27], v[116:119], v[226:229], v[24:27]
	v_mfma_f32_16x16x32_bf16 v[12:15], v[108:111], v[242:245], v[12:15]
	v_mfma_f32_16x16x32_bf16 v[8:11], v[116:119], v[242:245], v[8:11]
	v_mfma_f32_16x16x32_bf16 v[52:55], v[144:147], v[184:187], v[52:55]
	v_mfma_f32_16x16x32_bf16 v[48:51], v[152:155], v[184:187], v[48:51]
	v_mfma_f32_16x16x32_bf16 v[36:39], v[144:147], v[214:217], v[36:39]
	v_mfma_f32_16x16x32_bf16 v[32:35], v[152:155], v[214:217], v[32:35]
	v_mfma_f32_16x16x32_bf16 v[20:23], v[144:147], v[222:225], v[20:23]
	v_mfma_f32_16x16x32_bf16 v[16:19], v[152:155], v[222:225], v[16:19]
	v_mfma_f32_16x16x32_bf16 v[4:7], v[144:147], v[238:241], v[4:7]
	v_mfma_f32_16x16x32_bf16 v[0:3], v[152:155], v[238:241], v[0:3]
	v_mfma_f32_16x16x32_bf16 v[52:55], v[148:151], v[188:191], v[52:55]
	v_mfma_f32_16x16x32_bf16 v[48:51], v[156:159], v[188:191], v[48:51]
	v_mfma_f32_16x16x32_bf16 v[36:39], v[148:151], v[218:221], v[36:39]
	v_mfma_f32_16x16x32_bf16 v[32:35], v[156:159], v[218:221], v[32:35]
	v_mfma_f32_16x16x32_bf16 v[20:23], v[148:151], v[226:229], v[20:23]
	v_mfma_f32_16x16x32_bf16 v[16:19], v[156:159], v[226:229], v[16:19]
	v_mfma_f32_16x16x32_bf16 v[4:7], v[148:151], v[242:245], v[4:7]
	v_mfma_f32_16x16x32_bf16 v[0:3], v[156:159], v[242:245], v[0:3]
	s_barrier
	s_add_i32 s36, 0, 0x18000
	s_add_i32 s37, 0, 0x1c000
	v_add_u32_e32 v116, s36, v193
	v_add_u32_e32 v156, s37, v193
	ds_read_b128 v[104:107], v116
	ds_read_b128 v[108:111], v116 offset:1024
	ds_read_b128 v[112:115], v116 offset:2048
	ds_read_b128 v[116:119], v116 offset:3072
	ds_read_b128 v[144:147], v156
	ds_read_b128 v[148:151], v156 offset:1024
	ds_read_b128 v[152:155], v156 offset:2048
	ds_read_b128 v[156:159], v156 offset:3072
	s_add_u32 s12, s18, 0x160000
	s_addc_u32 s13, s19, 0
	s_mov_b32 m0, s23
	v_lshl_add_u64 v[196:197], s[12:13], 0, v[166:167]
	ds_read_b128 v[184:187], v212 offset:32768
	ds_read_b128 v[188:191], v212 offset:33792
	ds_read_b128 v[214:217], v212 offset:34816
	ds_read_b128 v[218:221], v212 offset:35840
	ds_read_b128 v[222:225], v212 offset:36864
	ds_read_b128 v[226:229], v212 offset:37888
	ds_read_b128 v[238:241], v212 offset:38912
	ds_read_b128 v[242:245], v212 offset:39936
	global_load_lds_dwordx4 v[196:197], off
	v_lshl_add_u64 v[196:197], s[12:13], 0, v[162:163]
	s_mov_b32 m0, s24
	s_nop 0
	global_load_lds_dwordx4 v[196:197], off
	s_waitcnt vmcnt(8) lgkmcnt(0)
	s_barrier
	v_mfma_f32_16x16x32_bf16 v[140:143], v[104:107], v[184:187], v[140:143]
	v_mfma_f32_16x16x32_bf16 v[136:139], v[112:115], v[184:187], v[136:139]
	v_mfma_f32_16x16x32_bf16 v[124:127], v[104:107], v[214:217], v[124:127]
	v_mfma_f32_16x16x32_bf16 v[120:123], v[112:115], v[214:217], v[120:123]
	v_mfma_f32_16x16x32_bf16 v[92:95], v[104:107], v[222:225], v[92:95]
	v_mfma_f32_16x16x32_bf16 v[88:91], v[112:115], v[222:225], v[88:91]
	v_mfma_f32_16x16x32_bf16 v[76:79], v[104:107], v[238:241], v[76:79]
	v_mfma_f32_16x16x32_bf16 v[72:75], v[112:115], v[238:241], v[72:75]
	v_mfma_f32_16x16x32_bf16 v[140:143], v[108:111], v[188:191], v[140:143]
	v_mfma_f32_16x16x32_bf16 v[136:139], v[116:119], v[188:191], v[136:139]
	v_mfma_f32_16x16x32_bf16 v[124:127], v[108:111], v[218:221], v[124:127]
	v_mfma_f32_16x16x32_bf16 v[120:123], v[116:119], v[218:221], v[120:123]
	v_mfma_f32_16x16x32_bf16 v[92:95], v[108:111], v[226:229], v[92:95]
	v_mfma_f32_16x16x32_bf16 v[88:91], v[116:119], v[226:229], v[88:91]
	v_mfma_f32_16x16x32_bf16 v[76:79], v[108:111], v[242:245], v[76:79]
	v_mfma_f32_16x16x32_bf16 v[72:75], v[116:119], v[242:245], v[72:75]
	v_mfma_f32_16x16x32_bf16 v[132:135], v[144:147], v[184:187], v[132:135]
	v_mfma_f32_16x16x32_bf16 v[128:131], v[152:155], v[184:187], v[128:131]
	v_mfma_f32_16x16x32_bf16 v[100:103], v[144:147], v[214:217], v[100:103]
	v_mfma_f32_16x16x32_bf16 v[96:99], v[152:155], v[214:217], v[96:99]
	v_mfma_f32_16x16x32_bf16 v[84:87], v[144:147], v[222:225], v[84:87]
	v_mfma_f32_16x16x32_bf16 v[80:83], v[152:155], v[222:225], v[80:83]
	v_mfma_f32_16x16x32_bf16 v[68:71], v[144:147], v[238:241], v[68:71]
	v_mfma_f32_16x16x32_bf16 v[64:67], v[152:155], v[238:241], v[64:67]
	v_mfma_f32_16x16x32_bf16 v[132:135], v[148:151], v[188:191], v[132:135]
	v_mfma_f32_16x16x32_bf16 v[128:131], v[156:159], v[188:191], v[128:131]
	v_mfma_f32_16x16x32_bf16 v[100:103], v[148:151], v[218:221], v[100:103]
	v_mfma_f32_16x16x32_bf16 v[96:99], v[156:159], v[218:221], v[96:99]
	v_mfma_f32_16x16x32_bf16 v[84:87], v[148:151], v[226:229], v[84:87]
	v_mfma_f32_16x16x32_bf16 v[80:83], v[156:159], v[226:229], v[80:83]
	v_mfma_f32_16x16x32_bf16 v[68:71], v[148:151], v[242:245], v[68:71]
	v_mfma_f32_16x16x32_bf16 v[64:67], v[156:159], v[242:245], v[64:67]
	s_barrier
; #define PG8_STAGE(bufoff, gbase, voff) do { _Pragma("unroll") for (int _i = 0; _i < 2; ++_i) \
;         __builtin_amdgcn_global_load_lds((const unsigned*)((const char*)(gbase) + (voff)[_i]), (LAS unsigned*)(lds + (bufoff) + ldsw + _i * 8192), 16, 0, 0); } while (0)
; #define PG8_LDA(dst, b, h) do { _Pragma("unroll") for (int m = 0; m < 4; ++m) _Pragma("unroll") for (int k = 0; k < 2; ++k) dst[m][k] = *(const LAS bf16x8*)(lds + PG8_SA(b, h) + aoff + m * 2048 + k * 1024); } while (0)
; #define PG8_MMA(ai, bj, At, Bt) do { __builtin_amdgcn_s_setprio(1); _Pragma("unroll") for (int m = 0; m < 4; ++m) _Pragma("unroll") for (int n = 0; n < 2; ++n) _Pragma("unroll") for (int k = 0; k < 2; ++k) \
;         acc[ai][bj][m][n] = __builtin_amdgcn_mfma_f32_16x16x32_bf16(Bt[n][k], At[m][k], acc[ai][bj][m][n], 0, 0, 0); __builtin_amdgcn_s_setprio(0); } while (0)
; #define PG8_WAIT_V(n) asm volatile("s_waitcnt vmcnt(" #n ")" ::: "memory")
; #define PG8_WAIT_L(n) asm volatile("s_waitcnt lgkmcnt(" #n ")" ::: "memory")
; #define PG8_BAR __builtin_amdgcn_s_barrier()
; #define PG8_SCHED __builtin_amdgcn_sched_barrier(0)
; template <class Epi, bool PERMA = false, bool DUAL = false, bool ALIGN_EPI = true, bool SP2 = true>
; __device__ __forceinline__ void gemm_phase(LAS unsigned char* lds, const Gemm g, const StaticOrder& S, const Epi& E) {
;     ...
;             PG8_LDA(At, 1, 1); PG8_STAGE(PG8_SB(1, 0), b3, voffB); PG8_STAGE(PG8_SB(1, 1), b3 + hstepB, voffB); PG8_STAGE(PG8_SA(1, 0), a3, voffA);
;             PG8_WAIT_V(8); PG8_WAIT_L(0); PG8_BAR; PG8_MMA(1, 0, At, B0); PG8_MMA(1, 1, At, B1); PG8_BAR; PG8_SCHED;
;     ...
;         if constexpr (ALIGN_EPI) { if (wr == 0) PG8_BAR; }
	s_add_i32 s12, s36, s20
	v_lshl_add_u64 v[196:197], v[206:207], 0, s[38:39]
	s_mov_b32 m0, s12
	ds_read_b128 v[184:187], v212 offset:49152
	ds_read_b128 v[188:191], v212 offset:50176
	ds_read_b128 v[214:217], v212 offset:51200
	ds_read_b128 v[218:221], v212 offset:52224
	ds_read_b128 v[222:225], v212 offset:53248
	ds_read_b128 v[226:229], v212 offset:54272
	ds_read_b128 v[238:241], v212 offset:55296
	ds_read_b128 v[242:245], v212 offset:56320
	global_load_lds_dwordx4 v[196:197], off
	s_add_i32 m0, s12, 0x2000
	s_add_u32 s12, s16, 0x160080
	v_lshl_add_u64 v[196:197], v[246:247], 0, s[38:39]
	s_addc_u32 s13, s17, 0
	s_add_i32 s16, s37, s20
	global_load_lds_dwordx4 v[196:197], off
	v_lshl_add_u64 v[196:197], s[12:13], 0, v[164:165]
	s_mov_b32 m0, s16
	v_lshl_add_u64 v[194:195], v[194:195], 0, s[38:39]
	global_load_lds_dwordx4 v[196:197], off
	v_lshl_add_u64 v[196:197], s[12:13], 0, v[160:161]
	s_add_i32 m0, s16, 0x2000
	s_nop 0
	global_load_lds_dwordx4 v[196:197], off
	v_lshl_add_u64 v[196:197], v[248:249], 0, s[38:39]
	s_mov_b32 m0, s29
	s_nop 0
	global_load_lds_dwordx4 v[196:197], off
	s_mov_b32 m0, s30
	s_nop 0
	global_load_lds_dwordx4 v[194:195], off
	s_waitcnt vmcnt(8) lgkmcnt(0)
	s_barrier
	v_mfma_f32_16x16x32_bf16 v[60:63], v[104:107], v[184:187], v[60:63]
	v_mfma_f32_16x16x32_bf16 v[56:59], v[112:115], v[184:187], v[56:59]
	v_mfma_f32_16x16x32_bf16 v[44:47], v[104:107], v[214:217], v[44:47]
	v_mfma_f32_16x16x32_bf16 v[40:43], v[112:115], v[214:217], v[40:43]
	v_mfma_f32_16x16x32_bf16 v[28:31], v[104:107], v[222:225], v[28:31]
	v_mfma_f32_16x16x32_bf16 v[24:27], v[112:115], v[222:225], v[24:27]
	v_mfma_f32_16x16x32_bf16 v[12:15], v[104:107], v[238:241], v[12:15]
	v_mfma_f32_16x16x32_bf16 v[8:11], v[112:115], v[238:241], v[8:11]
	v_mfma_f32_16x16x32_bf16 v[60:63], v[108:111], v[188:191], v[60:63]
	v_mfma_f32_16x16x32_bf16 v[56:59], v[116:119], v[188:191], v[56:59]
	v_mfma_f32_16x16x32_bf16 v[44:47], v[108:111], v[218:221], v[44:47]
	v_mfma_f32_16x16x32_bf16 v[40:43], v[116:119], v[218:221], v[40:43]
	v_mfma_f32_16x16x32_bf16 v[28:31], v[108:111], v[226:229], v[28:31]
	v_mfma_f32_16x16x32_bf16 v[24:27], v[116:119], v[226:229], v[24:27]
	v_mfma_f32_16x16x32_bf16 v[12:15], v[108:111], v[242:245], v[12:15]
	v_mfma_f32_16x16x32_bf16 v[8:11], v[116:119], v[242:245], v[8:11]
	v_mfma_f32_16x16x32_bf16 v[52:55], v[144:147], v[184:187], v[52:55]
	v_mfma_f32_16x16x32_bf16 v[48:51], v[152:155], v[184:187], v[48:51]
	v_mfma_f32_16x16x32_bf16 v[36:39], v[144:147], v[214:217], v[36:39]
	v_mfma_f32_16x16x32_bf16 v[32:35], v[152:155], v[214:217], v[32:35]
	v_mfma_f32_16x16x32_bf16 v[20:23], v[144:147], v[222:225], v[20:23]
	v_mfma_f32_16x16x32_bf16 v[16:19], v[152:155], v[222:225], v[16:19]
	v_mfma_f32_16x16x32_bf16 v[4:7], v[144:147], v[238:241], v[4:7]
	v_mfma_f32_16x16x32_bf16 v[0:3], v[152:155], v[238:241], v[0:3]
	v_mfma_f32_16x16x32_bf16 v[52:55], v[148:151], v[188:191], v[52:55]
	v_mfma_f32_16x16x32_bf16 v[48:51], v[156:159], v[188:191], v[48:51]
	v_mfma_f32_16x16x32_bf16 v[36:39], v[148:151], v[218:221], v[36:39]
	v_mfma_f32_16x16x32_bf16 v[32:35], v[156:159], v[218:221], v[32:35]
	v_mfma_f32_16x16x32_bf16 v[20:23], v[148:151], v[226:229], v[20:23]
	v_mfma_f32_16x16x32_bf16 v[16:19], v[156:159], v[226:229], v[16:19]
	v_mfma_f32_16x16x32_bf16 v[4:7], v[148:151], v[242:245], v[4:7]
	v_mfma_f32_16x16x32_bf16 v[0:3], v[156:159], v[242:245], v[0:3]
	s_barrier
	s_add_i32 s33, s33, 2
	s_add_u32 s9, s9, 0x100
	s_addc_u32 s11, s11, 0
	s_cmpk_gt_u32 s33, 0x55
	s_mov_b64 s[12:13], s[14:15]
	s_cbranch_scc0 .LBB0_675
	s_and_b64 vcc, exec, s[4:5]
	s_cbranch_vccz .LBB0_678
	s_barrier

; #define PG8_STAGE(bufoff, gbase, voff) do { _Pragma("unroll") for (int _i = 0; _i < 2; ++_i) \
;         __builtin_amdgcn_global_load_lds((const unsigned*)((const char*)(gbase) + (voff)[_i]), (LAS unsigned*)(lds + (bufoff) + ldsw + _i * 8192), 16, 0, 0); } while (0)
; #define PG8_LDA(dst, b, h) do { _Pragma("unroll") for (int m = 0; m < 4; ++m) _Pragma("unroll") for (int k = 0; k < 2; ++k) dst[m][k] = *(const LAS bf16x8*)(lds + PG8_SA(b, h) + aoff + m * 2048 + k * 1024); } while (0)
; #define PG8_LDB(dst, b, h) do { _Pragma("unroll") for (int n = 0; n < 2; ++n) _Pragma("unroll") for (int k = 0; k < 2; ++k) dst[n][k] = *(const LAS bf16x8*)(lds + PG8_SB(b, h) + boff + n * 2048 + k * 1024); } while (0)
; #define PG8_MMA(ai, bj, At, Bt) do { __builtin_amdgcn_s_setprio(1); _Pragma("unroll") for (int m = 0; m < 4; ++m) _Pragma("unroll") for (int n = 0; n < 2; ++n) _Pragma("unroll") for (int k = 0; k < 2; ++k) \
;         acc[ai][bj][m][n] = __builtin_amdgcn_mfma_f32_16x16x32_bf16(Bt[n][k], At[m][k], acc[ai][bj][m][n], 0, 0, 0); __builtin_amdgcn_s_setprio(0); } while (0)
; #define PG8_WAIT_V(n) asm volatile("s_waitcnt vmcnt(" #n ")" ::: "memory")
; #define PG8_WAIT_L(n) asm volatile("s_waitcnt lgkmcnt(" #n ")" ::: "memory")
; #define PG8_BAR __builtin_amdgcn_s_barrier()
; #define PG8_SCHED __builtin_amdgcn_sched_barrier(0)
; template <class Epi, bool PERMA = false, bool DUAL = false, bool ALIGN_EPI = true, bool SP2 = true>
; __device__ __forceinline__ void gemm_phase(LAS unsigned char* lds, const Gemm g, const StaticOrder& S, const Epi& E) {
;     ...
;             const bool last = (t == nt - 2);
;             const char* a1 = cA + (size_t)(t + 1) * kstep;
;             const char* a2 = last ? nA : cA + (size_t)(t + 2) * kstep; const char* b2 = last ? nB : cB + (size_t)(t + 2) * kstep;
;             const char* a3 = a2 + kstep; const char* b3 = b2 + kstep;
;             if constexpr (SP2) {
;             PG8_LDB(B0, 0, 0); PG8_LDB(B1, 0, 1); PG8_SCHED; PG8_LDA(At, 0, 0); PG8_STAGE(PG8_SA(1, 1), a1 + hstepA, voffA);
;             PG8_WAIT_V(8); PG8_WAIT_L(0); PG8_BAR; PG8_MMA(0, 0, At, B0); PG8_MMA(0, 1, At, B1); PG8_BAR; PG8_SCHED;
;             PG8_LDA(At, 0, 1); PG8_STAGE(PG8_SB(0, 0), b2, voffB); PG8_STAGE(PG8_SB(0, 1), b2 + hstepB, voffB); PG8_STAGE(PG8_SA(0, 0), a2, voffA);
.LBB0_770:
	s_add_u32 s23, s14, s22
	s_addc_u32 s28, s15, 0
	s_add_u32 s26, s23, 0x100
	s_addc_u32 s27, s28, 0
	s_and_b64 s[24:25], s[20:21], exec
	s_cselect_b32 s25, s9, s27
	s_cselect_b32 s24, s47, s26
	s_add_u32 s22, s16, s22
	s_addc_u32 s26, s17, 0
	s_add_u32 s22, s22, 0x100
	s_addc_u32 s26, s26, 0
	s_add_i32 s57, 0, 0x10000
	s_and_b64 s[20:21], s[20:21], exec
	s_cselect_b32 s27, s7, s26
	s_cselect_b32 s26, s48, s22
	s_add_i32 s21, 0, 0x14000
	s_add_u32 s30, s23, 0x10080
	s_addc_u32 s31, s28, 0
	s_add_i32 s56, s57, s35
	s_add_i32 m0, s36, 0xc000
	s_add_i32 s59, s36, 0xe000
	s_add_i32 s53, s56, 0x2000
	v_add_u32_e32 v138, s57, v140
	s_add_u32 s28, s26, 0x10000
	ds_read_b128 v[142:145], v138
	ds_read_b128 v[146:149], v138 offset:1024
	ds_read_b128 v[150:153], v138 offset:2048
	ds_read_b128 v[154:157], v138 offset:3072
	v_add_u32_e32 v138, s21, v140
	s_addc_u32 s29, s27, 0
	s_add_i32 s55, s21, s35
	ds_read_b128 v[158:161], v138
	ds_read_b128 v[162:165], v138 offset:1024
	ds_read_b128 v[166:169], v138 offset:2048
	ds_read_b128 v[170:173], v138 offset:3072
	s_add_i32 s54, s55, 0x2000
	s_add_i32 s52, 0, 0x18000
	s_add_i32 s51, 0, 0x1c000
	s_add_u32 s22, s24, 0x10000
	s_addc_u32 s23, s25, 0
	s_add_i32 s50, s52, s35
	s_add_i32 s49, s50, 0x2000
	s_add_u32 s20, s26, 0x10080
	s_addc_u32 s21, s27, 0
	s_add_i32 s58, s51, s35
	s_add_i32 s57, s58, 0x2000
	v_lshl_add_u64 v[138:139], s[30:31], 0, v[134:135]
	ds_read_b128 v[174:177], v141
	ds_read_b128 v[178:181], v141 offset:1024
	ds_read_b128 v[182:185], v141 offset:2048
	ds_read_b128 v[186:189], v141 offset:3072
	ds_read_b128 v[206:209], v141 offset:4096
	ds_read_b128 v[210:213], v141 offset:5120
	ds_read_b128 v[214:217], v141 offset:6144
	ds_read_b128 v[218:221], v141 offset:7168
	global_load_lds_dwordx4 v[138:139], off
	v_lshl_add_u64 v[138:139], s[30:31], 0, v[130:131]
	s_mov_b32 m0, s59
	s_nop 0
	global_load_lds_dwordx4 v[138:139], off
	s_waitcnt vmcnt(8) lgkmcnt(0)
	s_barrier
	v_mfma_f32_16x16x32_bf16 v[124:127], v[142:145], v[174:177], v[124:127]
	v_mfma_f32_16x16x32_bf16 v[120:123], v[150:153], v[174:177], v[120:123]
	v_mfma_f32_16x16x32_bf16 v[116:119], v[142:145], v[182:185], v[116:119]
	v_mfma_f32_16x16x32_bf16 v[108:111], v[150:153], v[182:185], v[108:111]
	v_mfma_f32_16x16x32_bf16 v[100:103], v[142:145], v[206:209], v[100:103]
	v_mfma_f32_16x16x32_bf16 v[92:95], v[150:153], v[206:209], v[92:95]
	v_mfma_f32_16x16x32_bf16 v[84:87], v[142:145], v[214:217], v[84:87]
	v_mfma_f32_16x16x32_bf16 v[76:79], v[150:153], v[214:217], v[76:79]
	v_mfma_f32_16x16x32_bf16 v[124:127], v[146:149], v[178:181], v[124:127]
	v_mfma_f32_16x16x32_bf16 v[120:123], v[154:157], v[178:181], v[120:123]
	v_mfma_f32_16x16x32_bf16 v[116:119], v[146:149], v[186:189], v[116:119]
	v_mfma_f32_16x16x32_bf16 v[108:111], v[154:157], v[186:189], v[108:111]
	v_mfma_f32_16x16x32_bf16 v[100:103], v[146:149], v[210:213], v[100:103]
	v_mfma_f32_16x16x32_bf16 v[92:95], v[154:157], v[210:213], v[92:95]
	v_mfma_f32_16x16x32_bf16 v[84:87], v[146:149], v[218:221], v[84:87]
	v_mfma_f32_16x16x32_bf16 v[76:79], v[154:157], v[218:221], v[76:79]
	v_mfma_f32_16x16x32_bf16 v[112:115], v[158:161], v[174:177], v[112:115]
	v_mfma_f32_16x16x32_bf16 v[104:107], v[166:169], v[174:177], v[104:107]
	v_mfma_f32_16x16x32_bf16 v[96:99], v[158:161], v[182:185], v[96:99]
	v_mfma_f32_16x16x32_bf16 v[88:91], v[166:169], v[182:185], v[88:91]
	v_mfma_f32_16x16x32_bf16 v[80:83], v[158:161], v[206:209], v[80:83]
	v_mfma_f32_16x16x32_bf16 v[72:75], v[166:169], v[206:209], v[72:75]
	v_mfma_f32_16x16x32_bf16 v[68:71], v[158:161], v[214:217], v[68:71]
	v_mfma_f32_16x16x32_bf16 v[64:67], v[166:169], v[214:217], v[64:67]
	v_mfma_f32_16x16x32_bf16 v[112:115], v[162:165], v[178:181], v[112:115]
	v_mfma_f32_16x16x32_bf16 v[104:107], v[170:173], v[178:181], v[104:107]
	v_mfma_f32_16x16x32_bf16 v[96:99], v[162:165], v[186:189], v[96:99]
	v_mfma_f32_16x16x32_bf16 v[88:91], v[170:173], v[186:189], v[88:91]
	v_mfma_f32_16x16x32_bf16 v[80:83], v[162:165], v[210:213], v[80:83]
	v_mfma_f32_16x16x32_bf16 v[72:75], v[170:173], v[210:213], v[72:75]
	v_mfma_f32_16x16x32_bf16 v[68:71], v[162:165], v[218:221], v[68:71]
	v_mfma_f32_16x16x32_bf16 v[64:67], v[170:173], v[218:221], v[64:67]
	s_barrier
	s_mov_b32 m0, s56
	v_lshl_add_u64 v[138:139], s[26:27], 0, v[132:133]
	ds_read_b128 v[174:177], v141 offset:16384
	ds_read_b128 v[178:181], v141 offset:17408
	ds_read_b128 v[182:185], v141 offset:18432
	ds_read_b128 v[186:189], v141 offset:19456
	ds_read_b128 v[206:209], v141 offset:20480
	ds_read_b128 v[210:213], v141 offset:21504
	ds_read_b128 v[214:217], v141 offset:22528
	ds_read_b128 v[218:221], v141 offset:23552
	global_load_lds_dwordx4 v[138:139], off
	v_lshl_add_u64 v[190:191], s[26:27], 0, v[128:129]
	s_mov_b32 m0, s53
	v_lshl_add_u64 v[194:195], s[28:29], 0, v[132:133]
	global_load_lds_dwordx4 v[190:191], off
	s_mov_b32 m0, s55
	v_lshl_add_u64 v[196:197], s[24:25], 0, v[130:131]
	global_load_lds_dwordx4 v[194:195], off
	v_lshl_add_u64 v[194:195], s[28:29], 0, v[128:129]
	s_mov_b32 m0, s54
	s_nop 0
	global_load_lds_dwordx4 v[194:195], off
	v_lshl_add_u64 v[194:195], s[24:25], 0, v[134:135]
	s_mov_b32 m0, s36
	s_nop 0
	global_load_lds_dwordx4 v[194:195], off
	s_mov_b32 m0, s37
	s_nop 0
	global_load_lds_dwordx4 v[196:197], off
	s_waitcnt vmcnt(8) lgkmcnt(0)
	s_barrier
; #define PG8_STAGE(bufoff, gbase, voff) do { _Pragma("unroll") for (int _i = 0; _i < 2; ++_i) \
;         __builtin_amdgcn_global_load_lds((const unsigned*)((const char*)(gbase) + (voff)[_i]), (LAS unsigned*)(lds + (bufoff) + ldsw + _i * 8192), 16, 0, 0); } while (0)
; #define PG8_LDA(dst, b, h) do { _Pragma("unroll") for (int m = 0; m < 4; ++m) _Pragma("unroll") for (int k = 0; k < 2; ++k) dst[m][k] = *(const LAS bf16x8*)(lds + PG8_SA(b, h) + aoff + m * 2048 + k * 1024); } while (0)
; #define PG8_LDB(dst, b, h) do { _Pragma("unroll") for (int n = 0; n < 2; ++n) _Pragma("unroll") for (int k = 0; k < 2; ++k) dst[n][k] = *(const LAS bf16x8*)(lds + PG8_SB(b, h) + boff + n * 2048 + k * 1024); } while (0)
; #define PG8_MMA(ai, bj, At, Bt) do { __builtin_amdgcn_s_setprio(1); _Pragma("unroll") for (int m = 0; m < 4; ++m) _Pragma("unroll") for (int n = 0; n < 2; ++n) _Pragma("unroll") for (int k = 0; k < 2; ++k) \
;         acc[ai][bj][m][n] = __builtin_amdgcn_mfma_f32_16x16x32_bf16(Bt[n][k], At[m][k], acc[ai][bj][m][n], 0, 0, 0); __builtin_amdgcn_s_setprio(0); } while (0)
; #define PG8_WAIT_V(n) asm volatile("s_waitcnt vmcnt(" #n ")" ::: "memory")
; #define PG8_WAIT_L(n) asm volatile("s_waitcnt lgkmcnt(" #n ")" ::: "memory")
; #define PG8_BAR __builtin_amdgcn_s_barrier()
; #define PG8_SCHED __builtin_amdgcn_sched_barrier(0)
; template <class Epi, bool PERMA = false, bool DUAL = false, bool ALIGN_EPI = true, bool SP2 = true>
; __device__ __forceinline__ void gemm_phase(LAS unsigned char* lds, const Gemm g, const StaticOrder& S, const Epi& E) {
;     ...
;             PG8_WAIT_V(8); PG8_WAIT_L(0); PG8_BAR; PG8_MMA(1, 0, At, B0); PG8_MMA(1, 1, At, B1); PG8_BAR; PG8_SCHED;
;             PG8_LDB(B0, 1, 0); PG8_LDB(B1, 1, 1); PG8_SCHED; PG8_LDA(At, 1, 0); PG8_STAGE(PG8_SA(0, 1), a2 + hstepA, voffA);
;             PG8_WAIT_V(8); PG8_WAIT_L(0); PG8_BAR; PG8_MMA(0, 0, At, B0); PG8_MMA(0, 1, At, B1); PG8_BAR; PG8_SCHED;
	v_mfma_f32_16x16x32_bf16 v[60:63], v[142:145], v[174:177], v[60:63]
	v_mfma_f32_16x16x32_bf16 v[56:59], v[150:153], v[174:177], v[56:59]
	v_mfma_f32_16x16x32_bf16 v[52:55], v[142:145], v[182:185], v[52:55]
	v_mfma_f32_16x16x32_bf16 v[44:47], v[150:153], v[182:185], v[44:47]
	v_mfma_f32_16x16x32_bf16 v[36:39], v[142:145], v[206:209], v[36:39]
	v_mfma_f32_16x16x32_bf16 v[28:31], v[150:153], v[206:209], v[28:31]
	v_mfma_f32_16x16x32_bf16 v[20:23], v[142:145], v[214:217], v[20:23]
	v_mfma_f32_16x16x32_bf16 v[12:15], v[150:153], v[214:217], v[12:15]
	v_mfma_f32_16x16x32_bf16 v[60:63], v[146:149], v[178:181], v[60:63]
	v_mfma_f32_16x16x32_bf16 v[56:59], v[154:157], v[178:181], v[56:59]
	v_mfma_f32_16x16x32_bf16 v[52:55], v[146:149], v[186:189], v[52:55]
	v_mfma_f32_16x16x32_bf16 v[44:47], v[154:157], v[186:189], v[44:47]
	v_mfma_f32_16x16x32_bf16 v[36:39], v[146:149], v[210:213], v[36:39]
	v_mfma_f32_16x16x32_bf16 v[28:31], v[154:157], v[210:213], v[28:31]
	v_mfma_f32_16x16x32_bf16 v[20:23], v[146:149], v[218:221], v[20:23]
	v_mfma_f32_16x16x32_bf16 v[12:15], v[154:157], v[218:221], v[12:15]
	v_mfma_f32_16x16x32_bf16 v[48:51], v[158:161], v[174:177], v[48:51]
	v_mfma_f32_16x16x32_bf16 v[40:43], v[166:169], v[174:177], v[40:43]
	v_mfma_f32_16x16x32_bf16 v[32:35], v[158:161], v[182:185], v[32:35]
	v_mfma_f32_16x16x32_bf16 v[24:27], v[166:169], v[182:185], v[24:27]
	v_mfma_f32_16x16x32_bf16 v[16:19], v[158:161], v[206:209], v[16:19]
	v_mfma_f32_16x16x32_bf16 v[8:11], v[166:169], v[206:209], v[8:11]
	v_mfma_f32_16x16x32_bf16 v[4:7], v[158:161], v[214:217], v[4:7]
	v_mfma_f32_16x16x32_bf16 v[0:3], v[166:169], v[214:217], v[0:3]
	v_mfma_f32_16x16x32_bf16 v[48:51], v[162:165], v[178:181], v[48:51]
	v_mfma_f32_16x16x32_bf16 v[40:43], v[170:173], v[178:181], v[40:43]
	v_mfma_f32_16x16x32_bf16 v[32:35], v[162:165], v[186:189], v[32:35]
	v_mfma_f32_16x16x32_bf16 v[24:27], v[170:173], v[186:189], v[24:27]
	v_mfma_f32_16x16x32_bf16 v[16:19], v[162:165], v[210:213], v[16:19]
	v_mfma_f32_16x16x32_bf16 v[8:11], v[170:173], v[210:213], v[8:11]
	v_mfma_f32_16x16x32_bf16 v[4:7], v[162:165], v[218:221], v[4:7]
	v_mfma_f32_16x16x32_bf16 v[0:3], v[170:173], v[218:221], v[0:3]
	s_barrier
	v_add_u32_e32 v154, s52, v140
	v_add_u32_e32 v170, s51, v140
	ds_read_b128 v[142:145], v154
	ds_read_b128 v[146:149], v154 offset:1024
	ds_read_b128 v[150:153], v154 offset:2048
	ds_read_b128 v[154:157], v154 offset:3072
	ds_read_b128 v[158:161], v170
	ds_read_b128 v[162:165], v170 offset:1024
	ds_read_b128 v[166:169], v170 offset:2048
	ds_read_b128 v[170:173], v170 offset:3072
	s_mov_b32 m0, s38
	v_lshl_add_u64 v[222:223], s[22:23], 0, v[134:135]
	ds_read_b128 v[174:177], v141 offset:32768
	ds_read_b128 v[178:181], v141 offset:33792
	ds_read_b128 v[182:185], v141 offset:34816
	ds_read_b128 v[186:189], v141 offset:35840
	ds_read_b128 v[206:209], v141 offset:36864
	ds_read_b128 v[210:213], v141 offset:37888
	ds_read_b128 v[214:217], v141 offset:38912
	ds_read_b128 v[218:221], v141 offset:39936
	global_load_lds_dwordx4 v[222:223], off
	v_lshl_add_u64 v[222:223], s[22:23], 0, v[130:131]
	s_mov_b32 m0, s39
	s_nop 0
	global_load_lds_dwordx4 v[222:223], off
	s_waitcnt vmcnt(8) lgkmcnt(0)
	s_barrier
	v_mfma_f32_16x16x32_bf16 v[124:127], v[142:145], v[174:177], v[124:127]
	v_mfma_f32_16x16x32_bf16 v[120:123], v[150:153], v[174:177], v[120:123]
	v_mfma_f32_16x16x32_bf16 v[116:119], v[142:145], v[182:185], v[116:119]
	v_mfma_f32_16x16x32_bf16 v[108:111], v[150:153], v[182:185], v[108:111]
	v_mfma_f32_16x16x32_bf16 v[100:103], v[142:145], v[206:209], v[100:103]
	v_mfma_f32_16x16x32_bf16 v[92:95], v[150:153], v[206:209], v[92:95]
	v_mfma_f32_16x16x32_bf16 v[84:87], v[142:145], v[214:217], v[84:87]
	v_mfma_f32_16x16x32_bf16 v[76:79], v[150:153], v[214:217], v[76:79]
	v_mfma_f32_16x16x32_bf16 v[124:127], v[146:149], v[178:181], v[124:127]
	v_mfma_f32_16x16x32_bf16 v[120:123], v[154:157], v[178:181], v[120:123]
	v_mfma_f32_16x16x32_bf16 v[116:119], v[146:149], v[186:189], v[116:119]
	v_mfma_f32_16x16x32_bf16 v[108:111], v[154:157], v[186:189], v[108:111]
	v_mfma_f32_16x16x32_bf16 v[100:103], v[146:149], v[210:213], v[100:103]
	v_mfma_f32_16x16x32_bf16 v[92:95], v[154:157], v[210:213], v[92:95]
	v_mfma_f32_16x16x32_bf16 v[84:87], v[146:149], v[218:221], v[84:87]
	v_mfma_f32_16x16x32_bf16 v[76:79], v[154:157], v[218:221], v[76:79]
	v_mfma_f32_16x16x32_bf16 v[112:115], v[158:161], v[174:177], v[112:115]
	v_mfma_f32_16x16x32_bf16 v[104:107], v[166:169], v[174:177], v[104:107]
	v_mfma_f32_16x16x32_bf16 v[96:99], v[158:161], v[182:185], v[96:99]
	v_mfma_f32_16x16x32_bf16 v[88:91], v[166:169], v[182:185], v[88:91]
	v_mfma_f32_16x16x32_bf16 v[80:83], v[158:161], v[206:209], v[80:83]
	v_mfma_f32_16x16x32_bf16 v[72:75], v[166:169], v[206:209], v[72:75]
	v_mfma_f32_16x16x32_bf16 v[68:71], v[158:161], v[214:217], v[68:71]
	v_mfma_f32_16x16x32_bf16 v[64:67], v[166:169], v[214:217], v[64:67]
	v_mfma_f32_16x16x32_bf16 v[112:115], v[162:165], v[178:181], v[112:115]
	v_mfma_f32_16x16x32_bf16 v[104:107], v[170:173], v[178:181], v[104:107]
	v_mfma_f32_16x16x32_bf16 v[96:99], v[162:165], v[186:189], v[96:99]
	v_mfma_f32_16x16x32_bf16 v[88:91], v[170:173], v[186:189], v[88:91]
	v_mfma_f32_16x16x32_bf16 v[80:83], v[162:165], v[210:213], v[80:83]
	v_mfma_f32_16x16x32_bf16 v[72:75], v[170:173], v[210:213], v[72:75]
	v_mfma_f32_16x16x32_bf16 v[68:71], v[162:165], v[218:221], v[68:71]
	v_mfma_f32_16x16x32_bf16 v[64:67], v[170:173], v[218:221], v[64:67]
	s_barrier
; #define PG8_STAGE(bufoff, gbase, voff) do { _Pragma("unroll") for (int _i = 0; _i < 2; ++_i) \
;         __builtin_amdgcn_global_load_lds((const unsigned*)((const char*)(gbase) + (voff)[_i]), (LAS unsigned*)(lds + (bufoff) + ldsw + _i * 8192), 16, 0, 0); } while (0)
; #define PG8_LDA(dst, b, h) do { _Pragma("unroll") for (int m = 0; m < 4; ++m) _Pragma("unroll") for (int k = 0; k < 2; ++k) dst[m][k] = *(const LAS bf16x8*)(lds + PG8_SA(b, h) + aoff + m * 2048 + k * 1024); } while (0)
; #define PG8_MMA(ai, bj, At, Bt) do { __builtin_amdgcn_s_setprio(1); _Pragma("unroll") for (int m = 0; m < 4; ++m) _Pragma("unroll") for (int n = 0; n < 2; ++n) _Pragma("unroll") for (int k = 0; k < 2; ++k) \
;         acc[ai][bj][m][n] = __builtin_amdgcn_mfma_f32_16x16x32_bf16(Bt[n][k], At[m][k], acc[ai][bj][m][n], 0, 0, 0); __builtin_amdgcn_s_setprio(0); } while (0)
; #define PG8_WAIT_V(n) asm volatile("s_waitcnt vmcnt(" #n ")" ::: "memory")
; #define PG8_WAIT_L(n) asm volatile("s_waitcnt lgkmcnt(" #n ")" ::: "memory")
; #define PG8_BAR __builtin_amdgcn_s_barrier()
; #define PG8_SCHED __builtin_amdgcn_sched_barrier(0)
; template <class Epi, bool PERMA = false, bool DUAL = false, bool ALIGN_EPI = true, bool SP2 = true>
; __device__ __forceinline__ void gemm_phase(LAS unsigned char* lds, const Gemm g, const StaticOrder& S, const Epi& E) {
;     ...
;             PG8_LDA(At, 1, 1); PG8_STAGE(PG8_SB(1, 0), b3, voffB); PG8_STAGE(PG8_SB(1, 1), b3 + hstepB, voffB); PG8_STAGE(PG8_SA(1, 0), a3, voffA);
;             PG8_WAIT_V(8); PG8_WAIT_L(0); PG8_BAR; PG8_MMA(1, 0, At, B0); PG8_MMA(1, 1, At, B1); PG8_BAR; PG8_SCHED;
;     ...
;         if constexpr (ALIGN_EPI) { if (wr == 0) PG8_BAR; }
	s_mov_b32 m0, s50
	v_lshl_add_u64 v[138:139], v[138:139], 0, s[68:69]
	ds_read_b128 v[174:177], v141 offset:49152
	ds_read_b128 v[178:181], v141 offset:50176
	ds_read_b128 v[182:185], v141 offset:51200
	ds_read_b128 v[186:189], v141 offset:52224
	ds_read_b128 v[206:209], v141 offset:53248
	ds_read_b128 v[210:213], v141 offset:54272
	ds_read_b128 v[214:217], v141 offset:55296
	ds_read_b128 v[218:221], v141 offset:56320
	global_load_lds_dwordx4 v[138:139], off
	v_lshl_add_u64 v[138:139], v[190:191], 0, s[68:69]
	s_mov_b32 m0, s49
	s_nop 0
	global_load_lds_dwordx4 v[138:139], off
	v_lshl_add_u64 v[138:139], s[20:21], 0, v[132:133]
	s_mov_b32 m0, s58
	s_nop 0
	global_load_lds_dwordx4 v[138:139], off
	v_lshl_add_u64 v[138:139], s[20:21], 0, v[128:129]
	s_mov_b32 m0, s57
	s_nop 0
	global_load_lds_dwordx4 v[138:139], off
	v_lshl_add_u64 v[138:139], v[194:195], 0, s[68:69]
	s_mov_b32 m0, s42
	s_nop 0
	global_load_lds_dwordx4 v[138:139], off
	v_lshl_add_u64 v[138:139], v[196:197], 0, s[68:69]
	s_mov_b32 m0, s43
	s_nop 0
	global_load_lds_dwordx4 v[138:139], off
	s_waitcnt vmcnt(8) lgkmcnt(0)
	s_barrier
	v_mfma_f32_16x16x32_bf16 v[60:63], v[142:145], v[174:177], v[60:63]
	v_mfma_f32_16x16x32_bf16 v[56:59], v[150:153], v[174:177], v[56:59]
	v_mfma_f32_16x16x32_bf16 v[52:55], v[142:145], v[182:185], v[52:55]
	v_mfma_f32_16x16x32_bf16 v[44:47], v[150:153], v[182:185], v[44:47]
	v_mfma_f32_16x16x32_bf16 v[36:39], v[142:145], v[206:209], v[36:39]
	v_mfma_f32_16x16x32_bf16 v[28:31], v[150:153], v[206:209], v[28:31]
	v_mfma_f32_16x16x32_bf16 v[20:23], v[142:145], v[214:217], v[20:23]
	v_mfma_f32_16x16x32_bf16 v[12:15], v[150:153], v[214:217], v[12:15]
	v_mfma_f32_16x16x32_bf16 v[60:63], v[146:149], v[178:181], v[60:63]
	v_mfma_f32_16x16x32_bf16 v[56:59], v[154:157], v[178:181], v[56:59]
	v_mfma_f32_16x16x32_bf16 v[52:55], v[146:149], v[186:189], v[52:55]
	v_mfma_f32_16x16x32_bf16 v[44:47], v[154:157], v[186:189], v[44:47]
	v_mfma_f32_16x16x32_bf16 v[36:39], v[146:149], v[210:213], v[36:39]
	v_mfma_f32_16x16x32_bf16 v[28:31], v[154:157], v[210:213], v[28:31]
	v_mfma_f32_16x16x32_bf16 v[20:23], v[146:149], v[218:221], v[20:23]
	v_mfma_f32_16x16x32_bf16 v[12:15], v[154:157], v[218:221], v[12:15]
	v_mfma_f32_16x16x32_bf16 v[48:51], v[158:161], v[174:177], v[48:51]
	v_mfma_f32_16x16x32_bf16 v[40:43], v[166:169], v[174:177], v[40:43]
	v_mfma_f32_16x16x32_bf16 v[32:35], v[158:161], v[182:185], v[32:35]
	v_mfma_f32_16x16x32_bf16 v[24:27], v[166:169], v[182:185], v[24:27]
	v_mfma_f32_16x16x32_bf16 v[16:19], v[158:161], v[206:209], v[16:19]
	v_mfma_f32_16x16x32_bf16 v[8:11], v[166:169], v[206:209], v[8:11]
	v_mfma_f32_16x16x32_bf16 v[4:7], v[158:161], v[214:217], v[4:7]
	v_mfma_f32_16x16x32_bf16 v[0:3], v[166:169], v[214:217], v[0:3]
	v_mfma_f32_16x16x32_bf16 v[48:51], v[162:165], v[178:181], v[48:51]
	v_mfma_f32_16x16x32_bf16 v[40:43], v[170:173], v[178:181], v[40:43]
	v_mfma_f32_16x16x32_bf16 v[32:35], v[162:165], v[186:189], v[32:35]
	v_mfma_f32_16x16x32_bf16 v[24:27], v[170:173], v[186:189], v[24:27]
	v_mfma_f32_16x16x32_bf16 v[16:19], v[162:165], v[210:213], v[16:19]
	v_mfma_f32_16x16x32_bf16 v[8:11], v[170:173], v[210:213], v[8:11]
	v_mfma_f32_16x16x32_bf16 v[4:7], v[162:165], v[218:221], v[4:7]
	v_mfma_f32_16x16x32_bf16 v[0:3], v[170:173], v[218:221], v[0:3]
	s_barrier
	s_movk_i32 s22, 0x100
	s_andn2_b64 vcc, exec, s[18:19]
	s_mov_b64 s[20:21], -1
	s_mov_b64 s[18:19], 0
	s_cbranch_vccz .LBB0_770
	s_and_b64 vcc, exec, s[4:5]
	s_cbranch_vccz .LBB0_773
	s_barrier

; #define PG8_STAGE(bufoff, gbase, voff) do { _Pragma("unroll") for (int _i = 0; _i < 2; ++_i) \
;         __builtin_amdgcn_global_load_lds((const unsigned*)((const char*)(gbase) + (voff)[_i]), (LAS unsigned*)(lds + (bufoff) + ldsw + _i * 8192), 16, 0, 0); } while (0)
; #define PG8_LDA(dst, b, h) do { _Pragma("unroll") for (int m = 0; m < 4; ++m) _Pragma("unroll") for (int k = 0; k < 2; ++k) dst[m][k] = *(const LAS bf16x8*)(lds + PG8_SA(b, h) + aoff + m * 2048 + k * 1024); } while (0)
; #define PG8_LDB(dst, b, h) do { _Pragma("unroll") for (int n = 0; n < 2; ++n) _Pragma("unroll") for (int k = 0; k < 2; ++k) dst[n][k] = *(const LAS bf16x8*)(lds + PG8_SB(b, h) + boff + n * 2048 + k * 1024); } while (0)
; #define PG8_MMA(ai, bj, At, Bt) do { __builtin_amdgcn_s_setprio(1); _Pragma("unroll") for (int m = 0; m < 4; ++m) _Pragma("unroll") for (int n = 0; n < 2; ++n) _Pragma("unroll") for (int k = 0; k < 2; ++k) \
;         acc[ai][bj][m][n] = __builtin_amdgcn_mfma_f32_16x16x32_bf16(Bt[n][k], At[m][k], acc[ai][bj][m][n], 0, 0, 0); __builtin_amdgcn_s_setprio(0); } while (0)
; #define PG8_WAIT_V(n) asm volatile("s_waitcnt vmcnt(" #n ")" ::: "memory")
; #define PG8_WAIT_L(n) asm volatile("s_waitcnt lgkmcnt(" #n ")" ::: "memory")
; #define PG8_BAR __builtin_amdgcn_s_barrier()
; #define PG8_SCHED __builtin_amdgcn_sched_barrier(0)
; template <class Epi, bool PERMA = false, bool DUAL = false, bool ALIGN_EPI = true, bool SP2 = true>
; __device__ __forceinline__ void gemm_phase(LAS unsigned char* lds, const Gemm g, const StaticOrder& S, const Epi& E) {
;     ...
;             const bool last = (t == nt - 2);
;             const char* a1 = cA + (size_t)(t + 1) * kstep;
;             const char* a2 = last ? nA : cA + (size_t)(t + 2) * kstep; const char* b2 = last ? nB : cB + (size_t)(t + 2) * kstep;
;             const char* a3 = a2 + kstep; const char* b3 = b2 + kstep;
;             if constexpr (SP2) {
;             PG8_LDB(B0, 0, 0); PG8_LDB(B1, 0, 1); PG8_SCHED; PG8_LDA(At, 0, 0); PG8_STAGE(PG8_SA(1, 1), a1 + hstepA, voffA);
;             PG8_WAIT_V(8); PG8_WAIT_L(0); PG8_BAR; PG8_MMA(0, 0, At, B0); PG8_MMA(0, 1, At, B1); PG8_BAR; PG8_SCHED;
;             PG8_LDA(At, 0, 1); PG8_STAGE(PG8_SB(0, 0), b2, voffB); PG8_STAGE(PG8_SB(0, 1), b2 + hstepB, voffB); PG8_STAGE(PG8_SA(0, 0), a2, voffA);
.LBB0_790:
	s_add_u32 s14, s12, 0xfff80080
	s_addc_u32 s15, s13, -1
	s_add_i32 s36, 0, 0x10000
	s_cmp_eq_u32 s35, 28
	s_cselect_b32 s17, s7, s15
	s_cselect_b32 s16, s30, s14
	s_cselect_b32 s15, s5, s34
	s_cselect_b32 s14, s31, s33
	s_add_i32 s40, 0, 0x14000
	v_add_u32_e32 v140, s36, v190
	v_add_u32_e32 v156, s40, v190
	ds_read_b128 v[120:123], v140
	ds_read_b128 v[128:131], v140 offset:1024
	ds_read_b128 v[132:135], v140 offset:2048
	ds_read_b128 v[140:143], v140 offset:3072
	ds_read_b128 v[144:147], v156
	ds_read_b128 v[148:151], v156 offset:1024
	ds_read_b128 v[152:155], v156 offset:2048
	ds_read_b128 v[156:159], v156 offset:3072
	v_lshl_add_u64 v[194:195], s[12:13], 0, v[174:175]
	s_add_i32 m0, s19, 0xc000
	ds_read_b128 v[178:181], v191
	ds_read_b128 v[182:185], v191 offset:1024
	ds_read_b128 v[186:189], v191 offset:2048
	ds_read_b128 v[206:209], v191 offset:3072
	ds_read_b128 v[210:213], v191 offset:4096
	ds_read_b128 v[214:217], v191 offset:5120
	ds_read_b128 v[218:221], v191 offset:6144
	ds_read_b128 v[222:225], v191 offset:7168
	global_load_lds_dwordx4 v[194:195], off
	v_lshl_add_u64 v[194:195], s[12:13], 0, v[176:177]
	s_add_i32 m0, s19, 0xe000
	s_nop 0
	global_load_lds_dwordx4 v[194:195], off
	s_waitcnt vmcnt(8) lgkmcnt(0)
	s_barrier
	v_mfma_f32_16x16x32_bf16 v[136:139], v[120:123], v[178:181], v[136:139]
	v_mfma_f32_16x16x32_bf16 v[124:127], v[132:135], v[178:181], v[124:127]
	v_mfma_f32_16x16x32_bf16 v[108:111], v[120:123], v[186:189], v[108:111]
	v_mfma_f32_16x16x32_bf16 v[104:107], v[132:135], v[186:189], v[104:107]
	v_mfma_f32_16x16x32_bf16 v[92:95], v[120:123], v[210:213], v[92:95]
	v_mfma_f32_16x16x32_bf16 v[88:91], v[132:135], v[210:213], v[88:91]
	v_mfma_f32_16x16x32_bf16 v[76:79], v[120:123], v[218:221], v[76:79]
	v_mfma_f32_16x16x32_bf16 v[72:75], v[132:135], v[218:221], v[72:75]
	v_mfma_f32_16x16x32_bf16 v[136:139], v[128:131], v[182:185], v[136:139]
	v_mfma_f32_16x16x32_bf16 v[124:127], v[140:143], v[182:185], v[124:127]
	v_mfma_f32_16x16x32_bf16 v[108:111], v[128:131], v[206:209], v[108:111]
	v_mfma_f32_16x16x32_bf16 v[104:107], v[140:143], v[206:209], v[104:107]
	v_mfma_f32_16x16x32_bf16 v[92:95], v[128:131], v[214:217], v[92:95]
	v_mfma_f32_16x16x32_bf16 v[88:91], v[140:143], v[214:217], v[88:91]
	v_mfma_f32_16x16x32_bf16 v[76:79], v[128:131], v[222:225], v[76:79]
	v_mfma_f32_16x16x32_bf16 v[72:75], v[140:143], v[222:225], v[72:75]
	v_mfma_f32_16x16x32_bf16 v[116:119], v[144:147], v[178:181], v[116:119]
	v_mfma_f32_16x16x32_bf16 v[112:115], v[152:155], v[178:181], v[112:115]
	v_mfma_f32_16x16x32_bf16 v[100:103], v[144:147], v[186:189], v[100:103]
	v_mfma_f32_16x16x32_bf16 v[96:99], v[152:155], v[186:189], v[96:99]
	v_mfma_f32_16x16x32_bf16 v[84:87], v[144:147], v[210:213], v[84:87]
	v_mfma_f32_16x16x32_bf16 v[80:83], v[152:155], v[210:213], v[80:83]
	v_mfma_f32_16x16x32_bf16 v[68:71], v[144:147], v[218:221], v[68:71]
	v_mfma_f32_16x16x32_bf16 v[64:67], v[152:155], v[218:221], v[64:67]
	v_mfma_f32_16x16x32_bf16 v[116:119], v[148:151], v[182:185], v[116:119]
	v_mfma_f32_16x16x32_bf16 v[112:115], v[156:159], v[182:185], v[112:115]
	v_mfma_f32_16x16x32_bf16 v[100:103], v[148:151], v[206:209], v[100:103]
	v_mfma_f32_16x16x32_bf16 v[96:99], v[156:159], v[206:209], v[96:99]
	v_mfma_f32_16x16x32_bf16 v[84:87], v[148:151], v[214:217], v[84:87]
	v_mfma_f32_16x16x32_bf16 v[80:83], v[156:159], v[214:217], v[80:83]
	v_mfma_f32_16x16x32_bf16 v[68:71], v[148:151], v[222:225], v[68:71]
	v_mfma_f32_16x16x32_bf16 v[64:67], v[156:159], v[222:225], v[64:67]
	s_barrier
	s_add_i32 s36, s36, s18
	v_lshl_add_u64 v[194:195], s[14:15], 0, v[164:165]
	s_mov_b32 m0, s36
	ds_read_b128 v[178:181], v191 offset:16384
	ds_read_b128 v[182:185], v191 offset:17408
	ds_read_b128 v[186:189], v191 offset:18432
	ds_read_b128 v[206:209], v191 offset:19456
	ds_read_b128 v[210:213], v191 offset:20480
	ds_read_b128 v[214:217], v191 offset:21504
	ds_read_b128 v[218:221], v191 offset:22528
	ds_read_b128 v[222:225], v191 offset:23552
	global_load_lds_dwordx4 v[194:195], off
	s_add_i32 m0, s36, 0x2000
	s_add_u32 s36, s14, 0x80000
	v_lshl_add_u64 v[196:197], s[14:15], 0, v[160:161]
	s_addc_u32 s37, s15, 0
	s_add_i32 s40, s40, s18
	global_load_lds_dwordx4 v[196:197], off
	v_lshl_add_u64 v[226:227], s[36:37], 0, v[164:165]
	s_mov_b32 m0, s40
	v_lshl_add_u64 v[228:229], s[16:17], 0, v[162:163]
	global_load_lds_dwordx4 v[226:227], off
	v_lshl_add_u64 v[226:227], s[36:37], 0, v[160:161]
	s_add_i32 m0, s40, 0x2000
	s_nop 0
	global_load_lds_dwordx4 v[226:227], off
	v_lshl_add_u64 v[226:227], s[16:17], 0, v[166:167]
	s_mov_b32 m0, s19
	s_nop 0
	global_load_lds_dwordx4 v[226:227], off
	s_mov_b32 m0, s20
	s_nop 0
	global_load_lds_dwordx4 v[228:229], off
	s_waitcnt vmcnt(8) lgkmcnt(0)
	s_barrier
; #define PG8_STAGE(bufoff, gbase, voff) do { _Pragma("unroll") for (int _i = 0; _i < 2; ++_i) \
;         __builtin_amdgcn_global_load_lds((const unsigned*)((const char*)(gbase) + (voff)[_i]), (LAS unsigned*)(lds + (bufoff) + ldsw + _i * 8192), 16, 0, 0); } while (0)
; #define PG8_LDA(dst, b, h) do { _Pragma("unroll") for (int m = 0; m < 4; ++m) _Pragma("unroll") for (int k = 0; k < 2; ++k) dst[m][k] = *(const LAS bf16x8*)(lds + PG8_SA(b, h) + aoff + m * 2048 + k * 1024); } while (0)
; #define PG8_LDB(dst, b, h) do { _Pragma("unroll") for (int n = 0; n < 2; ++n) _Pragma("unroll") for (int k = 0; k < 2; ++k) dst[n][k] = *(const LAS bf16x8*)(lds + PG8_SB(b, h) + boff + n * 2048 + k * 1024); } while (0)
; #define PG8_MMA(ai, bj, At, Bt) do { __builtin_amdgcn_s_setprio(1); _Pragma("unroll") for (int m = 0; m < 4; ++m) _Pragma("unroll") for (int n = 0; n < 2; ++n) _Pragma("unroll") for (int k = 0; k < 2; ++k) \
;         acc[ai][bj][m][n] = __builtin_amdgcn_mfma_f32_16x16x32_bf16(Bt[n][k], At[m][k], acc[ai][bj][m][n], 0, 0, 0); __builtin_amdgcn_s_setprio(0); } while (0)
; #define PG8_WAIT_V(n) asm volatile("s_waitcnt vmcnt(" #n ")" ::: "memory")
; #define PG8_WAIT_L(n) asm volatile("s_waitcnt lgkmcnt(" #n ")" ::: "memory")
; #define PG8_BAR __builtin_amdgcn_s_barrier()
; #define PG8_SCHED __builtin_amdgcn_sched_barrier(0)
; template <class Epi, bool PERMA = false, bool DUAL = false, bool ALIGN_EPI = true, bool SP2 = true>
; __device__ __forceinline__ void gemm_phase(LAS unsigned char* lds, const Gemm g, const StaticOrder& S, const Epi& E) {
;     ...
;             PG8_WAIT_V(8); PG8_WAIT_L(0); PG8_BAR; PG8_MMA(1, 0, At, B0); PG8_MMA(1, 1, At, B1); PG8_BAR; PG8_SCHED;
;             PG8_LDB(B0, 1, 0); PG8_LDB(B1, 1, 1); PG8_SCHED; PG8_LDA(At, 1, 0); PG8_STAGE(PG8_SA(0, 1), a2 + hstepA, voffA);
;             PG8_WAIT_V(8); PG8_WAIT_L(0); PG8_BAR; PG8_MMA(0, 0, At, B0); PG8_MMA(0, 1, At, B1); PG8_BAR; PG8_SCHED;
	v_mfma_f32_16x16x32_bf16 v[60:63], v[120:123], v[178:181], v[60:63]
	v_mfma_f32_16x16x32_bf16 v[56:59], v[132:135], v[178:181], v[56:59]
	v_mfma_f32_16x16x32_bf16 v[44:47], v[120:123], v[186:189], v[44:47]
	v_mfma_f32_16x16x32_bf16 v[40:43], v[132:135], v[186:189], v[40:43]
	v_mfma_f32_16x16x32_bf16 v[28:31], v[120:123], v[210:213], v[28:31]
	v_mfma_f32_16x16x32_bf16 v[24:27], v[132:135], v[210:213], v[24:27]
	v_mfma_f32_16x16x32_bf16 v[12:15], v[120:123], v[218:221], v[12:15]
	v_mfma_f32_16x16x32_bf16 v[8:11], v[132:135], v[218:221], v[8:11]
	v_mfma_f32_16x16x32_bf16 v[60:63], v[128:131], v[182:185], v[60:63]
	v_mfma_f32_16x16x32_bf16 v[56:59], v[140:143], v[182:185], v[56:59]
	v_mfma_f32_16x16x32_bf16 v[44:47], v[128:131], v[206:209], v[44:47]
	v_mfma_f32_16x16x32_bf16 v[40:43], v[140:143], v[206:209], v[40:43]
	v_mfma_f32_16x16x32_bf16 v[28:31], v[128:131], v[214:217], v[28:31]
	v_mfma_f32_16x16x32_bf16 v[24:27], v[140:143], v[214:217], v[24:27]
	v_mfma_f32_16x16x32_bf16 v[12:15], v[128:131], v[222:225], v[12:15]
	v_mfma_f32_16x16x32_bf16 v[8:11], v[140:143], v[222:225], v[8:11]
	v_mfma_f32_16x16x32_bf16 v[52:55], v[144:147], v[178:181], v[52:55]
	v_mfma_f32_16x16x32_bf16 v[48:51], v[152:155], v[178:181], v[48:51]
	v_mfma_f32_16x16x32_bf16 v[36:39], v[144:147], v[186:189], v[36:39]
	v_mfma_f32_16x16x32_bf16 v[32:35], v[152:155], v[186:189], v[32:35]
	v_mfma_f32_16x16x32_bf16 v[20:23], v[144:147], v[210:213], v[20:23]
	v_mfma_f32_16x16x32_bf16 v[16:19], v[152:155], v[210:213], v[16:19]
	v_mfma_f32_16x16x32_bf16 v[0:3], v[144:147], v[218:221], v[0:3]
	v_mfma_f32_16x16x32_bf16 v[4:7], v[152:155], v[218:221], v[4:7]
	v_mfma_f32_16x16x32_bf16 v[52:55], v[148:151], v[182:185], v[52:55]
	v_mfma_f32_16x16x32_bf16 v[48:51], v[156:159], v[182:185], v[48:51]
	v_mfma_f32_16x16x32_bf16 v[36:39], v[148:151], v[206:209], v[36:39]
	v_mfma_f32_16x16x32_bf16 v[32:35], v[156:159], v[206:209], v[32:35]
	v_mfma_f32_16x16x32_bf16 v[20:23], v[148:151], v[214:217], v[20:23]
	v_mfma_f32_16x16x32_bf16 v[16:19], v[156:159], v[214:217], v[16:19]
	v_mfma_f32_16x16x32_bf16 v[0:3], v[148:151], v[222:225], v[0:3]
	v_mfma_f32_16x16x32_bf16 v[4:7], v[156:159], v[222:225], v[4:7]
	s_barrier
	s_add_i32 s36, 0, 0x18000
	s_add_i32 s37, 0, 0x1c000
	v_add_u32_e32 v140, s36, v190
	v_add_u32_e32 v156, s37, v190
	ds_read_b128 v[120:123], v140
	ds_read_b128 v[128:131], v140 offset:1024
	ds_read_b128 v[132:135], v140 offset:2048
	ds_read_b128 v[140:143], v140 offset:3072
	ds_read_b128 v[144:147], v156
	ds_read_b128 v[148:151], v156 offset:1024
	ds_read_b128 v[152:155], v156 offset:2048
	ds_read_b128 v[156:159], v156 offset:3072
	s_add_u32 s16, s16, 0x80000
	s_addc_u32 s17, s17, 0
	s_mov_b32 m0, s21
	v_lshl_add_u64 v[238:239], s[16:17], 0, v[166:167]
	ds_read_b128 v[178:181], v191 offset:32768
	ds_read_b128 v[182:185], v191 offset:33792
	ds_read_b128 v[186:189], v191 offset:34816
	ds_read_b128 v[206:209], v191 offset:35840
	ds_read_b128 v[210:213], v191 offset:36864
	ds_read_b128 v[214:217], v191 offset:37888
	ds_read_b128 v[218:221], v191 offset:38912
	ds_read_b128 v[222:225], v191 offset:39936
	global_load_lds_dwordx4 v[238:239], off
	v_lshl_add_u64 v[238:239], s[16:17], 0, v[162:163]
	s_mov_b32 m0, s22
	s_nop 0
	global_load_lds_dwordx4 v[238:239], off
	s_waitcnt vmcnt(8) lgkmcnt(0)
	s_barrier
	v_mfma_f32_16x16x32_bf16 v[136:139], v[120:123], v[178:181], v[136:139]
	v_mfma_f32_16x16x32_bf16 v[124:127], v[132:135], v[178:181], v[124:127]
	v_mfma_f32_16x16x32_bf16 v[108:111], v[120:123], v[186:189], v[108:111]
	v_mfma_f32_16x16x32_bf16 v[104:107], v[132:135], v[186:189], v[104:107]
	v_mfma_f32_16x16x32_bf16 v[92:95], v[120:123], v[210:213], v[92:95]
	v_mfma_f32_16x16x32_bf16 v[88:91], v[132:135], v[210:213], v[88:91]
	v_mfma_f32_16x16x32_bf16 v[76:79], v[120:123], v[218:221], v[76:79]
	v_mfma_f32_16x16x32_bf16 v[72:75], v[132:135], v[218:221], v[72:75]
	v_mfma_f32_16x16x32_bf16 v[136:139], v[128:131], v[182:185], v[136:139]
	v_mfma_f32_16x16x32_bf16 v[124:127], v[140:143], v[182:185], v[124:127]
	v_mfma_f32_16x16x32_bf16 v[108:111], v[128:131], v[206:209], v[108:111]
	v_mfma_f32_16x16x32_bf16 v[104:107], v[140:143], v[206:209], v[104:107]
	v_mfma_f32_16x16x32_bf16 v[92:95], v[128:131], v[214:217], v[92:95]
	v_mfma_f32_16x16x32_bf16 v[88:91], v[140:143], v[214:217], v[88:91]
	v_mfma_f32_16x16x32_bf16 v[76:79], v[128:131], v[222:225], v[76:79]
	v_mfma_f32_16x16x32_bf16 v[72:75], v[140:143], v[222:225], v[72:75]
	v_mfma_f32_16x16x32_bf16 v[116:119], v[144:147], v[178:181], v[116:119]
	v_mfma_f32_16x16x32_bf16 v[112:115], v[152:155], v[178:181], v[112:115]
	v_mfma_f32_16x16x32_bf16 v[100:103], v[144:147], v[186:189], v[100:103]
	v_mfma_f32_16x16x32_bf16 v[96:99], v[152:155], v[186:189], v[96:99]
	v_mfma_f32_16x16x32_bf16 v[84:87], v[144:147], v[210:213], v[84:87]
	v_mfma_f32_16x16x32_bf16 v[80:83], v[152:155], v[210:213], v[80:83]
	v_mfma_f32_16x16x32_bf16 v[68:71], v[144:147], v[218:221], v[68:71]
	v_mfma_f32_16x16x32_bf16 v[64:67], v[152:155], v[218:221], v[64:67]
	v_mfma_f32_16x16x32_bf16 v[116:119], v[148:151], v[182:185], v[116:119]
	v_mfma_f32_16x16x32_bf16 v[112:115], v[156:159], v[182:185], v[112:115]
	v_mfma_f32_16x16x32_bf16 v[100:103], v[148:151], v[206:209], v[100:103]
	v_mfma_f32_16x16x32_bf16 v[96:99], v[156:159], v[206:209], v[96:99]
	v_mfma_f32_16x16x32_bf16 v[84:87], v[148:151], v[214:217], v[84:87]
	v_mfma_f32_16x16x32_bf16 v[80:83], v[156:159], v[214:217], v[80:83]
	v_mfma_f32_16x16x32_bf16 v[68:71], v[148:151], v[222:225], v[68:71]
	v_mfma_f32_16x16x32_bf16 v[64:67], v[156:159], v[222:225], v[64:67]
	s_barrier
; #define PG8_STAGE(bufoff, gbase, voff) do { _Pragma("unroll") for (int _i = 0; _i < 2; ++_i) \
;         __builtin_amdgcn_global_load_lds((const unsigned*)((const char*)(gbase) + (voff)[_i]), (LAS unsigned*)(lds + (bufoff) + ldsw + _i * 8192), 16, 0, 0); } while (0)
; #define PG8_LDA(dst, b, h) do { _Pragma("unroll") for (int m = 0; m < 4; ++m) _Pragma("unroll") for (int k = 0; k < 2; ++k) dst[m][k] = *(const LAS bf16x8*)(lds + PG8_SA(b, h) + aoff + m * 2048 + k * 1024); } while (0)
; #define PG8_MMA(ai, bj, At, Bt) do { __builtin_amdgcn_s_setprio(1); _Pragma("unroll") for (int m = 0; m < 4; ++m) _Pragma("unroll") for (int n = 0; n < 2; ++n) _Pragma("unroll") for (int k = 0; k < 2; ++k) \
;         acc[ai][bj][m][n] = __builtin_amdgcn_mfma_f32_16x16x32_bf16(Bt[n][k], At[m][k], acc[ai][bj][m][n], 0, 0, 0); __builtin_amdgcn_s_setprio(0); } while (0)
; #define PG8_WAIT_V(n) asm volatile("s_waitcnt vmcnt(" #n ")" ::: "memory")
; #define PG8_WAIT_L(n) asm volatile("s_waitcnt lgkmcnt(" #n ")" ::: "memory")
; #define PG8_BAR __builtin_amdgcn_s_barrier()
; #define PG8_SCHED __builtin_amdgcn_sched_barrier(0)
; template <class Epi, bool PERMA = false, bool DUAL = false, bool ALIGN_EPI = true, bool SP2 = true>
; __device__ __forceinline__ void gemm_phase(LAS unsigned char* lds, const Gemm g, const StaticOrder& S, const Epi& E) {
;     ...
;             PG8_LDA(At, 1, 1); PG8_STAGE(PG8_SB(1, 0), b3, voffB); PG8_STAGE(PG8_SB(1, 1), b3 + hstepB, voffB); PG8_STAGE(PG8_SA(1, 0), a3, voffA);
;             PG8_WAIT_V(8); PG8_WAIT_L(0); PG8_BAR; PG8_MMA(1, 0, At, B0); PG8_MMA(1, 1, At, B1); PG8_BAR; PG8_SCHED;
;     ...
;         if constexpr (ALIGN_EPI) { if (wr == 0) PG8_BAR; }
	s_add_i32 s16, s36, s18
	v_lshl_add_u64 v[194:195], v[194:195], 0, s[46:47]
	s_mov_b32 m0, s16
	ds_read_b128 v[178:181], v191 offset:49152
	ds_read_b128 v[182:185], v191 offset:50176
	ds_read_b128 v[186:189], v191 offset:51200
	ds_read_b128 v[206:209], v191 offset:52224
	ds_read_b128 v[210:213], v191 offset:53248
	ds_read_b128 v[214:217], v191 offset:54272
	ds_read_b128 v[218:221], v191 offset:55296
	ds_read_b128 v[222:225], v191 offset:56320
	global_load_lds_dwordx4 v[194:195], off
	s_add_i32 m0, s16, 0x2000
	s_add_u32 s14, s14, 0x80080
	v_lshl_add_u64 v[194:195], v[196:197], 0, s[46:47]
	s_addc_u32 s15, s15, 0
	s_add_i32 s16, s37, s18
	global_load_lds_dwordx4 v[194:195], off
	v_lshl_add_u64 v[194:195], s[14:15], 0, v[164:165]
	s_mov_b32 m0, s16
	s_nop 0
	global_load_lds_dwordx4 v[194:195], off
	v_lshl_add_u64 v[194:195], s[14:15], 0, v[160:161]
	s_add_i32 m0, s16, 0x2000
	s_nop 0
	global_load_lds_dwordx4 v[194:195], off
	v_lshl_add_u64 v[194:195], v[226:227], 0, s[46:47]
	s_mov_b32 m0, s25
	s_nop 0
	global_load_lds_dwordx4 v[194:195], off
	v_lshl_add_u64 v[194:195], v[228:229], 0, s[46:47]
	s_mov_b32 m0, s26
	s_nop 0
	global_load_lds_dwordx4 v[194:195], off
	s_waitcnt vmcnt(8) lgkmcnt(0)
	s_barrier
	v_mfma_f32_16x16x32_bf16 v[60:63], v[120:123], v[178:181], v[60:63]
	v_mfma_f32_16x16x32_bf16 v[56:59], v[132:135], v[178:181], v[56:59]
	v_mfma_f32_16x16x32_bf16 v[44:47], v[120:123], v[186:189], v[44:47]
	v_mfma_f32_16x16x32_bf16 v[40:43], v[132:135], v[186:189], v[40:43]
	v_mfma_f32_16x16x32_bf16 v[28:31], v[120:123], v[210:213], v[28:31]
	v_mfma_f32_16x16x32_bf16 v[24:27], v[132:135], v[210:213], v[24:27]
	v_mfma_f32_16x16x32_bf16 v[12:15], v[120:123], v[218:221], v[12:15]
	v_mfma_f32_16x16x32_bf16 v[8:11], v[132:135], v[218:221], v[8:11]
	v_mfma_f32_16x16x32_bf16 v[60:63], v[128:131], v[182:185], v[60:63]
	v_mfma_f32_16x16x32_bf16 v[56:59], v[140:143], v[182:185], v[56:59]
	v_mfma_f32_16x16x32_bf16 v[44:47], v[128:131], v[206:209], v[44:47]
	v_mfma_f32_16x16x32_bf16 v[40:43], v[140:143], v[206:209], v[40:43]
	v_mfma_f32_16x16x32_bf16 v[28:31], v[128:131], v[214:217], v[28:31]
	v_mfma_f32_16x16x32_bf16 v[24:27], v[140:143], v[214:217], v[24:27]
	v_mfma_f32_16x16x32_bf16 v[12:15], v[128:131], v[222:225], v[12:15]
	v_mfma_f32_16x16x32_bf16 v[8:11], v[140:143], v[222:225], v[8:11]
	v_mfma_f32_16x16x32_bf16 v[52:55], v[144:147], v[178:181], v[52:55]
	v_mfma_f32_16x16x32_bf16 v[48:51], v[152:155], v[178:181], v[48:51]
	v_mfma_f32_16x16x32_bf16 v[36:39], v[144:147], v[186:189], v[36:39]
	v_mfma_f32_16x16x32_bf16 v[32:35], v[152:155], v[186:189], v[32:35]
	v_mfma_f32_16x16x32_bf16 v[20:23], v[144:147], v[210:213], v[20:23]
	v_mfma_f32_16x16x32_bf16 v[16:19], v[152:155], v[210:213], v[16:19]
	v_mfma_f32_16x16x32_bf16 v[0:3], v[144:147], v[218:221], v[0:3]
	v_mfma_f32_16x16x32_bf16 v[4:7], v[152:155], v[218:221], v[4:7]
	v_mfma_f32_16x16x32_bf16 v[52:55], v[148:151], v[182:185], v[52:55]
	v_mfma_f32_16x16x32_bf16 v[48:51], v[156:159], v[182:185], v[48:51]
	v_mfma_f32_16x16x32_bf16 v[36:39], v[148:151], v[206:209], v[36:39]
	v_mfma_f32_16x16x32_bf16 v[32:35], v[156:159], v[206:209], v[32:35]
	v_mfma_f32_16x16x32_bf16 v[20:23], v[148:151], v[214:217], v[20:23]
	v_mfma_f32_16x16x32_bf16 v[16:19], v[156:159], v[214:217], v[16:19]
	v_mfma_f32_16x16x32_bf16 v[0:3], v[148:151], v[222:225], v[0:3]
	v_mfma_f32_16x16x32_bf16 v[4:7], v[156:159], v[222:225], v[4:7]
	s_barrier
	s_add_i32 s35, s35, 2
	s_add_u32 s12, s12, 0x100
	s_addc_u32 s13, s13, 0
	s_add_u32 s33, s33, 0x100
	s_addc_u32 s34, s34, 0
	s_cmp_gt_u32 s35, 29
	s_cbranch_scc0 .LBB0_790
	s_and_b64 vcc, exec, s[2:3]
	s_cbranch_vccz .LBB0_793
	s_barrier
